# GEMM K-loops: adjacent s_setprio 0 / s_setprio 1 pair between the two MFMA blocks of a super-phase removed (64 sites)
# baseline (speedup 1.0000x reference)
.LBB0_236:
	ds_read_b128 v[152:155], v149
	ds_read_b128 v[156:159], v149 offset:1024
	ds_read_b128 v[160:163], v149 offset:2048
	ds_read_b128 v[164:167], v149 offset:3072
	ds_read_b128 v[168:171], v150
	ds_read_b128 v[172:175], v150 offset:1024
	ds_read_b128 v[176:179], v150 offset:2048
	ds_read_b128 v[180:183], v150 offset:3072
	s_add_u32 s26, s24, 0xfffc0080
	s_addc_u32 s27, s25, -1
	s_cmp_eq_u32 s53, 12
	s_cselect_b32 s29, s17, s27
	s_cselect_b32 s28, s49, s26
	s_cselect_b32 s27, s15, s52
	s_cselect_b32 s26, s50, s51
	v_lshl_add_u64 v[144:145], s[24:25], 0, v[138:139]
	s_add_i32 m0, s36, 0xc000
	ds_read_b128 v[184:187], v151
	ds_read_b128 v[188:191], v151 offset:1024
	ds_read_b128 v[192:195], v151 offset:2048
	ds_read_b128 v[196:199], v151 offset:3072
	ds_read_b128 v[200:203], v151 offset:4096
	ds_read_b128 v[204:207], v151 offset:5120
	ds_read_b128 v[208:211], v151 offset:6144
	ds_read_b128 v[212:215], v151 offset:7168
	global_load_lds_dwordx4 v[144:145], off
	v_lshl_add_u64 v[144:145], s[24:25], 0, v[136:137]
	s_add_i32 m0, s36, 0xe000
	s_nop 0
	global_load_lds_dwordx4 v[144:145], off
	s_waitcnt vmcnt(8)
	s_waitcnt lgkmcnt(0)
	s_barrier
	s_setprio 1
	s_waitcnt lgkmcnt(0)
	v_mfma_f32_16x16x32_bf16 v[124:127], v[152:155], v[184:187], v[124:127]
	v_mfma_f32_16x16x32_bf16 v[120:123], v[160:163], v[184:187], v[120:123]
	v_mfma_f32_16x16x32_bf16 v[116:119], v[152:155], v[192:195], v[116:119]
	v_mfma_f32_16x16x32_bf16 v[112:115], v[160:163], v[192:195], v[112:115]
	v_mfma_f32_16x16x32_bf16 v[108:111], v[152:155], v[200:203], v[108:111]
	v_mfma_f32_16x16x32_bf16 v[104:107], v[160:163], v[200:203], v[104:107]
	v_mfma_f32_16x16x32_bf16 v[100:103], v[152:155], v[208:211], v[100:103]
	v_mfma_f32_16x16x32_bf16 v[96:99], v[160:163], v[208:211], v[96:99]
	v_mfma_f32_16x16x32_bf16 v[124:127], v[156:159], v[188:191], v[124:127]
	v_mfma_f32_16x16x32_bf16 v[120:123], v[164:167], v[188:191], v[120:123]
	v_mfma_f32_16x16x32_bf16 v[116:119], v[156:159], v[196:199], v[116:119]
	v_mfma_f32_16x16x32_bf16 v[112:115], v[164:167], v[196:199], v[112:115]
	v_mfma_f32_16x16x32_bf16 v[108:111], v[156:159], v[204:207], v[108:111]
	v_mfma_f32_16x16x32_bf16 v[104:107], v[164:167], v[204:207], v[104:107]
	v_mfma_f32_16x16x32_bf16 v[100:103], v[156:159], v[212:215], v[100:103]
	v_mfma_f32_16x16x32_bf16 v[96:99], v[164:167], v[212:215], v[96:99]
	v_mfma_f32_16x16x32_bf16 v[80:83], v[168:171], v[184:187], v[80:83]
	v_mfma_f32_16x16x32_bf16 v[72:75], v[176:179], v[184:187], v[72:75]
	v_mfma_f32_16x16x32_bf16 v[60:63], v[168:171], v[192:195], v[60:63]
	v_mfma_f32_16x16x32_bf16 v[56:59], v[176:179], v[192:195], v[56:59]
	v_mfma_f32_16x16x32_bf16 v[44:47], v[168:171], v[200:203], v[44:47]
	v_mfma_f32_16x16x32_bf16 v[40:43], v[176:179], v[200:203], v[40:43]
	v_mfma_f32_16x16x32_bf16 v[36:39], v[168:171], v[208:211], v[36:39]
	v_mfma_f32_16x16x32_bf16 v[32:35], v[176:179], v[208:211], v[32:35]
	v_mfma_f32_16x16x32_bf16 v[80:83], v[172:175], v[188:191], v[80:83]
	v_mfma_f32_16x16x32_bf16 v[72:75], v[180:183], v[188:191], v[72:75]
	v_mfma_f32_16x16x32_bf16 v[60:63], v[172:175], v[196:199], v[60:63]
	v_mfma_f32_16x16x32_bf16 v[56:59], v[180:183], v[196:199], v[56:59]
	v_mfma_f32_16x16x32_bf16 v[44:47], v[172:175], v[204:207], v[44:47]
	v_mfma_f32_16x16x32_bf16 v[40:43], v[180:183], v[204:207], v[40:43]
	v_mfma_f32_16x16x32_bf16 v[36:39], v[172:175], v[212:215], v[36:39]
	v_mfma_f32_16x16x32_bf16 v[32:35], v[180:183], v[212:215], v[32:35]
	s_setprio 0
	s_barrier
	s_add_i32 s54, s45, s31
	v_lshl_add_u64 v[144:145], s[26:27], 0, v[132:133]
	s_mov_b32 m0, s54
	ds_read_b128 v[184:187], v151 offset:16384
	ds_read_b128 v[188:191], v151 offset:17408
	ds_read_b128 v[192:195], v151 offset:18432
	ds_read_b128 v[196:199], v151 offset:19456
	ds_read_b128 v[200:203], v151 offset:20480
	ds_read_b128 v[204:207], v151 offset:21504
	ds_read_b128 v[208:211], v151 offset:22528
	ds_read_b128 v[212:215], v151 offset:23552
	global_load_lds_dwordx4 v[144:145], off
	s_add_i32 m0, s54, 0x2000
	s_add_u32 s54, s26, 0x40000
	v_lshl_add_u64 v[216:217], s[26:27], 0, v[128:129]
	s_addc_u32 s55, s27, 0
	s_add_i32 s56, s46, s31
	global_load_lds_dwordx4 v[216:217], off
	v_lshl_add_u64 v[218:219], s[54:55], 0, v[132:133]
	s_mov_b32 m0, s56
	v_lshl_add_u64 v[220:221], s[28:29], 0, v[130:131]
	global_load_lds_dwordx4 v[218:219], off
	v_lshl_add_u64 v[218:219], s[54:55], 0, v[128:129]
	s_add_i32 m0, s56, 0x2000
	s_nop 0
	global_load_lds_dwordx4 v[218:219], off
	v_lshl_add_u64 v[218:219], s[28:29], 0, v[134:135]
	s_mov_b32 m0, s36
	s_nop 0
	global_load_lds_dwordx4 v[218:219], off
	s_mov_b32 m0, s37
	s_nop 0
	global_load_lds_dwordx4 v[220:221], off
	s_waitcnt vmcnt(8)
	s_waitcnt lgkmcnt(0)
	s_barrier
	s_setprio 1
	s_waitcnt lgkmcnt(0)
	v_mfma_f32_16x16x32_bf16 v[92:95], v[152:155], v[184:187], v[92:95]
	v_mfma_f32_16x16x32_bf16 v[88:91], v[160:163], v[184:187], v[88:91]
	v_mfma_f32_16x16x32_bf16 v[84:87], v[152:155], v[192:195], v[84:87]
	v_mfma_f32_16x16x32_bf16 v[76:79], v[160:163], v[192:195], v[76:79]
	v_mfma_f32_16x16x32_bf16 v[68:71], v[152:155], v[200:203], v[68:71]
	v_mfma_f32_16x16x32_bf16 v[64:67], v[160:163], v[200:203], v[64:67]
	v_mfma_f32_16x16x32_bf16 v[52:55], v[152:155], v[208:211], v[52:55]
	v_mfma_f32_16x16x32_bf16 v[48:51], v[160:163], v[208:211], v[48:51]
	v_mfma_f32_16x16x32_bf16 v[92:95], v[156:159], v[188:191], v[92:95]
	v_mfma_f32_16x16x32_bf16 v[88:91], v[164:167], v[188:191], v[88:91]
	v_mfma_f32_16x16x32_bf16 v[84:87], v[156:159], v[196:199], v[84:87]
	v_mfma_f32_16x16x32_bf16 v[76:79], v[164:167], v[196:199], v[76:79]
	v_mfma_f32_16x16x32_bf16 v[68:71], v[156:159], v[204:207], v[68:71]
	v_mfma_f32_16x16x32_bf16 v[64:67], v[164:167], v[204:207], v[64:67]
	v_mfma_f32_16x16x32_bf16 v[52:55], v[156:159], v[212:215], v[52:55]
	v_mfma_f32_16x16x32_bf16 v[48:51], v[164:167], v[212:215], v[48:51]
	v_mfma_f32_16x16x32_bf16 v[28:31], v[168:171], v[184:187], v[28:31]
	v_mfma_f32_16x16x32_bf16 v[24:27], v[176:179], v[184:187], v[24:27]
	v_mfma_f32_16x16x32_bf16 v[20:23], v[168:171], v[192:195], v[20:23]
	v_mfma_f32_16x16x32_bf16 v[16:19], v[176:179], v[192:195], v[16:19]
	v_mfma_f32_16x16x32_bf16 v[12:15], v[168:171], v[200:203], v[12:15]
	v_mfma_f32_16x16x32_bf16 v[8:11], v[176:179], v[200:203], v[8:11]
	v_mfma_f32_16x16x32_bf16 v[4:7], v[168:171], v[208:211], v[4:7]
	v_mfma_f32_16x16x32_bf16 v[0:3], v[176:179], v[208:211], v[0:3]
	v_mfma_f32_16x16x32_bf16 v[28:31], v[172:175], v[188:191], v[28:31]
	v_mfma_f32_16x16x32_bf16 v[24:27], v[180:183], v[188:191], v[24:27]
	v_mfma_f32_16x16x32_bf16 v[20:23], v[172:175], v[196:199], v[20:23]
	v_mfma_f32_16x16x32_bf16 v[16:19], v[180:183], v[196:199], v[16:19]
	v_mfma_f32_16x16x32_bf16 v[12:15], v[172:175], v[204:207], v[12:15]
	v_mfma_f32_16x16x32_bf16 v[8:11], v[180:183], v[204:207], v[8:11]
	v_mfma_f32_16x16x32_bf16 v[4:7], v[172:175], v[212:215], v[4:7]
	v_mfma_f32_16x16x32_bf16 v[0:3], v[180:183], v[212:215], v[0:3]
	s_setprio 0
	s_barrier
	s_add_i32 s54, 0, 0x18000
	s_add_i32 s55, 0, 0x1c000
	v_add_u32_e32 v164, s54, v147
	v_add_u32_e32 v180, s55, v147
	ds_read_b128 v[152:155], v164
	ds_read_b128 v[156:159], v164 offset:1024
	ds_read_b128 v[160:163], v164 offset:2048
	ds_read_b128 v[164:167], v164 offset:3072
	ds_read_b128 v[168:171], v180
	ds_read_b128 v[172:175], v180 offset:1024
	ds_read_b128 v[176:179], v180 offset:2048
	ds_read_b128 v[180:183], v180 offset:3072
	s_add_u32 s28, s28, 0x40000
	s_addc_u32 s29, s29, 0
	s_mov_b32 m0, s38
	v_lshl_add_u64 v[222:223], s[28:29], 0, v[134:135]
	ds_read_b128 v[184:187], v151 offset:32768
	ds_read_b128 v[188:191], v151 offset:33792
	ds_read_b128 v[192:195], v151 offset:34816
	ds_read_b128 v[196:199], v151 offset:35840
	ds_read_b128 v[200:203], v151 offset:36864
	ds_read_b128 v[204:207], v151 offset:37888
	ds_read_b128 v[208:211], v151 offset:38912
	ds_read_b128 v[212:215], v151 offset:39936
	global_load_lds_dwordx4 v[222:223], off
	v_lshl_add_u64 v[222:223], s[28:29], 0, v[130:131]
	s_mov_b32 m0, s39
	s_nop 0
	global_load_lds_dwordx4 v[222:223], off
	s_waitcnt vmcnt(8)
	s_waitcnt lgkmcnt(0)
	s_barrier
	s_setprio 1
	s_waitcnt lgkmcnt(0)
	v_mfma_f32_16x16x32_bf16 v[124:127], v[152:155], v[184:187], v[124:127]
	v_mfma_f32_16x16x32_bf16 v[120:123], v[160:163], v[184:187], v[120:123]
	v_mfma_f32_16x16x32_bf16 v[116:119], v[152:155], v[192:195], v[116:119]
	v_mfma_f32_16x16x32_bf16 v[112:115], v[160:163], v[192:195], v[112:115]
	v_mfma_f32_16x16x32_bf16 v[108:111], v[152:155], v[200:203], v[108:111]
	v_mfma_f32_16x16x32_bf16 v[104:107], v[160:163], v[200:203], v[104:107]
	v_mfma_f32_16x16x32_bf16 v[100:103], v[152:155], v[208:211], v[100:103]
	v_mfma_f32_16x16x32_bf16 v[96:99], v[160:163], v[208:211], v[96:99]
	v_mfma_f32_16x16x32_bf16 v[124:127], v[156:159], v[188:191], v[124:127]
	v_mfma_f32_16x16x32_bf16 v[120:123], v[164:167], v[188:191], v[120:123]
	v_mfma_f32_16x16x32_bf16 v[116:119], v[156:159], v[196:199], v[116:119]
	v_mfma_f32_16x16x32_bf16 v[112:115], v[164:167], v[196:199], v[112:115]
	v_mfma_f32_16x16x32_bf16 v[108:111], v[156:159], v[204:207], v[108:111]
	v_mfma_f32_16x16x32_bf16 v[104:107], v[164:167], v[204:207], v[104:107]
	v_mfma_f32_16x16x32_bf16 v[100:103], v[156:159], v[212:215], v[100:103]
	v_mfma_f32_16x16x32_bf16 v[96:99], v[164:167], v[212:215], v[96:99]
	v_mfma_f32_16x16x32_bf16 v[80:83], v[168:171], v[184:187], v[80:83]
	v_mfma_f32_16x16x32_bf16 v[72:75], v[176:179], v[184:187], v[72:75]
	v_mfma_f32_16x16x32_bf16 v[60:63], v[168:171], v[192:195], v[60:63]
	v_mfma_f32_16x16x32_bf16 v[56:59], v[176:179], v[192:195], v[56:59]
	v_mfma_f32_16x16x32_bf16 v[44:47], v[168:171], v[200:203], v[44:47]
	v_mfma_f32_16x16x32_bf16 v[40:43], v[176:179], v[200:203], v[40:43]
	v_mfma_f32_16x16x32_bf16 v[36:39], v[168:171], v[208:211], v[36:39]
	v_mfma_f32_16x16x32_bf16 v[32:35], v[176:179], v[208:211], v[32:35]
	v_mfma_f32_16x16x32_bf16 v[80:83], v[172:175], v[188:191], v[80:83]
	v_mfma_f32_16x16x32_bf16 v[72:75], v[180:183], v[188:191], v[72:75]
	v_mfma_f32_16x16x32_bf16 v[60:63], v[172:175], v[196:199], v[60:63]
	v_mfma_f32_16x16x32_bf16 v[56:59], v[180:183], v[196:199], v[56:59]
	v_mfma_f32_16x16x32_bf16 v[44:47], v[172:175], v[204:207], v[44:47]
	v_mfma_f32_16x16x32_bf16 v[40:43], v[180:183], v[204:207], v[40:43]
	v_mfma_f32_16x16x32_bf16 v[36:39], v[172:175], v[212:215], v[36:39]
	v_mfma_f32_16x16x32_bf16 v[32:35], v[180:183], v[212:215], v[32:35]
	s_setprio 0
	s_barrier
	s_add_i32 s28, s54, s31
	v_lshl_add_u64 v[144:145], v[144:145], 0, s[10:11]
	s_mov_b32 m0, s28
	ds_read_b128 v[184:187], v151 offset:49152
	ds_read_b128 v[188:191], v151 offset:50176
	ds_read_b128 v[192:195], v151 offset:51200
	ds_read_b128 v[196:199], v151 offset:52224
	ds_read_b128 v[200:203], v151 offset:53248
	ds_read_b128 v[204:207], v151 offset:54272
	ds_read_b128 v[208:211], v151 offset:55296
	ds_read_b128 v[212:215], v151 offset:56320
	global_load_lds_dwordx4 v[144:145], off
	s_add_i32 m0, s28, 0x2000
	s_add_u32 s26, s26, 0x40080
	v_lshl_add_u64 v[144:145], v[216:217], 0, s[10:11]
	s_addc_u32 s27, s27, 0
	s_add_i32 s28, s55, s31
	global_load_lds_dwordx4 v[144:145], off
	v_lshl_add_u64 v[144:145], s[26:27], 0, v[132:133]
	s_mov_b32 m0, s28
	s_nop 0
	global_load_lds_dwordx4 v[144:145], off
	v_lshl_add_u64 v[144:145], s[26:27], 0, v[128:129]
	s_add_i32 m0, s28, 0x2000
	s_nop 0
	global_load_lds_dwordx4 v[144:145], off
	v_lshl_add_u64 v[144:145], v[218:219], 0, s[10:11]
	s_mov_b32 m0, s41
	s_nop 0
	global_load_lds_dwordx4 v[144:145], off
	v_lshl_add_u64 v[144:145], v[220:221], 0, s[10:11]
	s_mov_b32 m0, s42
	s_nop 0
	global_load_lds_dwordx4 v[144:145], off
	s_waitcnt vmcnt(8)
	s_waitcnt lgkmcnt(0)
	s_barrier
	s_setprio 1
	s_waitcnt lgkmcnt(0)
	v_mfma_f32_16x16x32_bf16 v[92:95], v[152:155], v[184:187], v[92:95]
	v_mfma_f32_16x16x32_bf16 v[88:91], v[160:163], v[184:187], v[88:91]
	v_mfma_f32_16x16x32_bf16 v[84:87], v[152:155], v[192:195], v[84:87]
	v_mfma_f32_16x16x32_bf16 v[76:79], v[160:163], v[192:195], v[76:79]
	v_mfma_f32_16x16x32_bf16 v[68:71], v[152:155], v[200:203], v[68:71]
	v_mfma_f32_16x16x32_bf16 v[64:67], v[160:163], v[200:203], v[64:67]
	v_mfma_f32_16x16x32_bf16 v[52:55], v[152:155], v[208:211], v[52:55]
	v_mfma_f32_16x16x32_bf16 v[48:51], v[160:163], v[208:211], v[48:51]
	v_mfma_f32_16x16x32_bf16 v[92:95], v[156:159], v[188:191], v[92:95]
	v_mfma_f32_16x16x32_bf16 v[88:91], v[164:167], v[188:191], v[88:91]
	v_mfma_f32_16x16x32_bf16 v[84:87], v[156:159], v[196:199], v[84:87]
	v_mfma_f32_16x16x32_bf16 v[76:79], v[164:167], v[196:199], v[76:79]
	v_mfma_f32_16x16x32_bf16 v[68:71], v[156:159], v[204:207], v[68:71]
	v_mfma_f32_16x16x32_bf16 v[64:67], v[164:167], v[204:207], v[64:67]
	v_mfma_f32_16x16x32_bf16 v[52:55], v[156:159], v[212:215], v[52:55]
	v_mfma_f32_16x16x32_bf16 v[48:51], v[164:167], v[212:215], v[48:51]
	v_mfma_f32_16x16x32_bf16 v[28:31], v[168:171], v[184:187], v[28:31]
	v_mfma_f32_16x16x32_bf16 v[24:27], v[176:179], v[184:187], v[24:27]
	v_mfma_f32_16x16x32_bf16 v[20:23], v[168:171], v[192:195], v[20:23]
	v_mfma_f32_16x16x32_bf16 v[16:19], v[176:179], v[192:195], v[16:19]
	v_mfma_f32_16x16x32_bf16 v[12:15], v[168:171], v[200:203], v[12:15]
	v_mfma_f32_16x16x32_bf16 v[8:11], v[176:179], v[200:203], v[8:11]
	v_mfma_f32_16x16x32_bf16 v[4:7], v[168:171], v[208:211], v[4:7]
	v_mfma_f32_16x16x32_bf16 v[0:3], v[176:179], v[208:211], v[0:3]
	v_mfma_f32_16x16x32_bf16 v[28:31], v[172:175], v[188:191], v[28:31]
	v_mfma_f32_16x16x32_bf16 v[24:27], v[180:183], v[188:191], v[24:27]
	v_mfma_f32_16x16x32_bf16 v[20:23], v[172:175], v[196:199], v[20:23]
	v_mfma_f32_16x16x32_bf16 v[16:19], v[180:183], v[196:199], v[16:19]
	v_mfma_f32_16x16x32_bf16 v[12:15], v[172:175], v[204:207], v[12:15]
	v_mfma_f32_16x16x32_bf16 v[8:11], v[180:183], v[204:207], v[8:11]
	v_mfma_f32_16x16x32_bf16 v[4:7], v[172:175], v[212:215], v[4:7]
	v_mfma_f32_16x16x32_bf16 v[0:3], v[180:183], v[212:215], v[0:3]
	s_setprio 0
	s_barrier
	s_add_i32 s53, s53, 2
	s_add_u32 s51, s51, 0x100
	s_addc_u32 s52, s52, 0
	s_add_u32 s24, s24, 0x100
	s_addc_u32 s25, s25, 0
	s_cmp_gt_u32 s53, 13
	s_cbranch_scc0 .LBB0_236
	s_and_b64 vcc, exec, s[12:13]
	s_cbranch_vccz .LBB0_239
	s_barrier

.LBB0_1116:
	ds_read_b128 v[144:147], v157
	ds_read_b128 v[148:151], v157 offset:1024
	ds_read_b128 v[160:163], v157 offset:2048
	ds_read_b128 v[164:167], v157 offset:3072
	ds_read_b128 v[168:171], v158
	ds_read_b128 v[172:175], v158 offset:1024
	ds_read_b128 v[176:179], v158 offset:2048
	ds_read_b128 v[180:183], v158 offset:3072
	s_add_u32 s28, s24, 0xfffc0080
	s_addc_u32 s29, s25, -1
	s_cmp_eq_u32 s54, 12
	s_cselect_b32 s31, s17, s29
	s_cselect_b32 s30, s50, s28
	s_cselect_b32 s29, s15, s53
	s_cselect_b32 s28, s51, s52
	v_lshl_add_u64 v[152:153], s[24:25], 0, v[138:139]
	s_add_i32 m0, s35, 0xc000
	ds_read_b128 v[184:187], v159
	ds_read_b128 v[188:191], v159 offset:1024
	ds_read_b128 v[192:195], v159 offset:2048
	ds_read_b128 v[196:199], v159 offset:3072
	ds_read_b128 v[200:203], v159 offset:4096
	ds_read_b128 v[204:207], v159 offset:5120
	ds_read_b128 v[208:211], v159 offset:6144
	ds_read_b128 v[212:215], v159 offset:7168
	global_load_lds_dwordx4 v[152:153], off
	v_lshl_add_u64 v[152:153], s[24:25], 0, v[136:137]
	s_add_i32 m0, s35, 0xe000
	s_nop 0
	global_load_lds_dwordx4 v[152:153], off
	s_waitcnt vmcnt(8)
	s_waitcnt lgkmcnt(0)
	s_barrier
	s_setprio 1
	s_waitcnt lgkmcnt(0)
	v_mfma_f32_16x16x32_bf16 v[124:127], v[144:147], v[184:187], v[124:127]
	v_mfma_f32_16x16x32_bf16 v[120:123], v[160:163], v[184:187], v[120:123]
	v_mfma_f32_16x16x32_bf16 v[116:119], v[144:147], v[192:195], v[116:119]
	v_mfma_f32_16x16x32_bf16 v[112:115], v[160:163], v[192:195], v[112:115]
	v_mfma_f32_16x16x32_bf16 v[108:111], v[144:147], v[200:203], v[108:111]
	v_mfma_f32_16x16x32_bf16 v[104:107], v[160:163], v[200:203], v[104:107]
	v_mfma_f32_16x16x32_bf16 v[100:103], v[144:147], v[208:211], v[100:103]
	v_mfma_f32_16x16x32_bf16 v[96:99], v[160:163], v[208:211], v[96:99]
	v_mfma_f32_16x16x32_bf16 v[124:127], v[148:151], v[188:191], v[124:127]
	v_mfma_f32_16x16x32_bf16 v[120:123], v[164:167], v[188:191], v[120:123]
	v_mfma_f32_16x16x32_bf16 v[116:119], v[148:151], v[196:199], v[116:119]
	v_mfma_f32_16x16x32_bf16 v[112:115], v[164:167], v[196:199], v[112:115]
	v_mfma_f32_16x16x32_bf16 v[108:111], v[148:151], v[204:207], v[108:111]
	v_mfma_f32_16x16x32_bf16 v[104:107], v[164:167], v[204:207], v[104:107]
	v_mfma_f32_16x16x32_bf16 v[100:103], v[148:151], v[212:215], v[100:103]
	v_mfma_f32_16x16x32_bf16 v[96:99], v[164:167], v[212:215], v[96:99]
	v_mfma_f32_16x16x32_bf16 v[76:79], v[168:171], v[184:187], v[76:79]
	v_mfma_f32_16x16x32_bf16 v[72:75], v[176:179], v[184:187], v[72:75]
	v_mfma_f32_16x16x32_bf16 v[60:63], v[168:171], v[192:195], v[60:63]
	v_mfma_f32_16x16x32_bf16 v[52:55], v[176:179], v[192:195], v[52:55]
	v_mfma_f32_16x16x32_bf16 v[44:47], v[168:171], v[200:203], v[44:47]
	v_mfma_f32_16x16x32_bf16 v[40:43], v[176:179], v[200:203], v[40:43]
	v_mfma_f32_16x16x32_bf16 v[36:39], v[168:171], v[208:211], v[36:39]
	v_mfma_f32_16x16x32_bf16 v[32:35], v[176:179], v[208:211], v[32:35]
	v_mfma_f32_16x16x32_bf16 v[76:79], v[172:175], v[188:191], v[76:79]
	v_mfma_f32_16x16x32_bf16 v[72:75], v[180:183], v[188:191], v[72:75]
	v_mfma_f32_16x16x32_bf16 v[60:63], v[172:175], v[196:199], v[60:63]
	v_mfma_f32_16x16x32_bf16 v[52:55], v[180:183], v[196:199], v[52:55]
	v_mfma_f32_16x16x32_bf16 v[44:47], v[172:175], v[204:207], v[44:47]
	v_mfma_f32_16x16x32_bf16 v[40:43], v[180:183], v[204:207], v[40:43]
	v_mfma_f32_16x16x32_bf16 v[36:39], v[172:175], v[212:215], v[36:39]
	v_mfma_f32_16x16x32_bf16 v[32:35], v[180:183], v[212:215], v[32:35]
	s_setprio 0
	s_barrier
	s_add_i32 s55, s45, s33
	v_lshl_add_u64 v[152:153], s[28:29], 0, v[130:131]
	s_mov_b32 m0, s55
	ds_read_b128 v[184:187], v159 offset:16384
	ds_read_b128 v[188:191], v159 offset:17408
	ds_read_b128 v[192:195], v159 offset:18432
	ds_read_b128 v[196:199], v159 offset:19456
	ds_read_b128 v[200:203], v159 offset:20480
	ds_read_b128 v[204:207], v159 offset:21504
	ds_read_b128 v[208:211], v159 offset:22528
	ds_read_b128 v[212:215], v159 offset:23552
	global_load_lds_dwordx4 v[152:153], off
	s_add_i32 m0, s55, 0x2000
	s_add_u32 s56, s28, 0x40000
	v_lshl_add_u64 v[216:217], s[28:29], 0, v[134:135]
	s_addc_u32 s57, s29, 0
	s_add_i32 s55, s46, s33
	global_load_lds_dwordx4 v[216:217], off
	v_lshl_add_u64 v[218:219], s[56:57], 0, v[130:131]
	s_mov_b32 m0, s55
	v_lshl_add_u64 v[220:221], s[30:31], 0, v[132:133]
	global_load_lds_dwordx4 v[218:219], off
	v_lshl_add_u64 v[218:219], s[56:57], 0, v[134:135]
	s_add_i32 m0, s55, 0x2000
	s_nop 0
	global_load_lds_dwordx4 v[218:219], off
	v_lshl_add_u64 v[218:219], s[30:31], 0, v[128:129]
	s_mov_b32 m0, s35
	s_nop 0
	global_load_lds_dwordx4 v[218:219], off
	s_mov_b32 m0, s36
	s_nop 0
	global_load_lds_dwordx4 v[220:221], off
	s_waitcnt vmcnt(8)
	s_waitcnt lgkmcnt(0)
	s_barrier
	s_setprio 1
	s_waitcnt lgkmcnt(0)
	v_mfma_f32_16x16x32_bf16 v[92:95], v[144:147], v[184:187], v[92:95]
	v_mfma_f32_16x16x32_bf16 v[88:91], v[160:163], v[184:187], v[88:91]
	v_mfma_f32_16x16x32_bf16 v[84:87], v[144:147], v[192:195], v[84:87]
	v_mfma_f32_16x16x32_bf16 v[80:83], v[160:163], v[192:195], v[80:83]
	v_mfma_f32_16x16x32_bf16 v[68:71], v[144:147], v[200:203], v[68:71]
	v_mfma_f32_16x16x32_bf16 v[64:67], v[160:163], v[200:203], v[64:67]
	v_mfma_f32_16x16x32_bf16 v[56:59], v[144:147], v[208:211], v[56:59]
	v_mfma_f32_16x16x32_bf16 v[48:51], v[160:163], v[208:211], v[48:51]
	v_mfma_f32_16x16x32_bf16 v[92:95], v[148:151], v[188:191], v[92:95]
	v_mfma_f32_16x16x32_bf16 v[88:91], v[164:167], v[188:191], v[88:91]
	v_mfma_f32_16x16x32_bf16 v[84:87], v[148:151], v[196:199], v[84:87]
	v_mfma_f32_16x16x32_bf16 v[80:83], v[164:167], v[196:199], v[80:83]
	v_mfma_f32_16x16x32_bf16 v[68:71], v[148:151], v[204:207], v[68:71]
	v_mfma_f32_16x16x32_bf16 v[64:67], v[164:167], v[204:207], v[64:67]
	v_mfma_f32_16x16x32_bf16 v[56:59], v[148:151], v[212:215], v[56:59]
	v_mfma_f32_16x16x32_bf16 v[48:51], v[164:167], v[212:215], v[48:51]
	v_mfma_f32_16x16x32_bf16 v[28:31], v[168:171], v[184:187], v[28:31]
	v_mfma_f32_16x16x32_bf16 v[24:27], v[176:179], v[184:187], v[24:27]
	v_mfma_f32_16x16x32_bf16 v[20:23], v[168:171], v[192:195], v[20:23]
	v_mfma_f32_16x16x32_bf16 v[16:19], v[176:179], v[192:195], v[16:19]
	v_mfma_f32_16x16x32_bf16 v[12:15], v[168:171], v[200:203], v[12:15]
	v_mfma_f32_16x16x32_bf16 v[8:11], v[176:179], v[200:203], v[8:11]
	v_mfma_f32_16x16x32_bf16 v[4:7], v[168:171], v[208:211], v[4:7]
	v_mfma_f32_16x16x32_bf16 v[0:3], v[176:179], v[208:211], v[0:3]
	v_mfma_f32_16x16x32_bf16 v[28:31], v[172:175], v[188:191], v[28:31]
	v_mfma_f32_16x16x32_bf16 v[24:27], v[180:183], v[188:191], v[24:27]
	v_mfma_f32_16x16x32_bf16 v[20:23], v[172:175], v[196:199], v[20:23]
	v_mfma_f32_16x16x32_bf16 v[16:19], v[180:183], v[196:199], v[16:19]
	v_mfma_f32_16x16x32_bf16 v[12:15], v[172:175], v[204:207], v[12:15]
	v_mfma_f32_16x16x32_bf16 v[8:11], v[180:183], v[204:207], v[8:11]
	v_mfma_f32_16x16x32_bf16 v[4:7], v[172:175], v[212:215], v[4:7]
	v_mfma_f32_16x16x32_bf16 v[0:3], v[180:183], v[212:215], v[0:3]
	s_setprio 0
	s_barrier
	s_add_i32 s55, 0, 0x18000
	s_add_i32 s56, 0, 0x1c000
	v_add_u32_e32 v164, s55, v155
	v_add_u32_e32 v180, s56, v155
	ds_read_b128 v[144:147], v164
	ds_read_b128 v[148:151], v164 offset:1024
	ds_read_b128 v[160:163], v164 offset:2048
	ds_read_b128 v[164:167], v164 offset:3072
	ds_read_b128 v[168:171], v180
	ds_read_b128 v[172:175], v180 offset:1024
	ds_read_b128 v[176:179], v180 offset:2048
	ds_read_b128 v[180:183], v180 offset:3072
	s_add_u32 s30, s30, 0x40000
	s_addc_u32 s31, s31, 0
	s_mov_b32 m0, s37
	v_lshl_add_u64 v[222:223], s[30:31], 0, v[128:129]
	ds_read_b128 v[184:187], v159 offset:32768
	ds_read_b128 v[188:191], v159 offset:33792
	ds_read_b128 v[192:195], v159 offset:34816
	ds_read_b128 v[196:199], v159 offset:35840
	ds_read_b128 v[200:203], v159 offset:36864
	ds_read_b128 v[204:207], v159 offset:37888
	ds_read_b128 v[208:211], v159 offset:38912
	ds_read_b128 v[212:215], v159 offset:39936
	global_load_lds_dwordx4 v[222:223], off
	v_lshl_add_u64 v[222:223], s[30:31], 0, v[132:133]
	s_mov_b32 m0, s38
	s_nop 0
	global_load_lds_dwordx4 v[222:223], off
	s_waitcnt vmcnt(8)
	s_waitcnt lgkmcnt(0)
	s_barrier
	s_setprio 1
	s_waitcnt lgkmcnt(0)
	v_mfma_f32_16x16x32_bf16 v[124:127], v[144:147], v[184:187], v[124:127]
	v_mfma_f32_16x16x32_bf16 v[120:123], v[160:163], v[184:187], v[120:123]
	v_mfma_f32_16x16x32_bf16 v[116:119], v[144:147], v[192:195], v[116:119]
	v_mfma_f32_16x16x32_bf16 v[112:115], v[160:163], v[192:195], v[112:115]
	v_mfma_f32_16x16x32_bf16 v[108:111], v[144:147], v[200:203], v[108:111]
	v_mfma_f32_16x16x32_bf16 v[104:107], v[160:163], v[200:203], v[104:107]
	v_mfma_f32_16x16x32_bf16 v[100:103], v[144:147], v[208:211], v[100:103]
	v_mfma_f32_16x16x32_bf16 v[96:99], v[160:163], v[208:211], v[96:99]
	v_mfma_f32_16x16x32_bf16 v[124:127], v[148:151], v[188:191], v[124:127]
	v_mfma_f32_16x16x32_bf16 v[120:123], v[164:167], v[188:191], v[120:123]
	v_mfma_f32_16x16x32_bf16 v[116:119], v[148:151], v[196:199], v[116:119]
	v_mfma_f32_16x16x32_bf16 v[112:115], v[164:167], v[196:199], v[112:115]
	v_mfma_f32_16x16x32_bf16 v[108:111], v[148:151], v[204:207], v[108:111]
	v_mfma_f32_16x16x32_bf16 v[104:107], v[164:167], v[204:207], v[104:107]
	v_mfma_f32_16x16x32_bf16 v[100:103], v[148:151], v[212:215], v[100:103]
	v_mfma_f32_16x16x32_bf16 v[96:99], v[164:167], v[212:215], v[96:99]
	v_mfma_f32_16x16x32_bf16 v[76:79], v[168:171], v[184:187], v[76:79]
	v_mfma_f32_16x16x32_bf16 v[72:75], v[176:179], v[184:187], v[72:75]
	v_mfma_f32_16x16x32_bf16 v[60:63], v[168:171], v[192:195], v[60:63]
	v_mfma_f32_16x16x32_bf16 v[52:55], v[176:179], v[192:195], v[52:55]
	v_mfma_f32_16x16x32_bf16 v[44:47], v[168:171], v[200:203], v[44:47]
	v_mfma_f32_16x16x32_bf16 v[40:43], v[176:179], v[200:203], v[40:43]
	v_mfma_f32_16x16x32_bf16 v[36:39], v[168:171], v[208:211], v[36:39]
	v_mfma_f32_16x16x32_bf16 v[32:35], v[176:179], v[208:211], v[32:35]
	v_mfma_f32_16x16x32_bf16 v[76:79], v[172:175], v[188:191], v[76:79]
	v_mfma_f32_16x16x32_bf16 v[72:75], v[180:183], v[188:191], v[72:75]
	v_mfma_f32_16x16x32_bf16 v[60:63], v[172:175], v[196:199], v[60:63]
	v_mfma_f32_16x16x32_bf16 v[52:55], v[180:183], v[196:199], v[52:55]
	v_mfma_f32_16x16x32_bf16 v[44:47], v[172:175], v[204:207], v[44:47]
	v_mfma_f32_16x16x32_bf16 v[40:43], v[180:183], v[204:207], v[40:43]
	v_mfma_f32_16x16x32_bf16 v[36:39], v[172:175], v[212:215], v[36:39]
	v_mfma_f32_16x16x32_bf16 v[32:35], v[180:183], v[212:215], v[32:35]
	s_setprio 0
	s_barrier
	s_add_i32 s30, s55, s33
	v_lshl_add_u64 v[152:153], v[152:153], 0, s[10:11]
	s_mov_b32 m0, s30
	ds_read_b128 v[184:187], v159 offset:49152
	ds_read_b128 v[188:191], v159 offset:50176
	ds_read_b128 v[192:195], v159 offset:51200
	ds_read_b128 v[196:199], v159 offset:52224
	ds_read_b128 v[200:203], v159 offset:53248
	ds_read_b128 v[204:207], v159 offset:54272
	ds_read_b128 v[208:211], v159 offset:55296
	ds_read_b128 v[212:215], v159 offset:56320
	global_load_lds_dwordx4 v[152:153], off
	s_add_i32 m0, s30, 0x2000
	s_add_u32 s28, s28, 0x40080
	v_lshl_add_u64 v[152:153], v[216:217], 0, s[10:11]
	s_addc_u32 s29, s29, 0
	s_add_i32 s30, s56, s33
	global_load_lds_dwordx4 v[152:153], off
	v_lshl_add_u64 v[152:153], s[28:29], 0, v[130:131]
	s_mov_b32 m0, s30
	s_nop 0
	global_load_lds_dwordx4 v[152:153], off
	v_lshl_add_u64 v[152:153], s[28:29], 0, v[134:135]
	s_add_i32 m0, s30, 0x2000
	s_nop 0
	global_load_lds_dwordx4 v[152:153], off
	v_lshl_add_u64 v[152:153], v[218:219], 0, s[10:11]
	s_mov_b32 m0, s41
	s_nop 0
	global_load_lds_dwordx4 v[152:153], off
	v_lshl_add_u64 v[152:153], v[220:221], 0, s[10:11]
	s_mov_b32 m0, s42
	s_nop 0
	global_load_lds_dwordx4 v[152:153], off
	s_waitcnt vmcnt(8)
	s_waitcnt lgkmcnt(0)
	s_barrier
	s_setprio 1
	s_waitcnt lgkmcnt(0)
	v_mfma_f32_16x16x32_bf16 v[92:95], v[144:147], v[184:187], v[92:95]
	v_mfma_f32_16x16x32_bf16 v[88:91], v[160:163], v[184:187], v[88:91]
	v_mfma_f32_16x16x32_bf16 v[84:87], v[144:147], v[192:195], v[84:87]
	v_mfma_f32_16x16x32_bf16 v[80:83], v[160:163], v[192:195], v[80:83]
	v_mfma_f32_16x16x32_bf16 v[68:71], v[144:147], v[200:203], v[68:71]
	v_mfma_f32_16x16x32_bf16 v[64:67], v[160:163], v[200:203], v[64:67]
	v_mfma_f32_16x16x32_bf16 v[56:59], v[144:147], v[208:211], v[56:59]
	v_mfma_f32_16x16x32_bf16 v[48:51], v[160:163], v[208:211], v[48:51]
	v_mfma_f32_16x16x32_bf16 v[92:95], v[148:151], v[188:191], v[92:95]
	v_mfma_f32_16x16x32_bf16 v[88:91], v[164:167], v[188:191], v[88:91]
	v_mfma_f32_16x16x32_bf16 v[84:87], v[148:151], v[196:199], v[84:87]
	v_mfma_f32_16x16x32_bf16 v[80:83], v[164:167], v[196:199], v[80:83]
	v_mfma_f32_16x16x32_bf16 v[68:71], v[148:151], v[204:207], v[68:71]
	v_mfma_f32_16x16x32_bf16 v[64:67], v[164:167], v[204:207], v[64:67]
	v_mfma_f32_16x16x32_bf16 v[56:59], v[148:151], v[212:215], v[56:59]
	v_mfma_f32_16x16x32_bf16 v[48:51], v[164:167], v[212:215], v[48:51]
	v_mfma_f32_16x16x32_bf16 v[28:31], v[168:171], v[184:187], v[28:31]
	v_mfma_f32_16x16x32_bf16 v[24:27], v[176:179], v[184:187], v[24:27]
	v_mfma_f32_16x16x32_bf16 v[20:23], v[168:171], v[192:195], v[20:23]
	v_mfma_f32_16x16x32_bf16 v[16:19], v[176:179], v[192:195], v[16:19]
	v_mfma_f32_16x16x32_bf16 v[12:15], v[168:171], v[200:203], v[12:15]
	v_mfma_f32_16x16x32_bf16 v[8:11], v[176:179], v[200:203], v[8:11]
	v_mfma_f32_16x16x32_bf16 v[4:7], v[168:171], v[208:211], v[4:7]
	v_mfma_f32_16x16x32_bf16 v[0:3], v[176:179], v[208:211], v[0:3]
	v_mfma_f32_16x16x32_bf16 v[28:31], v[172:175], v[188:191], v[28:31]
	v_mfma_f32_16x16x32_bf16 v[24:27], v[180:183], v[188:191], v[24:27]
	v_mfma_f32_16x16x32_bf16 v[20:23], v[172:175], v[196:199], v[20:23]
	v_mfma_f32_16x16x32_bf16 v[16:19], v[180:183], v[196:199], v[16:19]
	v_mfma_f32_16x16x32_bf16 v[12:15], v[172:175], v[204:207], v[12:15]
	v_mfma_f32_16x16x32_bf16 v[8:11], v[180:183], v[204:207], v[8:11]
	v_mfma_f32_16x16x32_bf16 v[4:7], v[172:175], v[212:215], v[4:7]
	v_mfma_f32_16x16x32_bf16 v[0:3], v[180:183], v[212:215], v[0:3]
	s_setprio 0
	s_barrier
	s_add_i32 s54, s54, 2
	s_add_u32 s52, s52, 0x100
	s_addc_u32 s53, s53, 0
	s_add_u32 s24, s24, 0x100
	s_addc_u32 s25, s25, 0
	s_cmp_gt_u32 s54, 13
	s_cbranch_scc0 .LBB0_1116
	s_and_b64 vcc, exec, s[12:13]
	s_cbranch_vccz .LBB0_1119
	s_barrier

.LBB0_1249:
	ds_read_b128 v[104:107], v238
	ds_read_b128 v[108:111], v238 offset:1024
	ds_read_b128 v[112:115], v238 offset:2048
	ds_read_b128 v[116:119], v238 offset:3072
	ds_read_b128 v[120:123], v239
	ds_read_b128 v[124:127], v239 offset:1024
	ds_read_b128 v[128:131], v239 offset:2048
	ds_read_b128 v[132:135], v239 offset:3072
	s_add_u32 s74, s24, 0xfffc0080
	s_addc_u32 s75, s25, -1
	s_cmp_eq_u32 s80, 12
	s_cselect_b32 s77, s69, s75
	s_cselect_b32 s76, s68, s74
	s_cselect_b32 s75, s67, s79
	s_cselect_b32 s74, s73, s78
	v_lshl_add_u64 v[208:209], s[24:25], 0, v[186:187]
	s_add_i32 m0, s42, 0xc000
	ds_read_b128 v[160:163], v240
	ds_read_b128 v[164:167], v240 offset:1024
	ds_read_b128 v[168:171], v240 offset:2048
	ds_read_b128 v[172:175], v240 offset:3072
	ds_read_b128 v[192:195], v240 offset:4096
	ds_read_b128 v[196:199], v240 offset:5120
	ds_read_b128 v[200:203], v240 offset:6144
	ds_read_b128 v[204:207], v240 offset:7168
	global_load_lds_dwordx4 v[208:209], off
	v_lshl_add_u64 v[208:209], s[24:25], 0, v[184:185]
	s_add_i32 m0, s42, 0xe000
	s_nop 0
	global_load_lds_dwordx4 v[208:209], off
	s_waitcnt vmcnt(8)
	s_waitcnt lgkmcnt(0)
	s_barrier
	s_setprio 1
	s_waitcnt lgkmcnt(0)
	v_mfma_f32_16x16x32_bf16 v[156:159], v[104:107], v[160:163], v[156:159]
	v_mfma_f32_16x16x32_bf16 v[60:63], v[112:115], v[160:163], v[60:63]
	v_mfma_f32_16x16x32_bf16 v[148:151], v[104:107], v[168:171], v[148:151]
	v_mfma_f32_16x16x32_bf16 v[52:55], v[112:115], v[168:171], v[52:55]
	v_mfma_f32_16x16x32_bf16 v[140:143], v[104:107], v[192:195], v[140:143]
	v_mfma_f32_16x16x32_bf16 v[44:47], v[112:115], v[192:195], v[44:47]
	v_mfma_f32_16x16x32_bf16 v[100:103], v[104:107], v[200:203], v[100:103]
	v_mfma_f32_16x16x32_bf16 v[36:39], v[112:115], v[200:203], v[36:39]
	v_mfma_f32_16x16x32_bf16 v[156:159], v[108:111], v[164:167], v[156:159]
	v_mfma_f32_16x16x32_bf16 v[60:63], v[116:119], v[164:167], v[60:63]
	v_mfma_f32_16x16x32_bf16 v[148:151], v[108:111], v[172:175], v[148:151]
	v_mfma_f32_16x16x32_bf16 v[52:55], v[116:119], v[172:175], v[52:55]
	v_mfma_f32_16x16x32_bf16 v[140:143], v[108:111], v[196:199], v[140:143]
	v_mfma_f32_16x16x32_bf16 v[44:47], v[116:119], v[196:199], v[44:47]
	v_mfma_f32_16x16x32_bf16 v[100:103], v[108:111], v[204:207], v[100:103]
	v_mfma_f32_16x16x32_bf16 v[36:39], v[116:119], v[204:207], v[36:39]
	v_mfma_f32_16x16x32_bf16 v[152:155], v[120:123], v[160:163], v[152:155]
	v_mfma_f32_16x16x32_bf16 v[56:59], v[128:131], v[160:163], v[56:59]
	v_mfma_f32_16x16x32_bf16 v[144:147], v[120:123], v[168:171], v[144:147]
	v_mfma_f32_16x16x32_bf16 v[48:51], v[128:131], v[168:171], v[48:51]
	v_mfma_f32_16x16x32_bf16 v[136:139], v[120:123], v[192:195], v[136:139]
	v_mfma_f32_16x16x32_bf16 v[40:43], v[128:131], v[192:195], v[40:43]
	v_mfma_f32_16x16x32_bf16 v[96:99], v[120:123], v[200:203], v[96:99]
	v_mfma_f32_16x16x32_bf16 v[32:35], v[128:131], v[200:203], v[32:35]
	v_mfma_f32_16x16x32_bf16 v[152:155], v[124:127], v[164:167], v[152:155]
	v_mfma_f32_16x16x32_bf16 v[56:59], v[132:135], v[164:167], v[56:59]
	v_mfma_f32_16x16x32_bf16 v[144:147], v[124:127], v[172:175], v[144:147]
	v_mfma_f32_16x16x32_bf16 v[48:51], v[132:135], v[172:175], v[48:51]
	v_mfma_f32_16x16x32_bf16 v[136:139], v[124:127], v[196:199], v[136:139]
	v_mfma_f32_16x16x32_bf16 v[40:43], v[132:135], v[196:199], v[40:43]
	v_mfma_f32_16x16x32_bf16 v[96:99], v[124:127], v[204:207], v[96:99]
	v_mfma_f32_16x16x32_bf16 v[32:35], v[132:135], v[204:207], v[32:35]
	s_setprio 0
	s_barrier
	s_add_i32 s81, s33, s41
	v_lshl_add_u64 v[208:209], s[74:75], 0, v[178:179]
	s_mov_b32 m0, s81
	ds_read_b128 v[160:163], v240 offset:16384
	ds_read_b128 v[164:167], v240 offset:17408
	ds_read_b128 v[168:171], v240 offset:18432
	ds_read_b128 v[172:175], v240 offset:19456
	ds_read_b128 v[192:195], v240 offset:20480
	ds_read_b128 v[196:199], v240 offset:21504
	ds_read_b128 v[200:203], v240 offset:22528
	ds_read_b128 v[204:207], v240 offset:23552
	global_load_lds_dwordx4 v[208:209], off
	s_add_i32 m0, s81, 0x2000
	s_add_u32 s82, s74, 0x40000
	v_lshl_add_u64 v[210:211], s[74:75], 0, v[182:183]
	s_addc_u32 s83, s75, 0
	s_add_i32 s81, s0, s41
	global_load_lds_dwordx4 v[210:211], off
	v_lshl_add_u64 v[212:213], s[82:83], 0, v[178:179]
	s_mov_b32 m0, s81
	v_lshl_add_u64 v[214:215], s[76:77], 0, v[180:181]
	global_load_lds_dwordx4 v[212:213], off
	v_lshl_add_u64 v[212:213], s[82:83], 0, v[182:183]
	s_add_i32 m0, s81, 0x2000
	s_nop 0
	global_load_lds_dwordx4 v[212:213], off
	v_lshl_add_u64 v[212:213], s[76:77], 0, v[176:177]
	s_mov_b32 m0, s42
	s_nop 0
	global_load_lds_dwordx4 v[212:213], off
	s_mov_b32 m0, s43
	s_nop 0
	global_load_lds_dwordx4 v[214:215], off
	s_waitcnt vmcnt(8)
	s_waitcnt lgkmcnt(0)
	s_barrier
	s_setprio 1
	s_waitcnt lgkmcnt(0)
	v_mfma_f32_16x16x32_bf16 v[92:95], v[104:107], v[160:163], v[92:95]
	v_mfma_f32_16x16x32_bf16 v[28:31], v[112:115], v[160:163], v[28:31]
	v_mfma_f32_16x16x32_bf16 v[84:87], v[104:107], v[168:171], v[84:87]
	v_mfma_f32_16x16x32_bf16 v[20:23], v[112:115], v[168:171], v[20:23]
	v_mfma_f32_16x16x32_bf16 v[76:79], v[104:107], v[192:195], v[76:79]
	v_mfma_f32_16x16x32_bf16 v[12:15], v[112:115], v[192:195], v[12:15]
	v_mfma_f32_16x16x32_bf16 v[68:71], v[104:107], v[200:203], v[68:71]
	v_mfma_f32_16x16x32_bf16 v[4:7], v[112:115], v[200:203], v[4:7]
	v_mfma_f32_16x16x32_bf16 v[92:95], v[108:111], v[164:167], v[92:95]
	v_mfma_f32_16x16x32_bf16 v[28:31], v[116:119], v[164:167], v[28:31]
	v_mfma_f32_16x16x32_bf16 v[84:87], v[108:111], v[172:175], v[84:87]
	v_mfma_f32_16x16x32_bf16 v[20:23], v[116:119], v[172:175], v[20:23]
	v_mfma_f32_16x16x32_bf16 v[76:79], v[108:111], v[196:199], v[76:79]
	v_mfma_f32_16x16x32_bf16 v[12:15], v[116:119], v[196:199], v[12:15]
	v_mfma_f32_16x16x32_bf16 v[68:71], v[108:111], v[204:207], v[68:71]
	v_mfma_f32_16x16x32_bf16 v[4:7], v[116:119], v[204:207], v[4:7]
	v_mfma_f32_16x16x32_bf16 v[88:91], v[120:123], v[160:163], v[88:91]
	v_mfma_f32_16x16x32_bf16 v[24:27], v[128:131], v[160:163], v[24:27]
	v_mfma_f32_16x16x32_bf16 v[80:83], v[120:123], v[168:171], v[80:83]
	v_mfma_f32_16x16x32_bf16 v[16:19], v[128:131], v[168:171], v[16:19]
	v_mfma_f32_16x16x32_bf16 v[72:75], v[120:123], v[192:195], v[72:75]
	v_mfma_f32_16x16x32_bf16 v[8:11], v[128:131], v[192:195], v[8:11]
	v_mfma_f32_16x16x32_bf16 v[64:67], v[120:123], v[200:203], v[64:67]
	v_mfma_f32_16x16x32_bf16 v[0:3], v[128:131], v[200:203], v[0:3]
	v_mfma_f32_16x16x32_bf16 v[88:91], v[124:127], v[164:167], v[88:91]
	v_mfma_f32_16x16x32_bf16 v[24:27], v[132:135], v[164:167], v[24:27]
	v_mfma_f32_16x16x32_bf16 v[80:83], v[124:127], v[172:175], v[80:83]
	v_mfma_f32_16x16x32_bf16 v[16:19], v[132:135], v[172:175], v[16:19]
	v_mfma_f32_16x16x32_bf16 v[72:75], v[124:127], v[196:199], v[72:75]
	v_mfma_f32_16x16x32_bf16 v[8:11], v[132:135], v[196:199], v[8:11]
	v_mfma_f32_16x16x32_bf16 v[64:67], v[124:127], v[204:207], v[64:67]
	v_mfma_f32_16x16x32_bf16 v[0:3], v[132:135], v[204:207], v[0:3]
	s_setprio 0
	s_barrier
	s_add_i32 s81, 0, 0x18000
	s_add_i32 s82, 0, 0x1c000
	v_add_u32_e32 v116, s81, v225
	v_add_u32_e32 v132, s82, v225
	ds_read_b128 v[104:107], v116
	ds_read_b128 v[108:111], v116 offset:1024
	ds_read_b128 v[112:115], v116 offset:2048
	ds_read_b128 v[116:119], v116 offset:3072
	ds_read_b128 v[120:123], v132
	ds_read_b128 v[124:127], v132 offset:1024
	ds_read_b128 v[128:131], v132 offset:2048
	ds_read_b128 v[132:135], v132 offset:3072
	s_add_u32 s76, s76, 0x40000
	s_addc_u32 s77, s77, 0
	s_mov_b32 m0, s96
	v_lshl_add_u64 v[216:217], s[76:77], 0, v[176:177]
	ds_read_b128 v[160:163], v240 offset:32768
	ds_read_b128 v[164:167], v240 offset:33792
	ds_read_b128 v[168:171], v240 offset:34816
	ds_read_b128 v[172:175], v240 offset:35840
	ds_read_b128 v[192:195], v240 offset:36864
	ds_read_b128 v[196:199], v240 offset:37888
	ds_read_b128 v[200:203], v240 offset:38912
	ds_read_b128 v[204:207], v240 offset:39936
	global_load_lds_dwordx4 v[216:217], off
	v_lshl_add_u64 v[216:217], s[76:77], 0, v[180:181]
	s_mov_b32 m0, s97
	s_nop 0
	global_load_lds_dwordx4 v[216:217], off
	s_waitcnt vmcnt(8)
	s_waitcnt lgkmcnt(0)
	s_barrier
	s_setprio 1
	s_waitcnt lgkmcnt(0)
	v_mfma_f32_16x16x32_bf16 v[156:159], v[104:107], v[160:163], v[156:159]
	v_mfma_f32_16x16x32_bf16 v[60:63], v[112:115], v[160:163], v[60:63]
	v_mfma_f32_16x16x32_bf16 v[148:151], v[104:107], v[168:171], v[148:151]
	v_mfma_f32_16x16x32_bf16 v[52:55], v[112:115], v[168:171], v[52:55]
	v_mfma_f32_16x16x32_bf16 v[140:143], v[104:107], v[192:195], v[140:143]
	v_mfma_f32_16x16x32_bf16 v[44:47], v[112:115], v[192:195], v[44:47]
	v_mfma_f32_16x16x32_bf16 v[100:103], v[104:107], v[200:203], v[100:103]
	v_mfma_f32_16x16x32_bf16 v[36:39], v[112:115], v[200:203], v[36:39]
	v_mfma_f32_16x16x32_bf16 v[156:159], v[108:111], v[164:167], v[156:159]
	v_mfma_f32_16x16x32_bf16 v[60:63], v[116:119], v[164:167], v[60:63]
	v_mfma_f32_16x16x32_bf16 v[148:151], v[108:111], v[172:175], v[148:151]
	v_mfma_f32_16x16x32_bf16 v[52:55], v[116:119], v[172:175], v[52:55]
	v_mfma_f32_16x16x32_bf16 v[140:143], v[108:111], v[196:199], v[140:143]
	v_mfma_f32_16x16x32_bf16 v[44:47], v[116:119], v[196:199], v[44:47]
	v_mfma_f32_16x16x32_bf16 v[100:103], v[108:111], v[204:207], v[100:103]
	v_mfma_f32_16x16x32_bf16 v[36:39], v[116:119], v[204:207], v[36:39]
	v_mfma_f32_16x16x32_bf16 v[152:155], v[120:123], v[160:163], v[152:155]
	v_mfma_f32_16x16x32_bf16 v[56:59], v[128:131], v[160:163], v[56:59]
	v_mfma_f32_16x16x32_bf16 v[144:147], v[120:123], v[168:171], v[144:147]
	v_mfma_f32_16x16x32_bf16 v[48:51], v[128:131], v[168:171], v[48:51]
	v_mfma_f32_16x16x32_bf16 v[136:139], v[120:123], v[192:195], v[136:139]
	v_mfma_f32_16x16x32_bf16 v[40:43], v[128:131], v[192:195], v[40:43]
	v_mfma_f32_16x16x32_bf16 v[96:99], v[120:123], v[200:203], v[96:99]
	v_mfma_f32_16x16x32_bf16 v[32:35], v[128:131], v[200:203], v[32:35]
	v_mfma_f32_16x16x32_bf16 v[152:155], v[124:127], v[164:167], v[152:155]
	v_mfma_f32_16x16x32_bf16 v[56:59], v[132:135], v[164:167], v[56:59]
	v_mfma_f32_16x16x32_bf16 v[144:147], v[124:127], v[172:175], v[144:147]
	v_mfma_f32_16x16x32_bf16 v[48:51], v[132:135], v[172:175], v[48:51]
	v_mfma_f32_16x16x32_bf16 v[136:139], v[124:127], v[196:199], v[136:139]
	v_mfma_f32_16x16x32_bf16 v[40:43], v[132:135], v[196:199], v[40:43]
	v_mfma_f32_16x16x32_bf16 v[96:99], v[124:127], v[204:207], v[96:99]
	v_mfma_f32_16x16x32_bf16 v[32:35], v[132:135], v[204:207], v[32:35]
	s_setprio 0
	s_barrier
	s_add_i32 s76, s81, s41
	v_lshl_add_u64 v[208:209], v[208:209], 0, s[46:47]
	s_mov_b32 m0, s76
	ds_read_b128 v[160:163], v240 offset:49152
	ds_read_b128 v[164:167], v240 offset:50176
	ds_read_b128 v[168:171], v240 offset:51200
	ds_read_b128 v[172:175], v240 offset:52224
	ds_read_b128 v[192:195], v240 offset:53248
	ds_read_b128 v[196:199], v240 offset:54272
	ds_read_b128 v[200:203], v240 offset:55296
	ds_read_b128 v[204:207], v240 offset:56320
	global_load_lds_dwordx4 v[208:209], off
	s_add_i32 m0, s76, 0x2000
	s_add_u32 s74, s74, 0x40080
	v_lshl_add_u64 v[208:209], v[210:211], 0, s[46:47]
	s_addc_u32 s75, s75, 0
	s_add_i32 s76, s82, s41
	global_load_lds_dwordx4 v[208:209], off
	v_lshl_add_u64 v[208:209], s[74:75], 0, v[178:179]
	s_mov_b32 m0, s76
	s_nop 0
	global_load_lds_dwordx4 v[208:209], off
	v_lshl_add_u64 v[208:209], s[74:75], 0, v[182:183]
	s_add_i32 m0, s76, 0x2000
	s_nop 0
	global_load_lds_dwordx4 v[208:209], off
	v_lshl_add_u64 v[208:209], v[212:213], 0, s[46:47]
	s_mov_b32 m0, s7
	s_nop 0
	global_load_lds_dwordx4 v[208:209], off
	v_lshl_add_u64 v[208:209], v[214:215], 0, s[46:47]
	s_mov_b32 m0, s36
	s_nop 0
	global_load_lds_dwordx4 v[208:209], off
	s_waitcnt vmcnt(8)
	s_waitcnt lgkmcnt(0)
	s_barrier
	s_setprio 1
	s_waitcnt lgkmcnt(0)
	v_mfma_f32_16x16x32_bf16 v[92:95], v[104:107], v[160:163], v[92:95]
	v_mfma_f32_16x16x32_bf16 v[28:31], v[112:115], v[160:163], v[28:31]
	v_mfma_f32_16x16x32_bf16 v[84:87], v[104:107], v[168:171], v[84:87]
	v_mfma_f32_16x16x32_bf16 v[20:23], v[112:115], v[168:171], v[20:23]
	v_mfma_f32_16x16x32_bf16 v[76:79], v[104:107], v[192:195], v[76:79]
	v_mfma_f32_16x16x32_bf16 v[12:15], v[112:115], v[192:195], v[12:15]
	v_mfma_f32_16x16x32_bf16 v[68:71], v[104:107], v[200:203], v[68:71]
	v_mfma_f32_16x16x32_bf16 v[4:7], v[112:115], v[200:203], v[4:7]
	v_mfma_f32_16x16x32_bf16 v[92:95], v[108:111], v[164:167], v[92:95]
	v_mfma_f32_16x16x32_bf16 v[28:31], v[116:119], v[164:167], v[28:31]
	v_mfma_f32_16x16x32_bf16 v[84:87], v[108:111], v[172:175], v[84:87]
	v_mfma_f32_16x16x32_bf16 v[20:23], v[116:119], v[172:175], v[20:23]
	v_mfma_f32_16x16x32_bf16 v[76:79], v[108:111], v[196:199], v[76:79]
	v_mfma_f32_16x16x32_bf16 v[12:15], v[116:119], v[196:199], v[12:15]
	v_mfma_f32_16x16x32_bf16 v[68:71], v[108:111], v[204:207], v[68:71]
	v_mfma_f32_16x16x32_bf16 v[4:7], v[116:119], v[204:207], v[4:7]
	v_mfma_f32_16x16x32_bf16 v[88:91], v[120:123], v[160:163], v[88:91]
	v_mfma_f32_16x16x32_bf16 v[24:27], v[128:131], v[160:163], v[24:27]
	v_mfma_f32_16x16x32_bf16 v[80:83], v[120:123], v[168:171], v[80:83]
	v_mfma_f32_16x16x32_bf16 v[16:19], v[128:131], v[168:171], v[16:19]
	v_mfma_f32_16x16x32_bf16 v[72:75], v[120:123], v[192:195], v[72:75]
	v_mfma_f32_16x16x32_bf16 v[8:11], v[128:131], v[192:195], v[8:11]
	v_mfma_f32_16x16x32_bf16 v[64:67], v[120:123], v[200:203], v[64:67]
	v_mfma_f32_16x16x32_bf16 v[0:3], v[128:131], v[200:203], v[0:3]
	v_mfma_f32_16x16x32_bf16 v[88:91], v[124:127], v[164:167], v[88:91]
	v_mfma_f32_16x16x32_bf16 v[24:27], v[132:135], v[164:167], v[24:27]
	v_mfma_f32_16x16x32_bf16 v[80:83], v[124:127], v[172:175], v[80:83]
	v_mfma_f32_16x16x32_bf16 v[16:19], v[132:135], v[172:175], v[16:19]
	v_mfma_f32_16x16x32_bf16 v[72:75], v[124:127], v[196:199], v[72:75]
	v_mfma_f32_16x16x32_bf16 v[8:11], v[132:135], v[196:199], v[8:11]
	v_mfma_f32_16x16x32_bf16 v[64:67], v[124:127], v[204:207], v[64:67]
	v_mfma_f32_16x16x32_bf16 v[0:3], v[132:135], v[204:207], v[0:3]
	s_setprio 0
	s_barrier
	s_add_i32 s80, s80, 2
	s_add_u32 s78, s78, 0x100
	s_addc_u32 s79, s79, 0
	s_add_u32 s24, s24, 0x100
	s_addc_u32 s25, s25, 0
	s_cmp_gt_u32 s80, 13
	s_cbranch_scc0 .LBB0_1249
	s_and_b64 vcc, exec, s[48:49]
	s_cbranch_vccz .LBB0_1252
	s_barrier

.LBB0_1367:
	ds_read_b128 v[144:147], v157
	ds_read_b128 v[148:151], v157 offset:1024
	ds_read_b128 v[160:163], v157 offset:2048
	ds_read_b128 v[164:167], v157 offset:3072
	ds_read_b128 v[168:171], v158
	ds_read_b128 v[172:175], v158 offset:1024
	ds_read_b128 v[176:179], v158 offset:2048
	ds_read_b128 v[180:183], v158 offset:3072
	s_add_u32 s24, s22, 0x100
	s_addc_u32 s25, s23, 0
	s_cmp_eq_u32 s52, 40
	s_cselect_b32 s29, s11, s25
	s_cselect_b32 s28, s10, s24
	s_cselect_b32 s27, s21, s51
	s_cselect_b32 s26, s20, s50
	v_lshl_add_u64 v[152:153], s[22:23], 0, v[138:139]
	s_add_i32 m0, s7, 0xc000
	ds_read_b128 v[184:187], v159
	ds_read_b128 v[188:191], v159 offset:1024
	ds_read_b128 v[192:195], v159 offset:2048
	ds_read_b128 v[196:199], v159 offset:3072
	ds_read_b128 v[200:203], v159 offset:4096
	ds_read_b128 v[204:207], v159 offset:5120
	ds_read_b128 v[208:211], v159 offset:6144
	ds_read_b128 v[212:215], v159 offset:7168
	global_load_lds_dwordx4 v[152:153], off
	v_lshl_add_u64 v[152:153], s[22:23], 0, v[136:137]
	s_add_i32 m0, s7, 0xe000
	s_nop 0
	global_load_lds_dwordx4 v[152:153], off
	s_waitcnt vmcnt(8)
	s_waitcnt lgkmcnt(0)
	s_barrier
	s_setprio 1
	s_waitcnt lgkmcnt(0)
	v_mfma_f32_16x16x32_bf16 v[124:127], v[144:147], v[184:187], v[124:127]
	v_mfma_f32_16x16x32_bf16 v[120:123], v[160:163], v[184:187], v[120:123]
	v_mfma_f32_16x16x32_bf16 v[116:119], v[144:147], v[192:195], v[116:119]
	v_mfma_f32_16x16x32_bf16 v[112:115], v[160:163], v[192:195], v[112:115]
	v_mfma_f32_16x16x32_bf16 v[108:111], v[144:147], v[200:203], v[108:111]
	v_mfma_f32_16x16x32_bf16 v[104:107], v[160:163], v[200:203], v[104:107]
	v_mfma_f32_16x16x32_bf16 v[100:103], v[144:147], v[208:211], v[100:103]
	v_mfma_f32_16x16x32_bf16 v[96:99], v[160:163], v[208:211], v[96:99]
	v_mfma_f32_16x16x32_bf16 v[124:127], v[148:151], v[188:191], v[124:127]
	v_mfma_f32_16x16x32_bf16 v[120:123], v[164:167], v[188:191], v[120:123]
	v_mfma_f32_16x16x32_bf16 v[116:119], v[148:151], v[196:199], v[116:119]
	v_mfma_f32_16x16x32_bf16 v[112:115], v[164:167], v[196:199], v[112:115]
	v_mfma_f32_16x16x32_bf16 v[108:111], v[148:151], v[204:207], v[108:111]
	v_mfma_f32_16x16x32_bf16 v[104:107], v[164:167], v[204:207], v[104:107]
	v_mfma_f32_16x16x32_bf16 v[100:103], v[148:151], v[212:215], v[100:103]
	v_mfma_f32_16x16x32_bf16 v[96:99], v[164:167], v[212:215], v[96:99]
	v_mfma_f32_16x16x32_bf16 v[76:79], v[168:171], v[184:187], v[76:79]
	v_mfma_f32_16x16x32_bf16 v[72:75], v[176:179], v[184:187], v[72:75]
	v_mfma_f32_16x16x32_bf16 v[60:63], v[168:171], v[192:195], v[60:63]
	v_mfma_f32_16x16x32_bf16 v[52:55], v[176:179], v[192:195], v[52:55]
	v_mfma_f32_16x16x32_bf16 v[44:47], v[168:171], v[200:203], v[44:47]
	v_mfma_f32_16x16x32_bf16 v[40:43], v[176:179], v[200:203], v[40:43]
	v_mfma_f32_16x16x32_bf16 v[36:39], v[168:171], v[208:211], v[36:39]
	v_mfma_f32_16x16x32_bf16 v[32:35], v[176:179], v[208:211], v[32:35]
	v_mfma_f32_16x16x32_bf16 v[76:79], v[172:175], v[188:191], v[76:79]
	v_mfma_f32_16x16x32_bf16 v[72:75], v[180:183], v[188:191], v[72:75]
	v_mfma_f32_16x16x32_bf16 v[60:63], v[172:175], v[196:199], v[60:63]
	v_mfma_f32_16x16x32_bf16 v[52:55], v[180:183], v[196:199], v[52:55]
	v_mfma_f32_16x16x32_bf16 v[44:47], v[172:175], v[204:207], v[44:47]
	v_mfma_f32_16x16x32_bf16 v[40:43], v[180:183], v[204:207], v[40:43]
	v_mfma_f32_16x16x32_bf16 v[36:39], v[172:175], v[212:215], v[36:39]
	v_mfma_f32_16x16x32_bf16 v[32:35], v[180:183], v[212:215], v[32:35]
	s_setprio 0
	s_barrier
	s_add_i32 s22, s41, s6
	v_lshl_add_u64 v[152:153], s[26:27], 0, v[130:131]
	s_mov_b32 m0, s22
	ds_read_b128 v[184:187], v159 offset:16384
	ds_read_b128 v[188:191], v159 offset:17408
	ds_read_b128 v[192:195], v159 offset:18432
	ds_read_b128 v[196:199], v159 offset:19456
	ds_read_b128 v[200:203], v159 offset:20480
	ds_read_b128 v[204:207], v159 offset:21504
	ds_read_b128 v[208:211], v159 offset:22528
	ds_read_b128 v[212:215], v159 offset:23552
	global_load_lds_dwordx4 v[152:153], off
	s_add_i32 m0, s22, 0x2000
	s_add_u32 s22, s26, 0xb0000
	v_lshl_add_u64 v[216:217], s[26:27], 0, v[134:135]
	s_addc_u32 s23, s27, 0
	s_add_i32 s53, s42, s6
	global_load_lds_dwordx4 v[216:217], off
	v_lshl_add_u64 v[218:219], s[22:23], 0, v[130:131]
	s_mov_b32 m0, s53
	v_lshl_add_u64 v[220:221], s[28:29], 0, v[132:133]
	global_load_lds_dwordx4 v[218:219], off
	v_lshl_add_u64 v[218:219], s[22:23], 0, v[134:135]
	s_add_i32 m0, s53, 0x2000
	s_nop 0
	global_load_lds_dwordx4 v[218:219], off
	v_lshl_add_u64 v[218:219], s[28:29], 0, v[128:129]
	s_mov_b32 m0, s7
	s_nop 0
	global_load_lds_dwordx4 v[218:219], off
	s_mov_b32 m0, s30
	s_nop 0
	global_load_lds_dwordx4 v[220:221], off
	s_waitcnt vmcnt(8)
	s_waitcnt lgkmcnt(0)
	s_barrier
	s_setprio 1
	s_waitcnt lgkmcnt(0)
	v_mfma_f32_16x16x32_bf16 v[92:95], v[144:147], v[184:187], v[92:95]
	v_mfma_f32_16x16x32_bf16 v[88:91], v[160:163], v[184:187], v[88:91]
	v_mfma_f32_16x16x32_bf16 v[84:87], v[144:147], v[192:195], v[84:87]
	v_mfma_f32_16x16x32_bf16 v[80:83], v[160:163], v[192:195], v[80:83]
	v_mfma_f32_16x16x32_bf16 v[68:71], v[144:147], v[200:203], v[68:71]
	v_mfma_f32_16x16x32_bf16 v[64:67], v[160:163], v[200:203], v[64:67]
	v_mfma_f32_16x16x32_bf16 v[56:59], v[144:147], v[208:211], v[56:59]
	v_mfma_f32_16x16x32_bf16 v[48:51], v[160:163], v[208:211], v[48:51]
	v_mfma_f32_16x16x32_bf16 v[92:95], v[148:151], v[188:191], v[92:95]
	v_mfma_f32_16x16x32_bf16 v[88:91], v[164:167], v[188:191], v[88:91]
	v_mfma_f32_16x16x32_bf16 v[84:87], v[148:151], v[196:199], v[84:87]
	v_mfma_f32_16x16x32_bf16 v[80:83], v[164:167], v[196:199], v[80:83]
	v_mfma_f32_16x16x32_bf16 v[68:71], v[148:151], v[204:207], v[68:71]
	v_mfma_f32_16x16x32_bf16 v[64:67], v[164:167], v[204:207], v[64:67]
	v_mfma_f32_16x16x32_bf16 v[56:59], v[148:151], v[212:215], v[56:59]
	v_mfma_f32_16x16x32_bf16 v[48:51], v[164:167], v[212:215], v[48:51]
	v_mfma_f32_16x16x32_bf16 v[28:31], v[168:171], v[184:187], v[28:31]
	v_mfma_f32_16x16x32_bf16 v[24:27], v[176:179], v[184:187], v[24:27]
	v_mfma_f32_16x16x32_bf16 v[20:23], v[168:171], v[192:195], v[20:23]
	v_mfma_f32_16x16x32_bf16 v[16:19], v[176:179], v[192:195], v[16:19]
	v_mfma_f32_16x16x32_bf16 v[12:15], v[168:171], v[200:203], v[12:15]
	v_mfma_f32_16x16x32_bf16 v[8:11], v[176:179], v[200:203], v[8:11]
	v_mfma_f32_16x16x32_bf16 v[4:7], v[168:171], v[208:211], v[4:7]
	v_mfma_f32_16x16x32_bf16 v[0:3], v[176:179], v[208:211], v[0:3]
	v_mfma_f32_16x16x32_bf16 v[28:31], v[172:175], v[188:191], v[28:31]
	v_mfma_f32_16x16x32_bf16 v[24:27], v[180:183], v[188:191], v[24:27]
	v_mfma_f32_16x16x32_bf16 v[20:23], v[172:175], v[196:199], v[20:23]
	v_mfma_f32_16x16x32_bf16 v[16:19], v[180:183], v[196:199], v[16:19]
	v_mfma_f32_16x16x32_bf16 v[12:15], v[172:175], v[204:207], v[12:15]
	v_mfma_f32_16x16x32_bf16 v[8:11], v[180:183], v[204:207], v[8:11]
	v_mfma_f32_16x16x32_bf16 v[4:7], v[172:175], v[212:215], v[4:7]
	v_mfma_f32_16x16x32_bf16 v[0:3], v[180:183], v[212:215], v[0:3]
	s_setprio 0
	s_barrier
	s_add_i32 s53, 0, 0x18000
	s_add_i32 s54, 0, 0x1c000
	v_add_u32_e32 v164, s53, v155
	v_add_u32_e32 v180, s54, v155
	ds_read_b128 v[144:147], v164
	ds_read_b128 v[148:151], v164 offset:1024
	ds_read_b128 v[160:163], v164 offset:2048
	ds_read_b128 v[164:167], v164 offset:3072
	ds_read_b128 v[168:171], v180
	ds_read_b128 v[172:175], v180 offset:1024
	ds_read_b128 v[176:179], v180 offset:2048
	ds_read_b128 v[180:183], v180 offset:3072
	s_add_u32 s22, s28, 0xb0000
	s_addc_u32 s23, s29, 0
	s_mov_b32 m0, s31
	v_lshl_add_u64 v[222:223], s[22:23], 0, v[128:129]
	ds_read_b128 v[184:187], v159 offset:32768
	ds_read_b128 v[188:191], v159 offset:33792
	ds_read_b128 v[192:195], v159 offset:34816
	ds_read_b128 v[196:199], v159 offset:35840
	ds_read_b128 v[200:203], v159 offset:36864
	ds_read_b128 v[204:207], v159 offset:37888
	ds_read_b128 v[208:211], v159 offset:38912
	ds_read_b128 v[212:215], v159 offset:39936
	global_load_lds_dwordx4 v[222:223], off
	v_lshl_add_u64 v[222:223], s[22:23], 0, v[132:133]
	s_mov_b32 m0, s33
	s_nop 0
	global_load_lds_dwordx4 v[222:223], off
	s_waitcnt vmcnt(8)
	s_waitcnt lgkmcnt(0)
	s_barrier
	s_setprio 1
	s_waitcnt lgkmcnt(0)
	v_mfma_f32_16x16x32_bf16 v[124:127], v[144:147], v[184:187], v[124:127]
	v_mfma_f32_16x16x32_bf16 v[120:123], v[160:163], v[184:187], v[120:123]
	v_mfma_f32_16x16x32_bf16 v[116:119], v[144:147], v[192:195], v[116:119]
	v_mfma_f32_16x16x32_bf16 v[112:115], v[160:163], v[192:195], v[112:115]
	v_mfma_f32_16x16x32_bf16 v[108:111], v[144:147], v[200:203], v[108:111]
	v_mfma_f32_16x16x32_bf16 v[104:107], v[160:163], v[200:203], v[104:107]
	v_mfma_f32_16x16x32_bf16 v[100:103], v[144:147], v[208:211], v[100:103]
	v_mfma_f32_16x16x32_bf16 v[96:99], v[160:163], v[208:211], v[96:99]
	v_mfma_f32_16x16x32_bf16 v[124:127], v[148:151], v[188:191], v[124:127]
	v_mfma_f32_16x16x32_bf16 v[120:123], v[164:167], v[188:191], v[120:123]
	v_mfma_f32_16x16x32_bf16 v[116:119], v[148:151], v[196:199], v[116:119]
	v_mfma_f32_16x16x32_bf16 v[112:115], v[164:167], v[196:199], v[112:115]
	v_mfma_f32_16x16x32_bf16 v[108:111], v[148:151], v[204:207], v[108:111]
	v_mfma_f32_16x16x32_bf16 v[104:107], v[164:167], v[204:207], v[104:107]
	v_mfma_f32_16x16x32_bf16 v[100:103], v[148:151], v[212:215], v[100:103]
	v_mfma_f32_16x16x32_bf16 v[96:99], v[164:167], v[212:215], v[96:99]
	v_mfma_f32_16x16x32_bf16 v[76:79], v[168:171], v[184:187], v[76:79]
	v_mfma_f32_16x16x32_bf16 v[72:75], v[176:179], v[184:187], v[72:75]
	v_mfma_f32_16x16x32_bf16 v[60:63], v[168:171], v[192:195], v[60:63]
	v_mfma_f32_16x16x32_bf16 v[52:55], v[176:179], v[192:195], v[52:55]
	v_mfma_f32_16x16x32_bf16 v[44:47], v[168:171], v[200:203], v[44:47]
	v_mfma_f32_16x16x32_bf16 v[40:43], v[176:179], v[200:203], v[40:43]
	v_mfma_f32_16x16x32_bf16 v[36:39], v[168:171], v[208:211], v[36:39]
	v_mfma_f32_16x16x32_bf16 v[32:35], v[176:179], v[208:211], v[32:35]
	v_mfma_f32_16x16x32_bf16 v[76:79], v[172:175], v[188:191], v[76:79]
	v_mfma_f32_16x16x32_bf16 v[72:75], v[180:183], v[188:191], v[72:75]
	v_mfma_f32_16x16x32_bf16 v[60:63], v[172:175], v[196:199], v[60:63]
	v_mfma_f32_16x16x32_bf16 v[52:55], v[180:183], v[196:199], v[52:55]
	v_mfma_f32_16x16x32_bf16 v[44:47], v[172:175], v[204:207], v[44:47]
	v_mfma_f32_16x16x32_bf16 v[40:43], v[180:183], v[204:207], v[40:43]
	v_mfma_f32_16x16x32_bf16 v[36:39], v[172:175], v[212:215], v[36:39]
	v_mfma_f32_16x16x32_bf16 v[32:35], v[180:183], v[212:215], v[32:35]
	s_setprio 0
	s_barrier
	s_add_i32 s22, s53, s6
	v_lshl_add_u64 v[152:153], v[152:153], 0, s[16:17]
	s_mov_b32 m0, s22
	ds_read_b128 v[184:187], v159 offset:49152
	ds_read_b128 v[188:191], v159 offset:50176
	ds_read_b128 v[192:195], v159 offset:51200
	ds_read_b128 v[196:199], v159 offset:52224
	ds_read_b128 v[200:203], v159 offset:53248
	ds_read_b128 v[204:207], v159 offset:54272
	ds_read_b128 v[208:211], v159 offset:55296
	ds_read_b128 v[212:215], v159 offset:56320
	global_load_lds_dwordx4 v[152:153], off
	s_add_i32 m0, s22, 0x2000
	s_add_u32 s22, s26, 0xb0080
	v_lshl_add_u64 v[152:153], v[216:217], 0, s[16:17]
	s_addc_u32 s23, s27, 0
	s_add_i32 s26, s54, s6
	global_load_lds_dwordx4 v[152:153], off
	v_lshl_add_u64 v[152:153], s[22:23], 0, v[130:131]
	s_mov_b32 m0, s26
	s_nop 0
	global_load_lds_dwordx4 v[152:153], off
	v_lshl_add_u64 v[152:153], s[22:23], 0, v[134:135]
	s_add_i32 m0, s26, 0x2000
	s_nop 0
	global_load_lds_dwordx4 v[152:153], off
	v_lshl_add_u64 v[152:153], v[218:219], 0, s[16:17]
	s_mov_b32 m0, s37
	s_nop 0
	global_load_lds_dwordx4 v[152:153], off
	v_lshl_add_u64 v[152:153], v[220:221], 0, s[16:17]
	s_mov_b32 m0, s38
	s_nop 0
	global_load_lds_dwordx4 v[152:153], off
	s_waitcnt vmcnt(8)
	s_waitcnt lgkmcnt(0)
	s_barrier
	s_setprio 1
	s_waitcnt lgkmcnt(0)
	v_mfma_f32_16x16x32_bf16 v[92:95], v[144:147], v[184:187], v[92:95]
	v_mfma_f32_16x16x32_bf16 v[88:91], v[160:163], v[184:187], v[88:91]
	v_mfma_f32_16x16x32_bf16 v[84:87], v[144:147], v[192:195], v[84:87]
	v_mfma_f32_16x16x32_bf16 v[80:83], v[160:163], v[192:195], v[80:83]
	v_mfma_f32_16x16x32_bf16 v[68:71], v[144:147], v[200:203], v[68:71]
	v_mfma_f32_16x16x32_bf16 v[64:67], v[160:163], v[200:203], v[64:67]
	v_mfma_f32_16x16x32_bf16 v[56:59], v[144:147], v[208:211], v[56:59]
	v_mfma_f32_16x16x32_bf16 v[48:51], v[160:163], v[208:211], v[48:51]
	v_mfma_f32_16x16x32_bf16 v[92:95], v[148:151], v[188:191], v[92:95]
	v_mfma_f32_16x16x32_bf16 v[88:91], v[164:167], v[188:191], v[88:91]
	v_mfma_f32_16x16x32_bf16 v[84:87], v[148:151], v[196:199], v[84:87]
	v_mfma_f32_16x16x32_bf16 v[80:83], v[164:167], v[196:199], v[80:83]
	v_mfma_f32_16x16x32_bf16 v[68:71], v[148:151], v[204:207], v[68:71]
	v_mfma_f32_16x16x32_bf16 v[64:67], v[164:167], v[204:207], v[64:67]
	v_mfma_f32_16x16x32_bf16 v[56:59], v[148:151], v[212:215], v[56:59]
	v_mfma_f32_16x16x32_bf16 v[48:51], v[164:167], v[212:215], v[48:51]
	v_mfma_f32_16x16x32_bf16 v[28:31], v[168:171], v[184:187], v[28:31]
	v_mfma_f32_16x16x32_bf16 v[24:27], v[176:179], v[184:187], v[24:27]
	v_mfma_f32_16x16x32_bf16 v[20:23], v[168:171], v[192:195], v[20:23]
	v_mfma_f32_16x16x32_bf16 v[16:19], v[176:179], v[192:195], v[16:19]
	v_mfma_f32_16x16x32_bf16 v[12:15], v[168:171], v[200:203], v[12:15]
	v_mfma_f32_16x16x32_bf16 v[8:11], v[176:179], v[200:203], v[8:11]
	v_mfma_f32_16x16x32_bf16 v[4:7], v[168:171], v[208:211], v[4:7]
	v_mfma_f32_16x16x32_bf16 v[0:3], v[176:179], v[208:211], v[0:3]
	v_mfma_f32_16x16x32_bf16 v[28:31], v[172:175], v[188:191], v[28:31]
	v_mfma_f32_16x16x32_bf16 v[24:27], v[180:183], v[188:191], v[24:27]
	v_mfma_f32_16x16x32_bf16 v[20:23], v[172:175], v[196:199], v[20:23]
	v_mfma_f32_16x16x32_bf16 v[16:19], v[180:183], v[196:199], v[16:19]
	v_mfma_f32_16x16x32_bf16 v[12:15], v[172:175], v[204:207], v[12:15]
	v_mfma_f32_16x16x32_bf16 v[8:11], v[180:183], v[204:207], v[8:11]
	v_mfma_f32_16x16x32_bf16 v[4:7], v[172:175], v[212:215], v[4:7]
	v_mfma_f32_16x16x32_bf16 v[0:3], v[180:183], v[212:215], v[0:3]
	s_setprio 0
	s_barrier
	s_add_i32 s52, s52, 2
	s_add_u32 s50, s50, 0x100
	s_addc_u32 s51, s51, 0
	s_cmp_gt_u32 s52, 41
	s_mov_b64 s[22:23], s[24:25]
	s_cbranch_scc0 .LBB0_1367
	s_and_b64 vcc, exec, s[18:19]
	s_cbranch_vccz .LBB0_1370
	s_barrier

.LBB0_1584:
	ds_read_b128 v[146:149], v153
	ds_read_b128 v[156:159], v153 offset:1024
	ds_read_b128 v[160:163], v153 offset:2048
	ds_read_b128 v[164:167], v153 offset:3072
	ds_read_b128 v[168:171], v154
	ds_read_b128 v[172:175], v154 offset:1024
	ds_read_b128 v[176:179], v154 offset:2048
	ds_read_b128 v[180:183], v154 offset:3072
	s_add_u32 s46, s44, 0xfffc0080
	s_addc_u32 s47, s45, -1
	s_cmp_eq_u32 s56, 12
	s_cselect_b32 s49, s25, s47
	s_cselect_b32 s48, s31, s46
	s_cselect_b32 s47, s23, s55
	s_cselect_b32 s46, s39, s54
	v_lshl_add_u64 v[216:217], s[44:45], 0, v[140:141]
	s_add_i32 m0, s6, 0xc000
	ds_read_b128 v[184:187], v155
	ds_read_b128 v[188:191], v155 offset:1024
	ds_read_b128 v[192:195], v155 offset:2048
	ds_read_b128 v[196:199], v155 offset:3072
	ds_read_b128 v[200:203], v155 offset:4096
	ds_read_b128 v[204:207], v155 offset:5120
	ds_read_b128 v[208:211], v155 offset:6144
	ds_read_b128 v[212:215], v155 offset:7168
	global_load_lds_dwordx4 v[216:217], off
	v_lshl_add_u64 v[216:217], s[44:45], 0, v[138:139]
	s_add_i32 m0, s6, 0xe000
	s_nop 0
	global_load_lds_dwordx4 v[216:217], off
	s_waitcnt vmcnt(8)
	s_waitcnt lgkmcnt(0)
	s_barrier
	s_setprio 1
	s_waitcnt lgkmcnt(0)
	v_mfma_f32_16x16x32_bf16 v[124:127], v[146:149], v[184:187], v[124:127]
	v_mfma_f32_16x16x32_bf16 v[120:123], v[160:163], v[184:187], v[120:123]
	v_mfma_f32_16x16x32_bf16 v[116:119], v[146:149], v[192:195], v[116:119]
	v_mfma_f32_16x16x32_bf16 v[112:115], v[160:163], v[192:195], v[112:115]
	v_mfma_f32_16x16x32_bf16 v[108:111], v[146:149], v[200:203], v[108:111]
	v_mfma_f32_16x16x32_bf16 v[104:107], v[160:163], v[200:203], v[104:107]
	v_mfma_f32_16x16x32_bf16 v[100:103], v[146:149], v[208:211], v[100:103]
	v_mfma_f32_16x16x32_bf16 v[96:99], v[160:163], v[208:211], v[96:99]
	v_mfma_f32_16x16x32_bf16 v[124:127], v[156:159], v[188:191], v[124:127]
	v_mfma_f32_16x16x32_bf16 v[120:123], v[164:167], v[188:191], v[120:123]
	v_mfma_f32_16x16x32_bf16 v[116:119], v[156:159], v[196:199], v[116:119]
	v_mfma_f32_16x16x32_bf16 v[112:115], v[164:167], v[196:199], v[112:115]
	v_mfma_f32_16x16x32_bf16 v[108:111], v[156:159], v[204:207], v[108:111]
	v_mfma_f32_16x16x32_bf16 v[104:107], v[164:167], v[204:207], v[104:107]
	v_mfma_f32_16x16x32_bf16 v[100:103], v[156:159], v[212:215], v[100:103]
	v_mfma_f32_16x16x32_bf16 v[96:99], v[164:167], v[212:215], v[96:99]
	v_mfma_f32_16x16x32_bf16 v[60:63], v[168:171], v[184:187], v[60:63]
	v_mfma_f32_16x16x32_bf16 v[56:59], v[176:179], v[184:187], v[56:59]
	v_mfma_f32_16x16x32_bf16 v[52:55], v[168:171], v[192:195], v[52:55]
	v_mfma_f32_16x16x32_bf16 v[48:51], v[176:179], v[192:195], v[48:51]
	v_mfma_f32_16x16x32_bf16 v[44:47], v[168:171], v[200:203], v[44:47]
	v_mfma_f32_16x16x32_bf16 v[40:43], v[176:179], v[200:203], v[40:43]
	v_mfma_f32_16x16x32_bf16 v[36:39], v[168:171], v[208:211], v[36:39]
	v_mfma_f32_16x16x32_bf16 v[32:35], v[176:179], v[208:211], v[32:35]
	v_mfma_f32_16x16x32_bf16 v[60:63], v[172:175], v[188:191], v[60:63]
	v_mfma_f32_16x16x32_bf16 v[56:59], v[180:183], v[188:191], v[56:59]
	v_mfma_f32_16x16x32_bf16 v[52:55], v[172:175], v[196:199], v[52:55]
	v_mfma_f32_16x16x32_bf16 v[48:51], v[180:183], v[196:199], v[48:51]
	v_mfma_f32_16x16x32_bf16 v[44:47], v[172:175], v[204:207], v[44:47]
	v_mfma_f32_16x16x32_bf16 v[40:43], v[180:183], v[204:207], v[40:43]
	v_mfma_f32_16x16x32_bf16 v[36:39], v[172:175], v[212:215], v[36:39]
	v_mfma_f32_16x16x32_bf16 v[32:35], v[180:183], v[212:215], v[32:35]
	s_setprio 0
	s_barrier
	s_add_i32 s57, s43, s5
	v_lshl_add_u64 v[216:217], s[46:47], 0, v[130:131]
	s_mov_b32 m0, s57
	ds_read_b128 v[184:187], v155 offset:16384
	ds_read_b128 v[188:191], v155 offset:17408
	ds_read_b128 v[192:195], v155 offset:18432
	ds_read_b128 v[196:199], v155 offset:19456
	ds_read_b128 v[200:203], v155 offset:20480
	ds_read_b128 v[204:207], v155 offset:21504
	ds_read_b128 v[208:211], v155 offset:22528
	ds_read_b128 v[212:215], v155 offset:23552
	global_load_lds_dwordx4 v[216:217], off
	s_add_i32 m0, s57, 0x2000
	s_add_u32 s58, s46, 0x40000
	v_lshl_add_u64 v[218:219], s[46:47], 0, v[134:135]
	s_addc_u32 s59, s47, 0
	s_add_i32 s57, s50, s5
	global_load_lds_dwordx4 v[218:219], off
	v_lshl_add_u64 v[220:221], s[58:59], 0, v[130:131]
	s_mov_b32 m0, s57
	v_lshl_add_u64 v[222:223], s[48:49], 0, v[132:133]
	global_load_lds_dwordx4 v[220:221], off
	v_lshl_add_u64 v[220:221], s[58:59], 0, v[134:135]
	s_add_i32 m0, s57, 0x2000
	s_nop 0
	global_load_lds_dwordx4 v[220:221], off
	v_lshl_add_u64 v[220:221], s[48:49], 0, v[128:129]
	s_mov_b32 m0, s6
	s_nop 0
	global_load_lds_dwordx4 v[220:221], off
	s_mov_b32 m0, s7
	s_nop 0
	global_load_lds_dwordx4 v[222:223], off
	s_waitcnt vmcnt(8)
	s_waitcnt lgkmcnt(0)
	s_barrier
	s_setprio 1
	s_waitcnt lgkmcnt(0)
	v_mfma_f32_16x16x32_bf16 v[92:95], v[146:149], v[184:187], v[92:95]
	v_mfma_f32_16x16x32_bf16 v[88:91], v[160:163], v[184:187], v[88:91]
	v_mfma_f32_16x16x32_bf16 v[84:87], v[146:149], v[192:195], v[84:87]
	v_mfma_f32_16x16x32_bf16 v[80:83], v[160:163], v[192:195], v[80:83]
	v_mfma_f32_16x16x32_bf16 v[76:79], v[146:149], v[200:203], v[76:79]
	v_mfma_f32_16x16x32_bf16 v[72:75], v[160:163], v[200:203], v[72:75]
	v_mfma_f32_16x16x32_bf16 v[68:71], v[146:149], v[208:211], v[68:71]
	v_mfma_f32_16x16x32_bf16 v[64:67], v[160:163], v[208:211], v[64:67]
	v_mfma_f32_16x16x32_bf16 v[92:95], v[156:159], v[188:191], v[92:95]
	v_mfma_f32_16x16x32_bf16 v[88:91], v[164:167], v[188:191], v[88:91]
	v_mfma_f32_16x16x32_bf16 v[84:87], v[156:159], v[196:199], v[84:87]
	v_mfma_f32_16x16x32_bf16 v[80:83], v[164:167], v[196:199], v[80:83]
	v_mfma_f32_16x16x32_bf16 v[76:79], v[156:159], v[204:207], v[76:79]
	v_mfma_f32_16x16x32_bf16 v[72:75], v[164:167], v[204:207], v[72:75]
	v_mfma_f32_16x16x32_bf16 v[68:71], v[156:159], v[212:215], v[68:71]
	v_mfma_f32_16x16x32_bf16 v[64:67], v[164:167], v[212:215], v[64:67]
	v_mfma_f32_16x16x32_bf16 v[28:31], v[168:171], v[184:187], v[28:31]
	v_mfma_f32_16x16x32_bf16 v[24:27], v[176:179], v[184:187], v[24:27]
	v_mfma_f32_16x16x32_bf16 v[20:23], v[168:171], v[192:195], v[20:23]
	v_mfma_f32_16x16x32_bf16 v[16:19], v[176:179], v[192:195], v[16:19]
	v_mfma_f32_16x16x32_bf16 v[12:15], v[168:171], v[200:203], v[12:15]
	v_mfma_f32_16x16x32_bf16 v[8:11], v[176:179], v[200:203], v[8:11]
	v_mfma_f32_16x16x32_bf16 v[4:7], v[168:171], v[208:211], v[4:7]
	v_mfma_f32_16x16x32_bf16 v[0:3], v[176:179], v[208:211], v[0:3]
	v_mfma_f32_16x16x32_bf16 v[28:31], v[172:175], v[188:191], v[28:31]
	v_mfma_f32_16x16x32_bf16 v[24:27], v[180:183], v[188:191], v[24:27]
	v_mfma_f32_16x16x32_bf16 v[20:23], v[172:175], v[196:199], v[20:23]
	v_mfma_f32_16x16x32_bf16 v[16:19], v[180:183], v[196:199], v[16:19]
	v_mfma_f32_16x16x32_bf16 v[12:15], v[172:175], v[204:207], v[12:15]
	v_mfma_f32_16x16x32_bf16 v[8:11], v[180:183], v[204:207], v[8:11]
	v_mfma_f32_16x16x32_bf16 v[4:7], v[172:175], v[212:215], v[4:7]
	v_mfma_f32_16x16x32_bf16 v[0:3], v[180:183], v[212:215], v[0:3]
	s_setprio 0
	s_barrier
	s_add_i32 s57, 0, 0x18000
	s_add_i32 s58, 0, 0x1c000
	v_add_u32_e32 v164, s57, v151
	v_add_u32_e32 v180, s58, v151
	ds_read_b128 v[146:149], v164
	ds_read_b128 v[156:159], v164 offset:1024
	ds_read_b128 v[160:163], v164 offset:2048
	ds_read_b128 v[164:167], v164 offset:3072
	ds_read_b128 v[168:171], v180
	ds_read_b128 v[172:175], v180 offset:1024
	ds_read_b128 v[176:179], v180 offset:2048
	ds_read_b128 v[180:183], v180 offset:3072
	s_add_u32 s48, s48, 0x40000
	s_addc_u32 s49, s49, 0
	s_mov_b32 m0, s8
	v_lshl_add_u64 v[224:225], s[48:49], 0, v[128:129]
	ds_read_b128 v[184:187], v155 offset:32768
	ds_read_b128 v[188:191], v155 offset:33792
	ds_read_b128 v[192:195], v155 offset:34816
	ds_read_b128 v[196:199], v155 offset:35840
	ds_read_b128 v[200:203], v155 offset:36864
	ds_read_b128 v[204:207], v155 offset:37888
	ds_read_b128 v[208:211], v155 offset:38912
	ds_read_b128 v[212:215], v155 offset:39936
	global_load_lds_dwordx4 v[224:225], off
	v_lshl_add_u64 v[224:225], s[48:49], 0, v[132:133]
	s_mov_b32 m0, s9
	s_nop 0
	global_load_lds_dwordx4 v[224:225], off
	s_waitcnt vmcnt(8)
	s_waitcnt lgkmcnt(0)
	s_barrier
	s_setprio 1
	s_waitcnt lgkmcnt(0)
	v_mfma_f32_16x16x32_bf16 v[124:127], v[146:149], v[184:187], v[124:127]
	v_mfma_f32_16x16x32_bf16 v[120:123], v[160:163], v[184:187], v[120:123]
	v_mfma_f32_16x16x32_bf16 v[116:119], v[146:149], v[192:195], v[116:119]
	v_mfma_f32_16x16x32_bf16 v[112:115], v[160:163], v[192:195], v[112:115]
	v_mfma_f32_16x16x32_bf16 v[108:111], v[146:149], v[200:203], v[108:111]
	v_mfma_f32_16x16x32_bf16 v[104:107], v[160:163], v[200:203], v[104:107]
	v_mfma_f32_16x16x32_bf16 v[100:103], v[146:149], v[208:211], v[100:103]
	v_mfma_f32_16x16x32_bf16 v[96:99], v[160:163], v[208:211], v[96:99]
	v_mfma_f32_16x16x32_bf16 v[124:127], v[156:159], v[188:191], v[124:127]
	v_mfma_f32_16x16x32_bf16 v[120:123], v[164:167], v[188:191], v[120:123]
	v_mfma_f32_16x16x32_bf16 v[116:119], v[156:159], v[196:199], v[116:119]
	v_mfma_f32_16x16x32_bf16 v[112:115], v[164:167], v[196:199], v[112:115]
	v_mfma_f32_16x16x32_bf16 v[108:111], v[156:159], v[204:207], v[108:111]
	v_mfma_f32_16x16x32_bf16 v[104:107], v[164:167], v[204:207], v[104:107]
	v_mfma_f32_16x16x32_bf16 v[100:103], v[156:159], v[212:215], v[100:103]
	v_mfma_f32_16x16x32_bf16 v[96:99], v[164:167], v[212:215], v[96:99]
	v_mfma_f32_16x16x32_bf16 v[60:63], v[168:171], v[184:187], v[60:63]
	v_mfma_f32_16x16x32_bf16 v[56:59], v[176:179], v[184:187], v[56:59]
	v_mfma_f32_16x16x32_bf16 v[52:55], v[168:171], v[192:195], v[52:55]
	v_mfma_f32_16x16x32_bf16 v[48:51], v[176:179], v[192:195], v[48:51]
	v_mfma_f32_16x16x32_bf16 v[44:47], v[168:171], v[200:203], v[44:47]
	v_mfma_f32_16x16x32_bf16 v[40:43], v[176:179], v[200:203], v[40:43]
	v_mfma_f32_16x16x32_bf16 v[36:39], v[168:171], v[208:211], v[36:39]
	v_mfma_f32_16x16x32_bf16 v[32:35], v[176:179], v[208:211], v[32:35]
	v_mfma_f32_16x16x32_bf16 v[60:63], v[172:175], v[188:191], v[60:63]
	v_mfma_f32_16x16x32_bf16 v[56:59], v[180:183], v[188:191], v[56:59]
	v_mfma_f32_16x16x32_bf16 v[52:55], v[172:175], v[196:199], v[52:55]
	v_mfma_f32_16x16x32_bf16 v[48:51], v[180:183], v[196:199], v[48:51]
	v_mfma_f32_16x16x32_bf16 v[44:47], v[172:175], v[204:207], v[44:47]
	v_mfma_f32_16x16x32_bf16 v[40:43], v[180:183], v[204:207], v[40:43]
	v_mfma_f32_16x16x32_bf16 v[36:39], v[172:175], v[212:215], v[36:39]
	v_mfma_f32_16x16x32_bf16 v[32:35], v[180:183], v[212:215], v[32:35]
	s_setprio 0
	s_barrier
	s_add_i32 s48, s57, s5
	v_lshl_add_u64 v[216:217], v[216:217], 0, s[18:19]
	s_mov_b32 m0, s48
	ds_read_b128 v[184:187], v155 offset:49152
	ds_read_b128 v[188:191], v155 offset:50176
	ds_read_b128 v[192:195], v155 offset:51200
	ds_read_b128 v[196:199], v155 offset:52224
	ds_read_b128 v[200:203], v155 offset:53248
	ds_read_b128 v[204:207], v155 offset:54272
	ds_read_b128 v[208:211], v155 offset:55296
	ds_read_b128 v[212:215], v155 offset:56320
	global_load_lds_dwordx4 v[216:217], off
	s_add_i32 m0, s48, 0x2000
	s_add_u32 s46, s46, 0x40080
	v_lshl_add_u64 v[216:217], v[218:219], 0, s[18:19]
	s_addc_u32 s47, s47, 0
	s_add_i32 s48, s58, s5
	global_load_lds_dwordx4 v[216:217], off
	v_lshl_add_u64 v[216:217], s[46:47], 0, v[130:131]
	s_mov_b32 m0, s48
	s_nop 0
	global_load_lds_dwordx4 v[216:217], off
	v_lshl_add_u64 v[216:217], s[46:47], 0, v[134:135]
	s_add_i32 m0, s48, 0x2000
	s_nop 0
	global_load_lds_dwordx4 v[216:217], off
	v_lshl_add_u64 v[216:217], v[220:221], 0, s[18:19]
	s_mov_b32 m0, s35
	s_nop 0
	global_load_lds_dwordx4 v[216:217], off
	v_lshl_add_u64 v[216:217], v[222:223], 0, s[18:19]
	s_mov_b32 m0, s36
	s_nop 0
	global_load_lds_dwordx4 v[216:217], off
	s_waitcnt vmcnt(8)
	s_waitcnt lgkmcnt(0)
	s_barrier
	s_setprio 1
	s_waitcnt lgkmcnt(0)
	v_mfma_f32_16x16x32_bf16 v[92:95], v[146:149], v[184:187], v[92:95]
	v_mfma_f32_16x16x32_bf16 v[88:91], v[160:163], v[184:187], v[88:91]
	v_mfma_f32_16x16x32_bf16 v[84:87], v[146:149], v[192:195], v[84:87]
	v_mfma_f32_16x16x32_bf16 v[80:83], v[160:163], v[192:195], v[80:83]
	v_mfma_f32_16x16x32_bf16 v[76:79], v[146:149], v[200:203], v[76:79]
	v_mfma_f32_16x16x32_bf16 v[72:75], v[160:163], v[200:203], v[72:75]
	v_mfma_f32_16x16x32_bf16 v[68:71], v[146:149], v[208:211], v[68:71]
	v_mfma_f32_16x16x32_bf16 v[64:67], v[160:163], v[208:211], v[64:67]
	v_mfma_f32_16x16x32_bf16 v[92:95], v[156:159], v[188:191], v[92:95]
	v_mfma_f32_16x16x32_bf16 v[88:91], v[164:167], v[188:191], v[88:91]
	v_mfma_f32_16x16x32_bf16 v[84:87], v[156:159], v[196:199], v[84:87]
	v_mfma_f32_16x16x32_bf16 v[80:83], v[164:167], v[196:199], v[80:83]
	v_mfma_f32_16x16x32_bf16 v[76:79], v[156:159], v[204:207], v[76:79]
	v_mfma_f32_16x16x32_bf16 v[72:75], v[164:167], v[204:207], v[72:75]
	v_mfma_f32_16x16x32_bf16 v[68:71], v[156:159], v[212:215], v[68:71]
	v_mfma_f32_16x16x32_bf16 v[64:67], v[164:167], v[212:215], v[64:67]
	v_mfma_f32_16x16x32_bf16 v[28:31], v[168:171], v[184:187], v[28:31]
	v_mfma_f32_16x16x32_bf16 v[24:27], v[176:179], v[184:187], v[24:27]
	v_mfma_f32_16x16x32_bf16 v[20:23], v[168:171], v[192:195], v[20:23]
	v_mfma_f32_16x16x32_bf16 v[16:19], v[176:179], v[192:195], v[16:19]
	v_mfma_f32_16x16x32_bf16 v[12:15], v[168:171], v[200:203], v[12:15]
	v_mfma_f32_16x16x32_bf16 v[8:11], v[176:179], v[200:203], v[8:11]
	v_mfma_f32_16x16x32_bf16 v[4:7], v[168:171], v[208:211], v[4:7]
	v_mfma_f32_16x16x32_bf16 v[0:3], v[176:179], v[208:211], v[0:3]
	v_mfma_f32_16x16x32_bf16 v[28:31], v[172:175], v[188:191], v[28:31]
	v_mfma_f32_16x16x32_bf16 v[24:27], v[180:183], v[188:191], v[24:27]
	v_mfma_f32_16x16x32_bf16 v[20:23], v[172:175], v[196:199], v[20:23]
	v_mfma_f32_16x16x32_bf16 v[16:19], v[180:183], v[196:199], v[16:19]
	v_mfma_f32_16x16x32_bf16 v[12:15], v[172:175], v[204:207], v[12:15]
	v_mfma_f32_16x16x32_bf16 v[8:11], v[180:183], v[204:207], v[8:11]
	v_mfma_f32_16x16x32_bf16 v[4:7], v[172:175], v[212:215], v[4:7]
	v_mfma_f32_16x16x32_bf16 v[0:3], v[180:183], v[212:215], v[0:3]
	s_setprio 0
	s_barrier
	s_add_i32 s56, s56, 2
	s_add_u32 s54, s54, 0x100
	s_addc_u32 s55, s55, 0
	s_add_u32 s44, s44, 0x100
	s_addc_u32 s45, s45, 0
	s_cmp_gt_u32 s56, 13
	s_cbranch_scc0 .LBB0_1584
	s_and_b64 vcc, exec, s[20:21]
	s_cbranch_vccz .LBB0_1587
	s_barrier

.LBB0_1805:
	ds_read_b128 v[144:147], v157
	ds_read_b128 v[148:151], v157 offset:1024
	ds_read_b128 v[160:163], v157 offset:2048
	ds_read_b128 v[164:167], v157 offset:3072
	ds_read_b128 v[168:171], v158
	ds_read_b128 v[172:175], v158 offset:1024
	ds_read_b128 v[176:179], v158 offset:2048
	ds_read_b128 v[180:183], v158 offset:3072
	s_add_u32 s44, s30, 0xfffc0080
	s_addc_u32 s45, s31, -1
	s_cmp_eq_u32 s54, 12
	s_cselect_b32 s47, s23, s45
	s_cselect_b32 s46, s50, s44
	s_cselect_b32 s45, s21, s53
	s_cselect_b32 s44, s51, s52
	v_lshl_add_u64 v[152:153], s[30:31], 0, v[138:139]
	s_add_i32 m0, s7, 0xc000
	ds_read_b128 v[184:187], v159
	ds_read_b128 v[188:191], v159 offset:1024
	ds_read_b128 v[192:195], v159 offset:2048
	ds_read_b128 v[196:199], v159 offset:3072
	ds_read_b128 v[200:203], v159 offset:4096
	ds_read_b128 v[204:207], v159 offset:5120
	ds_read_b128 v[208:211], v159 offset:6144
	ds_read_b128 v[212:215], v159 offset:7168
	global_load_lds_dwordx4 v[152:153], off
	v_lshl_add_u64 v[152:153], s[30:31], 0, v[136:137]
	s_add_i32 m0, s7, 0xe000
	s_nop 0
	global_load_lds_dwordx4 v[152:153], off
	s_waitcnt vmcnt(8)
	s_waitcnt lgkmcnt(0)
	s_barrier
	s_setprio 1
	s_waitcnt lgkmcnt(0)
	v_mfma_f32_16x16x32_bf16 v[124:127], v[144:147], v[184:187], v[124:127]
	v_mfma_f32_16x16x32_bf16 v[120:123], v[160:163], v[184:187], v[120:123]
	v_mfma_f32_16x16x32_bf16 v[116:119], v[144:147], v[192:195], v[116:119]
	v_mfma_f32_16x16x32_bf16 v[112:115], v[160:163], v[192:195], v[112:115]
	v_mfma_f32_16x16x32_bf16 v[108:111], v[144:147], v[200:203], v[108:111]
	v_mfma_f32_16x16x32_bf16 v[104:107], v[160:163], v[200:203], v[104:107]
	v_mfma_f32_16x16x32_bf16 v[100:103], v[144:147], v[208:211], v[100:103]
	v_mfma_f32_16x16x32_bf16 v[96:99], v[160:163], v[208:211], v[96:99]
	v_mfma_f32_16x16x32_bf16 v[124:127], v[148:151], v[188:191], v[124:127]
	v_mfma_f32_16x16x32_bf16 v[120:123], v[164:167], v[188:191], v[120:123]
	v_mfma_f32_16x16x32_bf16 v[116:119], v[148:151], v[196:199], v[116:119]
	v_mfma_f32_16x16x32_bf16 v[112:115], v[164:167], v[196:199], v[112:115]
	v_mfma_f32_16x16x32_bf16 v[108:111], v[148:151], v[204:207], v[108:111]
	v_mfma_f32_16x16x32_bf16 v[104:107], v[164:167], v[204:207], v[104:107]
	v_mfma_f32_16x16x32_bf16 v[100:103], v[148:151], v[212:215], v[100:103]
	v_mfma_f32_16x16x32_bf16 v[96:99], v[164:167], v[212:215], v[96:99]
	v_mfma_f32_16x16x32_bf16 v[76:79], v[168:171], v[184:187], v[76:79]
	v_mfma_f32_16x16x32_bf16 v[72:75], v[176:179], v[184:187], v[72:75]
	v_mfma_f32_16x16x32_bf16 v[60:63], v[168:171], v[192:195], v[60:63]
	v_mfma_f32_16x16x32_bf16 v[52:55], v[176:179], v[192:195], v[52:55]
	v_mfma_f32_16x16x32_bf16 v[44:47], v[168:171], v[200:203], v[44:47]
	v_mfma_f32_16x16x32_bf16 v[40:43], v[176:179], v[200:203], v[40:43]
	v_mfma_f32_16x16x32_bf16 v[36:39], v[168:171], v[208:211], v[36:39]
	v_mfma_f32_16x16x32_bf16 v[32:35], v[176:179], v[208:211], v[32:35]
	v_mfma_f32_16x16x32_bf16 v[76:79], v[172:175], v[188:191], v[76:79]
	v_mfma_f32_16x16x32_bf16 v[72:75], v[180:183], v[188:191], v[72:75]
	v_mfma_f32_16x16x32_bf16 v[60:63], v[172:175], v[196:199], v[60:63]
	v_mfma_f32_16x16x32_bf16 v[52:55], v[180:183], v[196:199], v[52:55]
	v_mfma_f32_16x16x32_bf16 v[44:47], v[172:175], v[204:207], v[44:47]
	v_mfma_f32_16x16x32_bf16 v[40:43], v[180:183], v[204:207], v[40:43]
	v_mfma_f32_16x16x32_bf16 v[36:39], v[172:175], v[212:215], v[36:39]
	v_mfma_f32_16x16x32_bf16 v[32:35], v[180:183], v[212:215], v[32:35]
	s_setprio 0
	s_barrier
	s_add_i32 s55, s41, s6
	v_lshl_add_u64 v[152:153], s[44:45], 0, v[130:131]
	s_mov_b32 m0, s55
	ds_read_b128 v[184:187], v159 offset:16384
	ds_read_b128 v[188:191], v159 offset:17408
	ds_read_b128 v[192:195], v159 offset:18432
	ds_read_b128 v[196:199], v159 offset:19456
	ds_read_b128 v[200:203], v159 offset:20480
	ds_read_b128 v[204:207], v159 offset:21504
	ds_read_b128 v[208:211], v159 offset:22528
	ds_read_b128 v[212:215], v159 offset:23552
	global_load_lds_dwordx4 v[152:153], off
	s_add_i32 m0, s55, 0x2000
	s_add_u32 s56, s44, 0x40000
	v_lshl_add_u64 v[216:217], s[44:45], 0, v[134:135]
	s_addc_u32 s57, s45, 0
	s_add_i32 s55, s42, s6
	global_load_lds_dwordx4 v[216:217], off
	v_lshl_add_u64 v[218:219], s[56:57], 0, v[130:131]
	s_mov_b32 m0, s55
	v_lshl_add_u64 v[220:221], s[46:47], 0, v[132:133]
	global_load_lds_dwordx4 v[218:219], off
	v_lshl_add_u64 v[218:219], s[56:57], 0, v[134:135]
	s_add_i32 m0, s55, 0x2000
	s_nop 0
	global_load_lds_dwordx4 v[218:219], off
	v_lshl_add_u64 v[218:219], s[46:47], 0, v[128:129]
	s_mov_b32 m0, s7
	s_nop 0
	global_load_lds_dwordx4 v[218:219], off
	s_mov_b32 m0, s8
	s_nop 0
	global_load_lds_dwordx4 v[220:221], off
	s_waitcnt vmcnt(8)
	s_waitcnt lgkmcnt(0)
	s_barrier
	s_setprio 1
	s_waitcnt lgkmcnt(0)
	v_mfma_f32_16x16x32_bf16 v[92:95], v[144:147], v[184:187], v[92:95]
	v_mfma_f32_16x16x32_bf16 v[88:91], v[160:163], v[184:187], v[88:91]
	v_mfma_f32_16x16x32_bf16 v[84:87], v[144:147], v[192:195], v[84:87]
	v_mfma_f32_16x16x32_bf16 v[80:83], v[160:163], v[192:195], v[80:83]
	v_mfma_f32_16x16x32_bf16 v[68:71], v[144:147], v[200:203], v[68:71]
	v_mfma_f32_16x16x32_bf16 v[64:67], v[160:163], v[200:203], v[64:67]
	v_mfma_f32_16x16x32_bf16 v[56:59], v[144:147], v[208:211], v[56:59]
	v_mfma_f32_16x16x32_bf16 v[48:51], v[160:163], v[208:211], v[48:51]
	v_mfma_f32_16x16x32_bf16 v[92:95], v[148:151], v[188:191], v[92:95]
	v_mfma_f32_16x16x32_bf16 v[88:91], v[164:167], v[188:191], v[88:91]
	v_mfma_f32_16x16x32_bf16 v[84:87], v[148:151], v[196:199], v[84:87]
	v_mfma_f32_16x16x32_bf16 v[80:83], v[164:167], v[196:199], v[80:83]
	v_mfma_f32_16x16x32_bf16 v[68:71], v[148:151], v[204:207], v[68:71]
	v_mfma_f32_16x16x32_bf16 v[64:67], v[164:167], v[204:207], v[64:67]
	v_mfma_f32_16x16x32_bf16 v[56:59], v[148:151], v[212:215], v[56:59]
	v_mfma_f32_16x16x32_bf16 v[48:51], v[164:167], v[212:215], v[48:51]
	v_mfma_f32_16x16x32_bf16 v[28:31], v[168:171], v[184:187], v[28:31]
	v_mfma_f32_16x16x32_bf16 v[24:27], v[176:179], v[184:187], v[24:27]
	v_mfma_f32_16x16x32_bf16 v[20:23], v[168:171], v[192:195], v[20:23]
	v_mfma_f32_16x16x32_bf16 v[16:19], v[176:179], v[192:195], v[16:19]
	v_mfma_f32_16x16x32_bf16 v[12:15], v[168:171], v[200:203], v[12:15]
	v_mfma_f32_16x16x32_bf16 v[8:11], v[176:179], v[200:203], v[8:11]
	v_mfma_f32_16x16x32_bf16 v[4:7], v[168:171], v[208:211], v[4:7]
	v_mfma_f32_16x16x32_bf16 v[0:3], v[176:179], v[208:211], v[0:3]
	v_mfma_f32_16x16x32_bf16 v[28:31], v[172:175], v[188:191], v[28:31]
	v_mfma_f32_16x16x32_bf16 v[24:27], v[180:183], v[188:191], v[24:27]
	v_mfma_f32_16x16x32_bf16 v[20:23], v[172:175], v[196:199], v[20:23]
	v_mfma_f32_16x16x32_bf16 v[16:19], v[180:183], v[196:199], v[16:19]
	v_mfma_f32_16x16x32_bf16 v[12:15], v[172:175], v[204:207], v[12:15]
	v_mfma_f32_16x16x32_bf16 v[8:11], v[180:183], v[204:207], v[8:11]
	v_mfma_f32_16x16x32_bf16 v[4:7], v[172:175], v[212:215], v[4:7]
	v_mfma_f32_16x16x32_bf16 v[0:3], v[180:183], v[212:215], v[0:3]
	s_setprio 0
	s_barrier
	s_add_i32 s55, 0, 0x18000
	s_add_i32 s56, 0, 0x1c000
	v_add_u32_e32 v164, s55, v155
	v_add_u32_e32 v180, s56, v155
	ds_read_b128 v[144:147], v164
	ds_read_b128 v[148:151], v164 offset:1024
	ds_read_b128 v[160:163], v164 offset:2048
	ds_read_b128 v[164:167], v164 offset:3072
	ds_read_b128 v[168:171], v180
	ds_read_b128 v[172:175], v180 offset:1024
	ds_read_b128 v[176:179], v180 offset:2048
	ds_read_b128 v[180:183], v180 offset:3072
	s_add_u32 s46, s46, 0x40000
	s_addc_u32 s47, s47, 0
	s_mov_b32 m0, s9
	v_lshl_add_u64 v[222:223], s[46:47], 0, v[128:129]
	ds_read_b128 v[184:187], v159 offset:32768
	ds_read_b128 v[188:191], v159 offset:33792
	ds_read_b128 v[192:195], v159 offset:34816
	ds_read_b128 v[196:199], v159 offset:35840
	ds_read_b128 v[200:203], v159 offset:36864
	ds_read_b128 v[204:207], v159 offset:37888
	ds_read_b128 v[208:211], v159 offset:38912
	ds_read_b128 v[212:215], v159 offset:39936
	global_load_lds_dwordx4 v[222:223], off
	v_lshl_add_u64 v[222:223], s[46:47], 0, v[132:133]
	s_mov_b32 m0, s33
	s_nop 0
	global_load_lds_dwordx4 v[222:223], off
	s_waitcnt vmcnt(8)
	s_waitcnt lgkmcnt(0)
	s_barrier
	s_setprio 1
	s_waitcnt lgkmcnt(0)
	v_mfma_f32_16x16x32_bf16 v[124:127], v[144:147], v[184:187], v[124:127]
	v_mfma_f32_16x16x32_bf16 v[120:123], v[160:163], v[184:187], v[120:123]
	v_mfma_f32_16x16x32_bf16 v[116:119], v[144:147], v[192:195], v[116:119]
	v_mfma_f32_16x16x32_bf16 v[112:115], v[160:163], v[192:195], v[112:115]
	v_mfma_f32_16x16x32_bf16 v[108:111], v[144:147], v[200:203], v[108:111]
	v_mfma_f32_16x16x32_bf16 v[104:107], v[160:163], v[200:203], v[104:107]
	v_mfma_f32_16x16x32_bf16 v[100:103], v[144:147], v[208:211], v[100:103]
	v_mfma_f32_16x16x32_bf16 v[96:99], v[160:163], v[208:211], v[96:99]
	v_mfma_f32_16x16x32_bf16 v[124:127], v[148:151], v[188:191], v[124:127]
	v_mfma_f32_16x16x32_bf16 v[120:123], v[164:167], v[188:191], v[120:123]
	v_mfma_f32_16x16x32_bf16 v[116:119], v[148:151], v[196:199], v[116:119]
	v_mfma_f32_16x16x32_bf16 v[112:115], v[164:167], v[196:199], v[112:115]
	v_mfma_f32_16x16x32_bf16 v[108:111], v[148:151], v[204:207], v[108:111]
	v_mfma_f32_16x16x32_bf16 v[104:107], v[164:167], v[204:207], v[104:107]
	v_mfma_f32_16x16x32_bf16 v[100:103], v[148:151], v[212:215], v[100:103]
	v_mfma_f32_16x16x32_bf16 v[96:99], v[164:167], v[212:215], v[96:99]
	v_mfma_f32_16x16x32_bf16 v[76:79], v[168:171], v[184:187], v[76:79]
	v_mfma_f32_16x16x32_bf16 v[72:75], v[176:179], v[184:187], v[72:75]
	v_mfma_f32_16x16x32_bf16 v[60:63], v[168:171], v[192:195], v[60:63]
	v_mfma_f32_16x16x32_bf16 v[52:55], v[176:179], v[192:195], v[52:55]
	v_mfma_f32_16x16x32_bf16 v[44:47], v[168:171], v[200:203], v[44:47]
	v_mfma_f32_16x16x32_bf16 v[40:43], v[176:179], v[200:203], v[40:43]
	v_mfma_f32_16x16x32_bf16 v[36:39], v[168:171], v[208:211], v[36:39]
	v_mfma_f32_16x16x32_bf16 v[32:35], v[176:179], v[208:211], v[32:35]
	v_mfma_f32_16x16x32_bf16 v[76:79], v[172:175], v[188:191], v[76:79]
	v_mfma_f32_16x16x32_bf16 v[72:75], v[180:183], v[188:191], v[72:75]
	v_mfma_f32_16x16x32_bf16 v[60:63], v[172:175], v[196:199], v[60:63]
	v_mfma_f32_16x16x32_bf16 v[52:55], v[180:183], v[196:199], v[52:55]
	v_mfma_f32_16x16x32_bf16 v[44:47], v[172:175], v[204:207], v[44:47]
	v_mfma_f32_16x16x32_bf16 v[40:43], v[180:183], v[204:207], v[40:43]
	v_mfma_f32_16x16x32_bf16 v[36:39], v[172:175], v[212:215], v[36:39]
	v_mfma_f32_16x16x32_bf16 v[32:35], v[180:183], v[212:215], v[32:35]
	s_setprio 0
	s_barrier
	s_add_i32 s46, s55, s6
	v_lshl_add_u64 v[152:153], v[152:153], 0, s[16:17]
	s_mov_b32 m0, s46
	ds_read_b128 v[184:187], v159 offset:49152
	ds_read_b128 v[188:191], v159 offset:50176
	ds_read_b128 v[192:195], v159 offset:51200
	ds_read_b128 v[196:199], v159 offset:52224
	ds_read_b128 v[200:203], v159 offset:53248
	ds_read_b128 v[204:207], v159 offset:54272
	ds_read_b128 v[208:211], v159 offset:55296
	ds_read_b128 v[212:215], v159 offset:56320
	global_load_lds_dwordx4 v[152:153], off
	s_add_i32 m0, s46, 0x2000
	s_add_u32 s44, s44, 0x40080
	v_lshl_add_u64 v[152:153], v[216:217], 0, s[16:17]
	s_addc_u32 s45, s45, 0
	s_add_i32 s46, s56, s6
	global_load_lds_dwordx4 v[152:153], off
	v_lshl_add_u64 v[152:153], s[44:45], 0, v[130:131]
	s_mov_b32 m0, s46
	s_nop 0
	global_load_lds_dwordx4 v[152:153], off
	v_lshl_add_u64 v[152:153], s[44:45], 0, v[134:135]
	s_add_i32 m0, s46, 0x2000
	s_nop 0
	global_load_lds_dwordx4 v[152:153], off
	v_lshl_add_u64 v[152:153], v[218:219], 0, s[16:17]
	s_mov_b32 m0, s37
	s_nop 0
	global_load_lds_dwordx4 v[152:153], off
	v_lshl_add_u64 v[152:153], v[220:221], 0, s[16:17]
	s_mov_b32 m0, s38
	s_nop 0
	global_load_lds_dwordx4 v[152:153], off
	s_waitcnt vmcnt(8)
	s_waitcnt lgkmcnt(0)
	s_barrier
	s_setprio 1
	s_waitcnt lgkmcnt(0)
	v_mfma_f32_16x16x32_bf16 v[92:95], v[144:147], v[184:187], v[92:95]
	v_mfma_f32_16x16x32_bf16 v[88:91], v[160:163], v[184:187], v[88:91]
	v_mfma_f32_16x16x32_bf16 v[84:87], v[144:147], v[192:195], v[84:87]
	v_mfma_f32_16x16x32_bf16 v[80:83], v[160:163], v[192:195], v[80:83]
	v_mfma_f32_16x16x32_bf16 v[68:71], v[144:147], v[200:203], v[68:71]
	v_mfma_f32_16x16x32_bf16 v[64:67], v[160:163], v[200:203], v[64:67]
	v_mfma_f32_16x16x32_bf16 v[56:59], v[144:147], v[208:211], v[56:59]
	v_mfma_f32_16x16x32_bf16 v[48:51], v[160:163], v[208:211], v[48:51]
	v_mfma_f32_16x16x32_bf16 v[92:95], v[148:151], v[188:191], v[92:95]
	v_mfma_f32_16x16x32_bf16 v[88:91], v[164:167], v[188:191], v[88:91]
	v_mfma_f32_16x16x32_bf16 v[84:87], v[148:151], v[196:199], v[84:87]
	v_mfma_f32_16x16x32_bf16 v[80:83], v[164:167], v[196:199], v[80:83]
	v_mfma_f32_16x16x32_bf16 v[68:71], v[148:151], v[204:207], v[68:71]
	v_mfma_f32_16x16x32_bf16 v[64:67], v[164:167], v[204:207], v[64:67]
	v_mfma_f32_16x16x32_bf16 v[56:59], v[148:151], v[212:215], v[56:59]
	v_mfma_f32_16x16x32_bf16 v[48:51], v[164:167], v[212:215], v[48:51]
	v_mfma_f32_16x16x32_bf16 v[28:31], v[168:171], v[184:187], v[28:31]
	v_mfma_f32_16x16x32_bf16 v[24:27], v[176:179], v[184:187], v[24:27]
	v_mfma_f32_16x16x32_bf16 v[20:23], v[168:171], v[192:195], v[20:23]
	v_mfma_f32_16x16x32_bf16 v[16:19], v[176:179], v[192:195], v[16:19]
	v_mfma_f32_16x16x32_bf16 v[12:15], v[168:171], v[200:203], v[12:15]
	v_mfma_f32_16x16x32_bf16 v[8:11], v[176:179], v[200:203], v[8:11]
	v_mfma_f32_16x16x32_bf16 v[4:7], v[168:171], v[208:211], v[4:7]
	v_mfma_f32_16x16x32_bf16 v[0:3], v[176:179], v[208:211], v[0:3]
	v_mfma_f32_16x16x32_bf16 v[28:31], v[172:175], v[188:191], v[28:31]
	v_mfma_f32_16x16x32_bf16 v[24:27], v[180:183], v[188:191], v[24:27]
	v_mfma_f32_16x16x32_bf16 v[20:23], v[172:175], v[196:199], v[20:23]
	v_mfma_f32_16x16x32_bf16 v[16:19], v[180:183], v[196:199], v[16:19]
	v_mfma_f32_16x16x32_bf16 v[12:15], v[172:175], v[204:207], v[12:15]
	v_mfma_f32_16x16x32_bf16 v[8:11], v[180:183], v[204:207], v[8:11]
	v_mfma_f32_16x16x32_bf16 v[4:7], v[172:175], v[212:215], v[4:7]
	v_mfma_f32_16x16x32_bf16 v[0:3], v[180:183], v[212:215], v[0:3]
	s_setprio 0
	s_barrier
	s_add_i32 s54, s54, 2
	s_add_u32 s52, s52, 0x100
	s_addc_u32 s53, s53, 0
	s_add_u32 s30, s30, 0x100
	s_addc_u32 s31, s31, 0
	s_cmp_gt_u32 s54, 13
	s_cbranch_scc0 .LBB0_1805
	s_and_b64 vcc, exec, s[18:19]
	s_cbranch_vccz .LBB0_1808
	s_barrier

.LBB0_1938:
	ds_read_b128 v[104:107], v233
	ds_read_b128 v[108:111], v233 offset:1024
	ds_read_b128 v[112:115], v233 offset:2048
	ds_read_b128 v[116:119], v233 offset:3072
	ds_read_b128 v[120:123], v234
	ds_read_b128 v[124:127], v234 offset:1024
	ds_read_b128 v[128:131], v234 offset:2048
	ds_read_b128 v[132:135], v234 offset:3072
	s_add_u32 s78, s28, 0xfffc0080
	s_addc_u32 s79, s29, -1
	s_cmp_eq_u32 s84, 12
	s_cselect_b32 s81, s73, s79
	s_cselect_b32 s80, s72, s78
	s_cselect_b32 s79, s71, s83
	s_cselect_b32 s78, s77, s82
	v_lshl_add_u64 v[208:209], s[28:29], 0, v[186:187]
	s_add_i32 m0, s42, 0xc000
	ds_read_b128 v[160:163], v235
	ds_read_b128 v[164:167], v235 offset:1024
	ds_read_b128 v[168:171], v235 offset:2048
	ds_read_b128 v[172:175], v235 offset:3072
	ds_read_b128 v[192:195], v235 offset:4096
	ds_read_b128 v[196:199], v235 offset:5120
	ds_read_b128 v[200:203], v235 offset:6144
	ds_read_b128 v[204:207], v235 offset:7168
	global_load_lds_dwordx4 v[208:209], off
	v_lshl_add_u64 v[208:209], s[28:29], 0, v[184:185]
	s_add_i32 m0, s42, 0xe000
	s_nop 0
	global_load_lds_dwordx4 v[208:209], off
	s_waitcnt vmcnt(8)
	s_waitcnt lgkmcnt(0)
	s_barrier
	s_setprio 1
	s_waitcnt lgkmcnt(0)
	v_mfma_f32_16x16x32_bf16 v[156:159], v[104:107], v[160:163], v[156:159]
	v_mfma_f32_16x16x32_bf16 v[60:63], v[112:115], v[160:163], v[60:63]
	v_mfma_f32_16x16x32_bf16 v[148:151], v[104:107], v[168:171], v[148:151]
	v_mfma_f32_16x16x32_bf16 v[52:55], v[112:115], v[168:171], v[52:55]
	v_mfma_f32_16x16x32_bf16 v[140:143], v[104:107], v[192:195], v[140:143]
	v_mfma_f32_16x16x32_bf16 v[44:47], v[112:115], v[192:195], v[44:47]
	v_mfma_f32_16x16x32_bf16 v[100:103], v[104:107], v[200:203], v[100:103]
	v_mfma_f32_16x16x32_bf16 v[36:39], v[112:115], v[200:203], v[36:39]
	v_mfma_f32_16x16x32_bf16 v[156:159], v[108:111], v[164:167], v[156:159]
	v_mfma_f32_16x16x32_bf16 v[60:63], v[116:119], v[164:167], v[60:63]
	v_mfma_f32_16x16x32_bf16 v[148:151], v[108:111], v[172:175], v[148:151]
	v_mfma_f32_16x16x32_bf16 v[52:55], v[116:119], v[172:175], v[52:55]
	v_mfma_f32_16x16x32_bf16 v[140:143], v[108:111], v[196:199], v[140:143]
	v_mfma_f32_16x16x32_bf16 v[44:47], v[116:119], v[196:199], v[44:47]
	v_mfma_f32_16x16x32_bf16 v[100:103], v[108:111], v[204:207], v[100:103]
	v_mfma_f32_16x16x32_bf16 v[36:39], v[116:119], v[204:207], v[36:39]
	v_mfma_f32_16x16x32_bf16 v[152:155], v[120:123], v[160:163], v[152:155]
	v_mfma_f32_16x16x32_bf16 v[56:59], v[128:131], v[160:163], v[56:59]
	v_mfma_f32_16x16x32_bf16 v[144:147], v[120:123], v[168:171], v[144:147]
	v_mfma_f32_16x16x32_bf16 v[48:51], v[128:131], v[168:171], v[48:51]
	v_mfma_f32_16x16x32_bf16 v[136:139], v[120:123], v[192:195], v[136:139]
	v_mfma_f32_16x16x32_bf16 v[40:43], v[128:131], v[192:195], v[40:43]
	v_mfma_f32_16x16x32_bf16 v[96:99], v[120:123], v[200:203], v[96:99]
	v_mfma_f32_16x16x32_bf16 v[32:35], v[128:131], v[200:203], v[32:35]
	v_mfma_f32_16x16x32_bf16 v[152:155], v[124:127], v[164:167], v[152:155]
	v_mfma_f32_16x16x32_bf16 v[56:59], v[132:135], v[164:167], v[56:59]
	v_mfma_f32_16x16x32_bf16 v[144:147], v[124:127], v[172:175], v[144:147]
	v_mfma_f32_16x16x32_bf16 v[48:51], v[132:135], v[172:175], v[48:51]
	v_mfma_f32_16x16x32_bf16 v[136:139], v[124:127], v[196:199], v[136:139]
	v_mfma_f32_16x16x32_bf16 v[40:43], v[132:135], v[196:199], v[40:43]
	v_mfma_f32_16x16x32_bf16 v[96:99], v[124:127], v[204:207], v[96:99]
	v_mfma_f32_16x16x32_bf16 v[32:35], v[132:135], v[204:207], v[32:35]
	s_setprio 0
	s_barrier
	s_add_i32 s85, s33, s41
	v_lshl_add_u64 v[208:209], s[78:79], 0, v[178:179]
	s_mov_b32 m0, s85
	ds_read_b128 v[160:163], v235 offset:16384
	ds_read_b128 v[164:167], v235 offset:17408
	ds_read_b128 v[168:171], v235 offset:18432
	ds_read_b128 v[172:175], v235 offset:19456
	ds_read_b128 v[192:195], v235 offset:20480
	ds_read_b128 v[196:199], v235 offset:21504
	ds_read_b128 v[200:203], v235 offset:22528
	ds_read_b128 v[204:207], v235 offset:23552
	global_load_lds_dwordx4 v[208:209], off
	s_add_i32 m0, s85, 0x2000
	s_add_u32 s86, s78, 0x40000
	v_lshl_add_u64 v[210:211], s[78:79], 0, v[182:183]
	s_addc_u32 s87, s79, 0
	s_add_i32 s85, s44, s41
	global_load_lds_dwordx4 v[210:211], off
	v_lshl_add_u64 v[212:213], s[86:87], 0, v[178:179]
	s_mov_b32 m0, s85
	v_lshl_add_u64 v[214:215], s[80:81], 0, v[180:181]
	global_load_lds_dwordx4 v[212:213], off
	v_lshl_add_u64 v[212:213], s[86:87], 0, v[182:183]
	s_add_i32 m0, s85, 0x2000
	s_nop 0
	global_load_lds_dwordx4 v[212:213], off
	v_lshl_add_u64 v[212:213], s[80:81], 0, v[176:177]
	s_mov_b32 m0, s42
	s_nop 0
	global_load_lds_dwordx4 v[212:213], off
	s_mov_b32 m0, s43
	s_nop 0
	global_load_lds_dwordx4 v[214:215], off
	s_waitcnt vmcnt(8)
	s_waitcnt lgkmcnt(0)
	s_barrier
	s_setprio 1
	s_waitcnt lgkmcnt(0)
	v_mfma_f32_16x16x32_bf16 v[92:95], v[104:107], v[160:163], v[92:95]
	v_mfma_f32_16x16x32_bf16 v[28:31], v[112:115], v[160:163], v[28:31]
	v_mfma_f32_16x16x32_bf16 v[84:87], v[104:107], v[168:171], v[84:87]
	v_mfma_f32_16x16x32_bf16 v[20:23], v[112:115], v[168:171], v[20:23]
	v_mfma_f32_16x16x32_bf16 v[76:79], v[104:107], v[192:195], v[76:79]
	v_mfma_f32_16x16x32_bf16 v[12:15], v[112:115], v[192:195], v[12:15]
	v_mfma_f32_16x16x32_bf16 v[68:71], v[104:107], v[200:203], v[68:71]
	v_mfma_f32_16x16x32_bf16 v[4:7], v[112:115], v[200:203], v[4:7]
	v_mfma_f32_16x16x32_bf16 v[92:95], v[108:111], v[164:167], v[92:95]
	v_mfma_f32_16x16x32_bf16 v[28:31], v[116:119], v[164:167], v[28:31]
	v_mfma_f32_16x16x32_bf16 v[84:87], v[108:111], v[172:175], v[84:87]
	v_mfma_f32_16x16x32_bf16 v[20:23], v[116:119], v[172:175], v[20:23]
	v_mfma_f32_16x16x32_bf16 v[76:79], v[108:111], v[196:199], v[76:79]
	v_mfma_f32_16x16x32_bf16 v[12:15], v[116:119], v[196:199], v[12:15]
	v_mfma_f32_16x16x32_bf16 v[68:71], v[108:111], v[204:207], v[68:71]
	v_mfma_f32_16x16x32_bf16 v[4:7], v[116:119], v[204:207], v[4:7]
	v_mfma_f32_16x16x32_bf16 v[88:91], v[120:123], v[160:163], v[88:91]
	v_mfma_f32_16x16x32_bf16 v[24:27], v[128:131], v[160:163], v[24:27]
	v_mfma_f32_16x16x32_bf16 v[80:83], v[120:123], v[168:171], v[80:83]
	v_mfma_f32_16x16x32_bf16 v[16:19], v[128:131], v[168:171], v[16:19]
	v_mfma_f32_16x16x32_bf16 v[72:75], v[120:123], v[192:195], v[72:75]
	v_mfma_f32_16x16x32_bf16 v[8:11], v[128:131], v[192:195], v[8:11]
	v_mfma_f32_16x16x32_bf16 v[64:67], v[120:123], v[200:203], v[64:67]
	v_mfma_f32_16x16x32_bf16 v[0:3], v[128:131], v[200:203], v[0:3]
	v_mfma_f32_16x16x32_bf16 v[88:91], v[124:127], v[164:167], v[88:91]
	v_mfma_f32_16x16x32_bf16 v[24:27], v[132:135], v[164:167], v[24:27]
	v_mfma_f32_16x16x32_bf16 v[80:83], v[124:127], v[172:175], v[80:83]
	v_mfma_f32_16x16x32_bf16 v[16:19], v[132:135], v[172:175], v[16:19]
	v_mfma_f32_16x16x32_bf16 v[72:75], v[124:127], v[196:199], v[72:75]
	v_mfma_f32_16x16x32_bf16 v[8:11], v[132:135], v[196:199], v[8:11]
	v_mfma_f32_16x16x32_bf16 v[64:67], v[124:127], v[204:207], v[64:67]
	v_mfma_f32_16x16x32_bf16 v[0:3], v[132:135], v[204:207], v[0:3]
	s_setprio 0
	s_barrier
	s_add_i32 s85, 0, 0x18000
	s_add_i32 s86, 0, 0x1c000
	v_add_u32_e32 v116, s85, v221
	v_add_u32_e32 v132, s86, v221
	ds_read_b128 v[104:107], v116
	ds_read_b128 v[108:111], v116 offset:1024
	ds_read_b128 v[112:115], v116 offset:2048
	ds_read_b128 v[116:119], v116 offset:3072
	ds_read_b128 v[120:123], v132
	ds_read_b128 v[124:127], v132 offset:1024
	ds_read_b128 v[128:131], v132 offset:2048
	ds_read_b128 v[132:135], v132 offset:3072
	s_add_u32 s80, s80, 0x40000
	s_addc_u32 s81, s81, 0
	s_mov_b32 m0, s8
	v_lshl_add_u64 v[216:217], s[80:81], 0, v[176:177]
	ds_read_b128 v[160:163], v235 offset:32768
	ds_read_b128 v[164:167], v235 offset:33792
	ds_read_b128 v[168:171], v235 offset:34816
	ds_read_b128 v[172:175], v235 offset:35840
	ds_read_b128 v[192:195], v235 offset:36864
	ds_read_b128 v[196:199], v235 offset:37888
	ds_read_b128 v[200:203], v235 offset:38912
	ds_read_b128 v[204:207], v235 offset:39936
	global_load_lds_dwordx4 v[216:217], off
	v_lshl_add_u64 v[216:217], s[80:81], 0, v[180:181]
	s_mov_b32 m0, s9
	s_nop 0
	global_load_lds_dwordx4 v[216:217], off
	s_waitcnt vmcnt(8)
	s_waitcnt lgkmcnt(0)
	s_barrier
	s_setprio 1
	s_waitcnt lgkmcnt(0)
	v_mfma_f32_16x16x32_bf16 v[156:159], v[104:107], v[160:163], v[156:159]
	v_mfma_f32_16x16x32_bf16 v[60:63], v[112:115], v[160:163], v[60:63]
	v_mfma_f32_16x16x32_bf16 v[148:151], v[104:107], v[168:171], v[148:151]
	v_mfma_f32_16x16x32_bf16 v[52:55], v[112:115], v[168:171], v[52:55]
	v_mfma_f32_16x16x32_bf16 v[140:143], v[104:107], v[192:195], v[140:143]
	v_mfma_f32_16x16x32_bf16 v[44:47], v[112:115], v[192:195], v[44:47]
	v_mfma_f32_16x16x32_bf16 v[100:103], v[104:107], v[200:203], v[100:103]
	v_mfma_f32_16x16x32_bf16 v[36:39], v[112:115], v[200:203], v[36:39]
	v_mfma_f32_16x16x32_bf16 v[156:159], v[108:111], v[164:167], v[156:159]
	v_mfma_f32_16x16x32_bf16 v[60:63], v[116:119], v[164:167], v[60:63]
	v_mfma_f32_16x16x32_bf16 v[148:151], v[108:111], v[172:175], v[148:151]
	v_mfma_f32_16x16x32_bf16 v[52:55], v[116:119], v[172:175], v[52:55]
	v_mfma_f32_16x16x32_bf16 v[140:143], v[108:111], v[196:199], v[140:143]
	v_mfma_f32_16x16x32_bf16 v[44:47], v[116:119], v[196:199], v[44:47]
	v_mfma_f32_16x16x32_bf16 v[100:103], v[108:111], v[204:207], v[100:103]
	v_mfma_f32_16x16x32_bf16 v[36:39], v[116:119], v[204:207], v[36:39]
	v_mfma_f32_16x16x32_bf16 v[152:155], v[120:123], v[160:163], v[152:155]
	v_mfma_f32_16x16x32_bf16 v[56:59], v[128:131], v[160:163], v[56:59]
	v_mfma_f32_16x16x32_bf16 v[144:147], v[120:123], v[168:171], v[144:147]
	v_mfma_f32_16x16x32_bf16 v[48:51], v[128:131], v[168:171], v[48:51]
	v_mfma_f32_16x16x32_bf16 v[136:139], v[120:123], v[192:195], v[136:139]
	v_mfma_f32_16x16x32_bf16 v[40:43], v[128:131], v[192:195], v[40:43]
	v_mfma_f32_16x16x32_bf16 v[96:99], v[120:123], v[200:203], v[96:99]
	v_mfma_f32_16x16x32_bf16 v[32:35], v[128:131], v[200:203], v[32:35]
	v_mfma_f32_16x16x32_bf16 v[152:155], v[124:127], v[164:167], v[152:155]
	v_mfma_f32_16x16x32_bf16 v[56:59], v[132:135], v[164:167], v[56:59]
	v_mfma_f32_16x16x32_bf16 v[144:147], v[124:127], v[172:175], v[144:147]
	v_mfma_f32_16x16x32_bf16 v[48:51], v[132:135], v[172:175], v[48:51]
	v_mfma_f32_16x16x32_bf16 v[136:139], v[124:127], v[196:199], v[136:139]
	v_mfma_f32_16x16x32_bf16 v[40:43], v[132:135], v[196:199], v[40:43]
	v_mfma_f32_16x16x32_bf16 v[96:99], v[124:127], v[204:207], v[96:99]
	v_mfma_f32_16x16x32_bf16 v[32:35], v[132:135], v[204:207], v[32:35]
	s_setprio 0
	s_barrier
	s_add_i32 s80, s85, s41
	v_lshl_add_u64 v[208:209], v[208:209], 0, s[52:53]
	s_mov_b32 m0, s80
	ds_read_b128 v[160:163], v235 offset:49152
	ds_read_b128 v[164:167], v235 offset:50176
	ds_read_b128 v[168:171], v235 offset:51200
	ds_read_b128 v[172:175], v235 offset:52224
	ds_read_b128 v[192:195], v235 offset:53248
	ds_read_b128 v[196:199], v235 offset:54272
	ds_read_b128 v[200:203], v235 offset:55296
	ds_read_b128 v[204:207], v235 offset:56320
	global_load_lds_dwordx4 v[208:209], off
	s_add_i32 m0, s80, 0x2000
	s_add_u32 s78, s78, 0x40080
	v_lshl_add_u64 v[208:209], v[210:211], 0, s[52:53]
	s_addc_u32 s79, s79, 0
	s_add_i32 s80, s86, s41
	global_load_lds_dwordx4 v[208:209], off
	v_lshl_add_u64 v[208:209], s[78:79], 0, v[178:179]
	s_mov_b32 m0, s80
	s_nop 0
	global_load_lds_dwordx4 v[208:209], off
	v_lshl_add_u64 v[208:209], s[78:79], 0, v[182:183]
	s_add_i32 m0, s80, 0x2000
	s_nop 0
	global_load_lds_dwordx4 v[208:209], off
	v_lshl_add_u64 v[208:209], v[212:213], 0, s[52:53]
	s_mov_b32 m0, s5
	s_nop 0
	global_load_lds_dwordx4 v[208:209], off
	v_lshl_add_u64 v[208:209], v[214:215], 0, s[52:53]
	s_mov_b32 m0, s6
	s_nop 0
	global_load_lds_dwordx4 v[208:209], off
	s_waitcnt vmcnt(8)
	s_waitcnt lgkmcnt(0)
	s_barrier
	s_setprio 1
	s_waitcnt lgkmcnt(0)
	v_mfma_f32_16x16x32_bf16 v[92:95], v[104:107], v[160:163], v[92:95]
	v_mfma_f32_16x16x32_bf16 v[28:31], v[112:115], v[160:163], v[28:31]
	v_mfma_f32_16x16x32_bf16 v[84:87], v[104:107], v[168:171], v[84:87]
	v_mfma_f32_16x16x32_bf16 v[20:23], v[112:115], v[168:171], v[20:23]
	v_mfma_f32_16x16x32_bf16 v[76:79], v[104:107], v[192:195], v[76:79]
	v_mfma_f32_16x16x32_bf16 v[12:15], v[112:115], v[192:195], v[12:15]
	v_mfma_f32_16x16x32_bf16 v[68:71], v[104:107], v[200:203], v[68:71]
	v_mfma_f32_16x16x32_bf16 v[4:7], v[112:115], v[200:203], v[4:7]
	v_mfma_f32_16x16x32_bf16 v[92:95], v[108:111], v[164:167], v[92:95]
	v_mfma_f32_16x16x32_bf16 v[28:31], v[116:119], v[164:167], v[28:31]
	v_mfma_f32_16x16x32_bf16 v[84:87], v[108:111], v[172:175], v[84:87]
	v_mfma_f32_16x16x32_bf16 v[20:23], v[116:119], v[172:175], v[20:23]
	v_mfma_f32_16x16x32_bf16 v[76:79], v[108:111], v[196:199], v[76:79]
	v_mfma_f32_16x16x32_bf16 v[12:15], v[116:119], v[196:199], v[12:15]
	v_mfma_f32_16x16x32_bf16 v[68:71], v[108:111], v[204:207], v[68:71]
	v_mfma_f32_16x16x32_bf16 v[4:7], v[116:119], v[204:207], v[4:7]
	v_mfma_f32_16x16x32_bf16 v[88:91], v[120:123], v[160:163], v[88:91]
	v_mfma_f32_16x16x32_bf16 v[24:27], v[128:131], v[160:163], v[24:27]
	v_mfma_f32_16x16x32_bf16 v[80:83], v[120:123], v[168:171], v[80:83]
	v_mfma_f32_16x16x32_bf16 v[16:19], v[128:131], v[168:171], v[16:19]
	v_mfma_f32_16x16x32_bf16 v[72:75], v[120:123], v[192:195], v[72:75]
	v_mfma_f32_16x16x32_bf16 v[8:11], v[128:131], v[192:195], v[8:11]
	v_mfma_f32_16x16x32_bf16 v[64:67], v[120:123], v[200:203], v[64:67]
	v_mfma_f32_16x16x32_bf16 v[0:3], v[128:131], v[200:203], v[0:3]
	v_mfma_f32_16x16x32_bf16 v[88:91], v[124:127], v[164:167], v[88:91]
	v_mfma_f32_16x16x32_bf16 v[24:27], v[132:135], v[164:167], v[24:27]
	v_mfma_f32_16x16x32_bf16 v[80:83], v[124:127], v[172:175], v[80:83]
	v_mfma_f32_16x16x32_bf16 v[16:19], v[132:135], v[172:175], v[16:19]
	v_mfma_f32_16x16x32_bf16 v[72:75], v[124:127], v[196:199], v[72:75]
	v_mfma_f32_16x16x32_bf16 v[8:11], v[132:135], v[196:199], v[8:11]
	v_mfma_f32_16x16x32_bf16 v[64:67], v[124:127], v[204:207], v[64:67]
	v_mfma_f32_16x16x32_bf16 v[0:3], v[132:135], v[204:207], v[0:3]
	s_setprio 0
	s_barrier
	s_add_i32 s84, s84, 2
	s_add_u32 s82, s82, 0x100
	s_addc_u32 s83, s83, 0
	s_add_u32 s28, s28, 0x100
	s_addc_u32 s29, s29, 0
	s_cmp_gt_u32 s84, 13
	s_cbranch_scc0 .LBB0_1938
	s_and_b64 vcc, exec, s[54:55]
	s_cbranch_vccz .LBB0_1941
	s_barrier

.LBB0_2056:
	ds_read_b128 v[144:147], v157
	ds_read_b128 v[148:151], v157 offset:1024
	ds_read_b128 v[160:163], v157 offset:2048
	ds_read_b128 v[164:167], v157 offset:3072
	ds_read_b128 v[168:171], v158
	ds_read_b128 v[172:175], v158 offset:1024
	ds_read_b128 v[176:179], v158 offset:2048
	ds_read_b128 v[180:183], v158 offset:3072
	s_add_u32 s26, s24, 0x100
	s_addc_u32 s27, s25, 0
	s_cmp_eq_u32 s52, 40
	s_cselect_b32 s31, s13, s27
	s_cselect_b32 s30, s12, s26
	s_cselect_b32 s29, s23, s51
	s_cselect_b32 s28, s22, s50
	v_lshl_add_u64 v[152:153], s[24:25], 0, v[138:139]
	s_add_i32 m0, s7, 0xc000
	ds_read_b128 v[184:187], v159
	ds_read_b128 v[188:191], v159 offset:1024
	ds_read_b128 v[192:195], v159 offset:2048
	ds_read_b128 v[196:199], v159 offset:3072
	ds_read_b128 v[200:203], v159 offset:4096
	ds_read_b128 v[204:207], v159 offset:5120
	ds_read_b128 v[208:211], v159 offset:6144
	ds_read_b128 v[212:215], v159 offset:7168
	global_load_lds_dwordx4 v[152:153], off
	v_lshl_add_u64 v[152:153], s[24:25], 0, v[136:137]
	s_add_i32 m0, s7, 0xe000
	s_nop 0
	global_load_lds_dwordx4 v[152:153], off
	s_waitcnt vmcnt(8)
	s_waitcnt lgkmcnt(0)
	s_barrier
	s_setprio 1
	s_waitcnt lgkmcnt(0)
	v_mfma_f32_16x16x32_bf16 v[124:127], v[144:147], v[184:187], v[124:127]
	v_mfma_f32_16x16x32_bf16 v[120:123], v[160:163], v[184:187], v[120:123]
	v_mfma_f32_16x16x32_bf16 v[116:119], v[144:147], v[192:195], v[116:119]
	v_mfma_f32_16x16x32_bf16 v[112:115], v[160:163], v[192:195], v[112:115]
	v_mfma_f32_16x16x32_bf16 v[108:111], v[144:147], v[200:203], v[108:111]
	v_mfma_f32_16x16x32_bf16 v[104:107], v[160:163], v[200:203], v[104:107]
	v_mfma_f32_16x16x32_bf16 v[100:103], v[144:147], v[208:211], v[100:103]
	v_mfma_f32_16x16x32_bf16 v[96:99], v[160:163], v[208:211], v[96:99]
	v_mfma_f32_16x16x32_bf16 v[124:127], v[148:151], v[188:191], v[124:127]
	v_mfma_f32_16x16x32_bf16 v[120:123], v[164:167], v[188:191], v[120:123]
	v_mfma_f32_16x16x32_bf16 v[116:119], v[148:151], v[196:199], v[116:119]
	v_mfma_f32_16x16x32_bf16 v[112:115], v[164:167], v[196:199], v[112:115]
	v_mfma_f32_16x16x32_bf16 v[108:111], v[148:151], v[204:207], v[108:111]
	v_mfma_f32_16x16x32_bf16 v[104:107], v[164:167], v[204:207], v[104:107]
	v_mfma_f32_16x16x32_bf16 v[100:103], v[148:151], v[212:215], v[100:103]
	v_mfma_f32_16x16x32_bf16 v[96:99], v[164:167], v[212:215], v[96:99]
	v_mfma_f32_16x16x32_bf16 v[76:79], v[168:171], v[184:187], v[76:79]
	v_mfma_f32_16x16x32_bf16 v[72:75], v[176:179], v[184:187], v[72:75]
	v_mfma_f32_16x16x32_bf16 v[60:63], v[168:171], v[192:195], v[60:63]
	v_mfma_f32_16x16x32_bf16 v[52:55], v[176:179], v[192:195], v[52:55]
	v_mfma_f32_16x16x32_bf16 v[44:47], v[168:171], v[200:203], v[44:47]
	v_mfma_f32_16x16x32_bf16 v[40:43], v[176:179], v[200:203], v[40:43]
	v_mfma_f32_16x16x32_bf16 v[36:39], v[168:171], v[208:211], v[36:39]
	v_mfma_f32_16x16x32_bf16 v[32:35], v[176:179], v[208:211], v[32:35]
	v_mfma_f32_16x16x32_bf16 v[76:79], v[172:175], v[188:191], v[76:79]
	v_mfma_f32_16x16x32_bf16 v[72:75], v[180:183], v[188:191], v[72:75]
	v_mfma_f32_16x16x32_bf16 v[60:63], v[172:175], v[196:199], v[60:63]
	v_mfma_f32_16x16x32_bf16 v[52:55], v[180:183], v[196:199], v[52:55]
	v_mfma_f32_16x16x32_bf16 v[44:47], v[172:175], v[204:207], v[44:47]
	v_mfma_f32_16x16x32_bf16 v[40:43], v[180:183], v[204:207], v[40:43]
	v_mfma_f32_16x16x32_bf16 v[36:39], v[172:175], v[212:215], v[36:39]
	v_mfma_f32_16x16x32_bf16 v[32:35], v[180:183], v[212:215], v[32:35]
	s_setprio 0
	s_barrier
	s_add_i32 s24, s41, s6
	v_lshl_add_u64 v[152:153], s[28:29], 0, v[130:131]
	s_mov_b32 m0, s24
	ds_read_b128 v[184:187], v159 offset:16384
	ds_read_b128 v[188:191], v159 offset:17408
	ds_read_b128 v[192:195], v159 offset:18432
	ds_read_b128 v[196:199], v159 offset:19456
	ds_read_b128 v[200:203], v159 offset:20480
	ds_read_b128 v[204:207], v159 offset:21504
	ds_read_b128 v[208:211], v159 offset:22528
	ds_read_b128 v[212:215], v159 offset:23552
	global_load_lds_dwordx4 v[152:153], off
	s_add_i32 m0, s24, 0x2000
	s_add_u32 s24, s28, 0xb0000
	v_lshl_add_u64 v[216:217], s[28:29], 0, v[134:135]
	s_addc_u32 s25, s29, 0
	s_add_i32 s53, s42, s6
	global_load_lds_dwordx4 v[216:217], off
	v_lshl_add_u64 v[218:219], s[24:25], 0, v[130:131]
	s_mov_b32 m0, s53
	v_lshl_add_u64 v[220:221], s[30:31], 0, v[132:133]
	global_load_lds_dwordx4 v[218:219], off
	v_lshl_add_u64 v[218:219], s[24:25], 0, v[134:135]
	s_add_i32 m0, s53, 0x2000
	s_nop 0
	global_load_lds_dwordx4 v[218:219], off
	v_lshl_add_u64 v[218:219], s[30:31], 0, v[128:129]
	s_mov_b32 m0, s7
	s_nop 0
	global_load_lds_dwordx4 v[218:219], off
	s_mov_b32 m0, s8
	s_nop 0
	global_load_lds_dwordx4 v[220:221], off
	s_waitcnt vmcnt(8)
	s_waitcnt lgkmcnt(0)
	s_barrier
	s_setprio 1
	s_waitcnt lgkmcnt(0)
	v_mfma_f32_16x16x32_bf16 v[92:95], v[144:147], v[184:187], v[92:95]
	v_mfma_f32_16x16x32_bf16 v[88:91], v[160:163], v[184:187], v[88:91]
	v_mfma_f32_16x16x32_bf16 v[84:87], v[144:147], v[192:195], v[84:87]
	v_mfma_f32_16x16x32_bf16 v[80:83], v[160:163], v[192:195], v[80:83]
	v_mfma_f32_16x16x32_bf16 v[68:71], v[144:147], v[200:203], v[68:71]
	v_mfma_f32_16x16x32_bf16 v[64:67], v[160:163], v[200:203], v[64:67]
	v_mfma_f32_16x16x32_bf16 v[56:59], v[144:147], v[208:211], v[56:59]
	v_mfma_f32_16x16x32_bf16 v[48:51], v[160:163], v[208:211], v[48:51]
	v_mfma_f32_16x16x32_bf16 v[92:95], v[148:151], v[188:191], v[92:95]
	v_mfma_f32_16x16x32_bf16 v[88:91], v[164:167], v[188:191], v[88:91]
	v_mfma_f32_16x16x32_bf16 v[84:87], v[148:151], v[196:199], v[84:87]
	v_mfma_f32_16x16x32_bf16 v[80:83], v[164:167], v[196:199], v[80:83]
	v_mfma_f32_16x16x32_bf16 v[68:71], v[148:151], v[204:207], v[68:71]
	v_mfma_f32_16x16x32_bf16 v[64:67], v[164:167], v[204:207], v[64:67]
	v_mfma_f32_16x16x32_bf16 v[56:59], v[148:151], v[212:215], v[56:59]
	v_mfma_f32_16x16x32_bf16 v[48:51], v[164:167], v[212:215], v[48:51]
	v_mfma_f32_16x16x32_bf16 v[28:31], v[168:171], v[184:187], v[28:31]
	v_mfma_f32_16x16x32_bf16 v[24:27], v[176:179], v[184:187], v[24:27]
	v_mfma_f32_16x16x32_bf16 v[20:23], v[168:171], v[192:195], v[20:23]
	v_mfma_f32_16x16x32_bf16 v[16:19], v[176:179], v[192:195], v[16:19]
	v_mfma_f32_16x16x32_bf16 v[12:15], v[168:171], v[200:203], v[12:15]
	v_mfma_f32_16x16x32_bf16 v[8:11], v[176:179], v[200:203], v[8:11]
	v_mfma_f32_16x16x32_bf16 v[4:7], v[168:171], v[208:211], v[4:7]
	v_mfma_f32_16x16x32_bf16 v[0:3], v[176:179], v[208:211], v[0:3]
	v_mfma_f32_16x16x32_bf16 v[28:31], v[172:175], v[188:191], v[28:31]
	v_mfma_f32_16x16x32_bf16 v[24:27], v[180:183], v[188:191], v[24:27]
	v_mfma_f32_16x16x32_bf16 v[20:23], v[172:175], v[196:199], v[20:23]
	v_mfma_f32_16x16x32_bf16 v[16:19], v[180:183], v[196:199], v[16:19]
	v_mfma_f32_16x16x32_bf16 v[12:15], v[172:175], v[204:207], v[12:15]
	v_mfma_f32_16x16x32_bf16 v[8:11], v[180:183], v[204:207], v[8:11]
	v_mfma_f32_16x16x32_bf16 v[4:7], v[172:175], v[212:215], v[4:7]
	v_mfma_f32_16x16x32_bf16 v[0:3], v[180:183], v[212:215], v[0:3]
	s_setprio 0
	s_barrier
	s_add_i32 s53, 0, 0x18000
	s_add_i32 s54, 0, 0x1c000
	v_add_u32_e32 v164, s53, v155
	v_add_u32_e32 v180, s54, v155
	ds_read_b128 v[144:147], v164
	ds_read_b128 v[148:151], v164 offset:1024
	ds_read_b128 v[160:163], v164 offset:2048
	ds_read_b128 v[164:167], v164 offset:3072
	ds_read_b128 v[168:171], v180
	ds_read_b128 v[172:175], v180 offset:1024
	ds_read_b128 v[176:179], v180 offset:2048
	ds_read_b128 v[180:183], v180 offset:3072
	s_add_u32 s24, s30, 0xb0000
	s_addc_u32 s25, s31, 0
	s_mov_b32 m0, s9
	v_lshl_add_u64 v[222:223], s[24:25], 0, v[128:129]
	ds_read_b128 v[184:187], v159 offset:32768
	ds_read_b128 v[188:191], v159 offset:33792
	ds_read_b128 v[192:195], v159 offset:34816
	ds_read_b128 v[196:199], v159 offset:35840
	ds_read_b128 v[200:203], v159 offset:36864
	ds_read_b128 v[204:207], v159 offset:37888
	ds_read_b128 v[208:211], v159 offset:38912
	ds_read_b128 v[212:215], v159 offset:39936
	global_load_lds_dwordx4 v[222:223], off
	v_lshl_add_u64 v[222:223], s[24:25], 0, v[132:133]
	s_mov_b32 m0, s33
	s_nop 0
	global_load_lds_dwordx4 v[222:223], off
	s_waitcnt vmcnt(8)
	s_waitcnt lgkmcnt(0)
	s_barrier
	s_setprio 1
	s_waitcnt lgkmcnt(0)
	v_mfma_f32_16x16x32_bf16 v[124:127], v[144:147], v[184:187], v[124:127]
	v_mfma_f32_16x16x32_bf16 v[120:123], v[160:163], v[184:187], v[120:123]
	v_mfma_f32_16x16x32_bf16 v[116:119], v[144:147], v[192:195], v[116:119]
	v_mfma_f32_16x16x32_bf16 v[112:115], v[160:163], v[192:195], v[112:115]
	v_mfma_f32_16x16x32_bf16 v[108:111], v[144:147], v[200:203], v[108:111]
	v_mfma_f32_16x16x32_bf16 v[104:107], v[160:163], v[200:203], v[104:107]
	v_mfma_f32_16x16x32_bf16 v[100:103], v[144:147], v[208:211], v[100:103]
	v_mfma_f32_16x16x32_bf16 v[96:99], v[160:163], v[208:211], v[96:99]
	v_mfma_f32_16x16x32_bf16 v[124:127], v[148:151], v[188:191], v[124:127]
	v_mfma_f32_16x16x32_bf16 v[120:123], v[164:167], v[188:191], v[120:123]
	v_mfma_f32_16x16x32_bf16 v[116:119], v[148:151], v[196:199], v[116:119]
	v_mfma_f32_16x16x32_bf16 v[112:115], v[164:167], v[196:199], v[112:115]
	v_mfma_f32_16x16x32_bf16 v[108:111], v[148:151], v[204:207], v[108:111]
	v_mfma_f32_16x16x32_bf16 v[104:107], v[164:167], v[204:207], v[104:107]
	v_mfma_f32_16x16x32_bf16 v[100:103], v[148:151], v[212:215], v[100:103]
	v_mfma_f32_16x16x32_bf16 v[96:99], v[164:167], v[212:215], v[96:99]
	v_mfma_f32_16x16x32_bf16 v[76:79], v[168:171], v[184:187], v[76:79]
	v_mfma_f32_16x16x32_bf16 v[72:75], v[176:179], v[184:187], v[72:75]
	v_mfma_f32_16x16x32_bf16 v[60:63], v[168:171], v[192:195], v[60:63]
	v_mfma_f32_16x16x32_bf16 v[52:55], v[176:179], v[192:195], v[52:55]
	v_mfma_f32_16x16x32_bf16 v[44:47], v[168:171], v[200:203], v[44:47]
	v_mfma_f32_16x16x32_bf16 v[40:43], v[176:179], v[200:203], v[40:43]
	v_mfma_f32_16x16x32_bf16 v[36:39], v[168:171], v[208:211], v[36:39]
	v_mfma_f32_16x16x32_bf16 v[32:35], v[176:179], v[208:211], v[32:35]
	v_mfma_f32_16x16x32_bf16 v[76:79], v[172:175], v[188:191], v[76:79]
	v_mfma_f32_16x16x32_bf16 v[72:75], v[180:183], v[188:191], v[72:75]
	v_mfma_f32_16x16x32_bf16 v[60:63], v[172:175], v[196:199], v[60:63]
	v_mfma_f32_16x16x32_bf16 v[52:55], v[180:183], v[196:199], v[52:55]
	v_mfma_f32_16x16x32_bf16 v[44:47], v[172:175], v[204:207], v[44:47]
	v_mfma_f32_16x16x32_bf16 v[40:43], v[180:183], v[204:207], v[40:43]
	v_mfma_f32_16x16x32_bf16 v[36:39], v[172:175], v[212:215], v[36:39]
	v_mfma_f32_16x16x32_bf16 v[32:35], v[180:183], v[212:215], v[32:35]
	s_setprio 0
	s_barrier
	s_add_i32 s24, s53, s6
	v_lshl_add_u64 v[152:153], v[152:153], 0, s[18:19]
	s_mov_b32 m0, s24
	ds_read_b128 v[184:187], v159 offset:49152
	ds_read_b128 v[188:191], v159 offset:50176
	ds_read_b128 v[192:195], v159 offset:51200
	ds_read_b128 v[196:199], v159 offset:52224
	ds_read_b128 v[200:203], v159 offset:53248
	ds_read_b128 v[204:207], v159 offset:54272
	ds_read_b128 v[208:211], v159 offset:55296
	ds_read_b128 v[212:215], v159 offset:56320
	global_load_lds_dwordx4 v[152:153], off
	s_add_i32 m0, s24, 0x2000
	s_add_u32 s24, s28, 0xb0080
	v_lshl_add_u64 v[152:153], v[216:217], 0, s[18:19]
	s_addc_u32 s25, s29, 0
	s_add_i32 s28, s54, s6
	global_load_lds_dwordx4 v[152:153], off
	v_lshl_add_u64 v[152:153], s[24:25], 0, v[130:131]
	s_mov_b32 m0, s28
	s_nop 0
	global_load_lds_dwordx4 v[152:153], off
	v_lshl_add_u64 v[152:153], s[24:25], 0, v[134:135]
	s_add_i32 m0, s28, 0x2000
	s_nop 0
	global_load_lds_dwordx4 v[152:153], off
	v_lshl_add_u64 v[152:153], v[218:219], 0, s[18:19]
	s_mov_b32 m0, s37
	s_nop 0
	global_load_lds_dwordx4 v[152:153], off
	v_lshl_add_u64 v[152:153], v[220:221], 0, s[18:19]
	s_mov_b32 m0, s38
	s_nop 0
	global_load_lds_dwordx4 v[152:153], off
	s_waitcnt vmcnt(8)
	s_waitcnt lgkmcnt(0)
	s_barrier
	s_setprio 1
	s_waitcnt lgkmcnt(0)
	v_mfma_f32_16x16x32_bf16 v[92:95], v[144:147], v[184:187], v[92:95]
	v_mfma_f32_16x16x32_bf16 v[88:91], v[160:163], v[184:187], v[88:91]
	v_mfma_f32_16x16x32_bf16 v[84:87], v[144:147], v[192:195], v[84:87]
	v_mfma_f32_16x16x32_bf16 v[80:83], v[160:163], v[192:195], v[80:83]
	v_mfma_f32_16x16x32_bf16 v[68:71], v[144:147], v[200:203], v[68:71]
	v_mfma_f32_16x16x32_bf16 v[64:67], v[160:163], v[200:203], v[64:67]
	v_mfma_f32_16x16x32_bf16 v[56:59], v[144:147], v[208:211], v[56:59]
	v_mfma_f32_16x16x32_bf16 v[48:51], v[160:163], v[208:211], v[48:51]
	v_mfma_f32_16x16x32_bf16 v[92:95], v[148:151], v[188:191], v[92:95]
	v_mfma_f32_16x16x32_bf16 v[88:91], v[164:167], v[188:191], v[88:91]
	v_mfma_f32_16x16x32_bf16 v[84:87], v[148:151], v[196:199], v[84:87]
	v_mfma_f32_16x16x32_bf16 v[80:83], v[164:167], v[196:199], v[80:83]
	v_mfma_f32_16x16x32_bf16 v[68:71], v[148:151], v[204:207], v[68:71]
	v_mfma_f32_16x16x32_bf16 v[64:67], v[164:167], v[204:207], v[64:67]
	v_mfma_f32_16x16x32_bf16 v[56:59], v[148:151], v[212:215], v[56:59]
	v_mfma_f32_16x16x32_bf16 v[48:51], v[164:167], v[212:215], v[48:51]
	v_mfma_f32_16x16x32_bf16 v[28:31], v[168:171], v[184:187], v[28:31]
	v_mfma_f32_16x16x32_bf16 v[24:27], v[176:179], v[184:187], v[24:27]
	v_mfma_f32_16x16x32_bf16 v[20:23], v[168:171], v[192:195], v[20:23]
	v_mfma_f32_16x16x32_bf16 v[16:19], v[176:179], v[192:195], v[16:19]
	v_mfma_f32_16x16x32_bf16 v[12:15], v[168:171], v[200:203], v[12:15]
	v_mfma_f32_16x16x32_bf16 v[8:11], v[176:179], v[200:203], v[8:11]
	v_mfma_f32_16x16x32_bf16 v[4:7], v[168:171], v[208:211], v[4:7]
	v_mfma_f32_16x16x32_bf16 v[0:3], v[176:179], v[208:211], v[0:3]
	v_mfma_f32_16x16x32_bf16 v[28:31], v[172:175], v[188:191], v[28:31]
	v_mfma_f32_16x16x32_bf16 v[24:27], v[180:183], v[188:191], v[24:27]
	v_mfma_f32_16x16x32_bf16 v[20:23], v[172:175], v[196:199], v[20:23]
	v_mfma_f32_16x16x32_bf16 v[16:19], v[180:183], v[196:199], v[16:19]
	v_mfma_f32_16x16x32_bf16 v[12:15], v[172:175], v[204:207], v[12:15]
	v_mfma_f32_16x16x32_bf16 v[8:11], v[180:183], v[204:207], v[8:11]
	v_mfma_f32_16x16x32_bf16 v[4:7], v[172:175], v[212:215], v[4:7]
	v_mfma_f32_16x16x32_bf16 v[0:3], v[180:183], v[212:215], v[0:3]
	s_setprio 0
	s_barrier
	s_add_i32 s52, s52, 2
	s_add_u32 s50, s50, 0x100
	s_addc_u32 s51, s51, 0
	s_cmp_gt_u32 s52, 41
	s_mov_b64 s[24:25], s[26:27]
	s_cbranch_scc0 .LBB0_2056
	s_and_b64 vcc, exec, s[20:21]
	s_cbranch_vccz .LBB0_2059
	s_barrier

.LBB0_2337:
	ds_read_b128 v[152:155], v149
	ds_read_b128 v[156:159], v149 offset:1024
	ds_read_b128 v[160:163], v149 offset:2048
	ds_read_b128 v[164:167], v149 offset:3072
	ds_read_b128 v[168:171], v150
	ds_read_b128 v[172:175], v150 offset:1024
	ds_read_b128 v[176:179], v150 offset:2048
	ds_read_b128 v[180:183], v150 offset:3072
	s_add_u32 s42, s30, 0xfffc0080
	s_addc_u32 s43, s31, -1
	s_cmp_eq_u32 s53, 12
	s_cselect_b32 s45, s23, s43
	s_cselect_b32 s44, s49, s42
	s_cselect_b32 s43, s21, s52
	s_cselect_b32 s42, s50, s51
	v_lshl_add_u64 v[144:145], s[30:31], 0, v[138:139]
	s_add_i32 m0, s8, 0xc000
	ds_read_b128 v[184:187], v151
	ds_read_b128 v[188:191], v151 offset:1024
	ds_read_b128 v[192:195], v151 offset:2048
	ds_read_b128 v[196:199], v151 offset:3072
	ds_read_b128 v[200:203], v151 offset:4096
	ds_read_b128 v[204:207], v151 offset:5120
	ds_read_b128 v[208:211], v151 offset:6144
	ds_read_b128 v[212:215], v151 offset:7168
	global_load_lds_dwordx4 v[144:145], off
	v_lshl_add_u64 v[144:145], s[30:31], 0, v[136:137]
	s_add_i32 m0, s8, 0xe000
	s_nop 0
	global_load_lds_dwordx4 v[144:145], off
	s_waitcnt vmcnt(8)
	s_waitcnt lgkmcnt(0)
	s_barrier
	s_setprio 1
	s_waitcnt lgkmcnt(0)
	v_mfma_f32_16x16x32_bf16 v[124:127], v[152:155], v[184:187], v[124:127]
	v_mfma_f32_16x16x32_bf16 v[120:123], v[160:163], v[184:187], v[120:123]
	v_mfma_f32_16x16x32_bf16 v[116:119], v[152:155], v[192:195], v[116:119]
	v_mfma_f32_16x16x32_bf16 v[112:115], v[160:163], v[192:195], v[112:115]
	v_mfma_f32_16x16x32_bf16 v[108:111], v[152:155], v[200:203], v[108:111]
	v_mfma_f32_16x16x32_bf16 v[104:107], v[160:163], v[200:203], v[104:107]
	v_mfma_f32_16x16x32_bf16 v[100:103], v[152:155], v[208:211], v[100:103]
	v_mfma_f32_16x16x32_bf16 v[96:99], v[160:163], v[208:211], v[96:99]
	v_mfma_f32_16x16x32_bf16 v[124:127], v[156:159], v[188:191], v[124:127]
	v_mfma_f32_16x16x32_bf16 v[120:123], v[164:167], v[188:191], v[120:123]
	v_mfma_f32_16x16x32_bf16 v[116:119], v[156:159], v[196:199], v[116:119]
	v_mfma_f32_16x16x32_bf16 v[112:115], v[164:167], v[196:199], v[112:115]
	v_mfma_f32_16x16x32_bf16 v[108:111], v[156:159], v[204:207], v[108:111]
	v_mfma_f32_16x16x32_bf16 v[104:107], v[164:167], v[204:207], v[104:107]
	v_mfma_f32_16x16x32_bf16 v[100:103], v[156:159], v[212:215], v[100:103]
	v_mfma_f32_16x16x32_bf16 v[96:99], v[164:167], v[212:215], v[96:99]
	v_mfma_f32_16x16x32_bf16 v[80:83], v[168:171], v[184:187], v[80:83]
	v_mfma_f32_16x16x32_bf16 v[72:75], v[176:179], v[184:187], v[72:75]
	v_mfma_f32_16x16x32_bf16 v[60:63], v[168:171], v[192:195], v[60:63]
	v_mfma_f32_16x16x32_bf16 v[56:59], v[176:179], v[192:195], v[56:59]
	v_mfma_f32_16x16x32_bf16 v[44:47], v[168:171], v[200:203], v[44:47]
	v_mfma_f32_16x16x32_bf16 v[40:43], v[176:179], v[200:203], v[40:43]
	v_mfma_f32_16x16x32_bf16 v[36:39], v[168:171], v[208:211], v[36:39]
	v_mfma_f32_16x16x32_bf16 v[32:35], v[176:179], v[208:211], v[32:35]
	v_mfma_f32_16x16x32_bf16 v[80:83], v[172:175], v[188:191], v[80:83]
	v_mfma_f32_16x16x32_bf16 v[72:75], v[180:183], v[188:191], v[72:75]
	v_mfma_f32_16x16x32_bf16 v[60:63], v[172:175], v[196:199], v[60:63]
	v_mfma_f32_16x16x32_bf16 v[56:59], v[180:183], v[196:199], v[56:59]
	v_mfma_f32_16x16x32_bf16 v[44:47], v[172:175], v[204:207], v[44:47]
	v_mfma_f32_16x16x32_bf16 v[40:43], v[180:183], v[204:207], v[40:43]
	v_mfma_f32_16x16x32_bf16 v[36:39], v[172:175], v[212:215], v[36:39]
	v_mfma_f32_16x16x32_bf16 v[32:35], v[180:183], v[212:215], v[32:35]
	s_setprio 0
	s_barrier
	s_add_i32 s54, s41, s5
	v_lshl_add_u64 v[144:145], s[42:43], 0, v[132:133]
	s_mov_b32 m0, s54
	ds_read_b128 v[184:187], v151 offset:16384
	ds_read_b128 v[188:191], v151 offset:17408
	ds_read_b128 v[192:195], v151 offset:18432
	ds_read_b128 v[196:199], v151 offset:19456
	ds_read_b128 v[200:203], v151 offset:20480
	ds_read_b128 v[204:207], v151 offset:21504
	ds_read_b128 v[208:211], v151 offset:22528
	ds_read_b128 v[212:215], v151 offset:23552
	global_load_lds_dwordx4 v[144:145], off
	s_add_i32 m0, s54, 0x2000
	s_add_u32 s54, s42, 0x40000
	v_lshl_add_u64 v[216:217], s[42:43], 0, v[128:129]
	s_addc_u32 s55, s43, 0
	s_add_i32 s56, s46, s5
	global_load_lds_dwordx4 v[216:217], off
	v_lshl_add_u64 v[218:219], s[54:55], 0, v[132:133]
	s_mov_b32 m0, s56
	v_lshl_add_u64 v[220:221], s[44:45], 0, v[130:131]
	global_load_lds_dwordx4 v[218:219], off
	v_lshl_add_u64 v[218:219], s[54:55], 0, v[128:129]
	s_add_i32 m0, s56, 0x2000
	s_nop 0
	global_load_lds_dwordx4 v[218:219], off
	v_lshl_add_u64 v[218:219], s[44:45], 0, v[134:135]
	s_mov_b32 m0, s8
	s_nop 0
	global_load_lds_dwordx4 v[218:219], off
	s_mov_b32 m0, s9
	s_nop 0
	global_load_lds_dwordx4 v[220:221], off
	s_waitcnt vmcnt(8)
	s_waitcnt lgkmcnt(0)
	s_barrier
	s_setprio 1
	s_waitcnt lgkmcnt(0)
	v_mfma_f32_16x16x32_bf16 v[92:95], v[152:155], v[184:187], v[92:95]
	v_mfma_f32_16x16x32_bf16 v[88:91], v[160:163], v[184:187], v[88:91]
	v_mfma_f32_16x16x32_bf16 v[84:87], v[152:155], v[192:195], v[84:87]
	v_mfma_f32_16x16x32_bf16 v[76:79], v[160:163], v[192:195], v[76:79]
	v_mfma_f32_16x16x32_bf16 v[68:71], v[152:155], v[200:203], v[68:71]
	v_mfma_f32_16x16x32_bf16 v[64:67], v[160:163], v[200:203], v[64:67]
	v_mfma_f32_16x16x32_bf16 v[52:55], v[152:155], v[208:211], v[52:55]
	v_mfma_f32_16x16x32_bf16 v[48:51], v[160:163], v[208:211], v[48:51]
	v_mfma_f32_16x16x32_bf16 v[92:95], v[156:159], v[188:191], v[92:95]
	v_mfma_f32_16x16x32_bf16 v[88:91], v[164:167], v[188:191], v[88:91]
	v_mfma_f32_16x16x32_bf16 v[84:87], v[156:159], v[196:199], v[84:87]
	v_mfma_f32_16x16x32_bf16 v[76:79], v[164:167], v[196:199], v[76:79]
	v_mfma_f32_16x16x32_bf16 v[68:71], v[156:159], v[204:207], v[68:71]
	v_mfma_f32_16x16x32_bf16 v[64:67], v[164:167], v[204:207], v[64:67]
	v_mfma_f32_16x16x32_bf16 v[52:55], v[156:159], v[212:215], v[52:55]
	v_mfma_f32_16x16x32_bf16 v[48:51], v[164:167], v[212:215], v[48:51]
	v_mfma_f32_16x16x32_bf16 v[28:31], v[168:171], v[184:187], v[28:31]
	v_mfma_f32_16x16x32_bf16 v[24:27], v[176:179], v[184:187], v[24:27]
	v_mfma_f32_16x16x32_bf16 v[20:23], v[168:171], v[192:195], v[20:23]
	v_mfma_f32_16x16x32_bf16 v[16:19], v[176:179], v[192:195], v[16:19]
	v_mfma_f32_16x16x32_bf16 v[12:15], v[168:171], v[200:203], v[12:15]
	v_mfma_f32_16x16x32_bf16 v[8:11], v[176:179], v[200:203], v[8:11]
	v_mfma_f32_16x16x32_bf16 v[4:7], v[168:171], v[208:211], v[4:7]
	v_mfma_f32_16x16x32_bf16 v[0:3], v[176:179], v[208:211], v[0:3]
	v_mfma_f32_16x16x32_bf16 v[28:31], v[172:175], v[188:191], v[28:31]
	v_mfma_f32_16x16x32_bf16 v[24:27], v[180:183], v[188:191], v[24:27]
	v_mfma_f32_16x16x32_bf16 v[20:23], v[172:175], v[196:199], v[20:23]
	v_mfma_f32_16x16x32_bf16 v[16:19], v[180:183], v[196:199], v[16:19]
	v_mfma_f32_16x16x32_bf16 v[12:15], v[172:175], v[204:207], v[12:15]
	v_mfma_f32_16x16x32_bf16 v[8:11], v[180:183], v[204:207], v[8:11]
	v_mfma_f32_16x16x32_bf16 v[4:7], v[172:175], v[212:215], v[4:7]
	v_mfma_f32_16x16x32_bf16 v[0:3], v[180:183], v[212:215], v[0:3]
	s_setprio 0
	s_barrier
	s_add_i32 s54, 0, 0x18000
	s_add_i32 s55, 0, 0x1c000
	v_add_u32_e32 v164, s54, v147
	v_add_u32_e32 v180, s55, v147
	ds_read_b128 v[152:155], v164
	ds_read_b128 v[156:159], v164 offset:1024
	ds_read_b128 v[160:163], v164 offset:2048
	ds_read_b128 v[164:167], v164 offset:3072
	ds_read_b128 v[168:171], v180
	ds_read_b128 v[172:175], v180 offset:1024
	ds_read_b128 v[176:179], v180 offset:2048
	ds_read_b128 v[180:183], v180 offset:3072
	s_add_u32 s44, s44, 0x40000
	s_addc_u32 s45, s45, 0
	s_mov_b32 m0, s33
	v_lshl_add_u64 v[222:223], s[44:45], 0, v[134:135]
	ds_read_b128 v[184:187], v151 offset:32768
	ds_read_b128 v[188:191], v151 offset:33792
	ds_read_b128 v[192:195], v151 offset:34816
	ds_read_b128 v[196:199], v151 offset:35840
	ds_read_b128 v[200:203], v151 offset:36864
	ds_read_b128 v[204:207], v151 offset:37888
	ds_read_b128 v[208:211], v151 offset:38912
	ds_read_b128 v[212:215], v151 offset:39936
	global_load_lds_dwordx4 v[222:223], off
	v_lshl_add_u64 v[222:223], s[44:45], 0, v[130:131]
	s_mov_b32 m0, s35
	s_nop 0
	global_load_lds_dwordx4 v[222:223], off
	s_waitcnt vmcnt(8)
	s_waitcnt lgkmcnt(0)
	s_barrier
	s_setprio 1
	s_waitcnt lgkmcnt(0)
	v_mfma_f32_16x16x32_bf16 v[124:127], v[152:155], v[184:187], v[124:127]
	v_mfma_f32_16x16x32_bf16 v[120:123], v[160:163], v[184:187], v[120:123]
	v_mfma_f32_16x16x32_bf16 v[116:119], v[152:155], v[192:195], v[116:119]
	v_mfma_f32_16x16x32_bf16 v[112:115], v[160:163], v[192:195], v[112:115]
	v_mfma_f32_16x16x32_bf16 v[108:111], v[152:155], v[200:203], v[108:111]
	v_mfma_f32_16x16x32_bf16 v[104:107], v[160:163], v[200:203], v[104:107]
	v_mfma_f32_16x16x32_bf16 v[100:103], v[152:155], v[208:211], v[100:103]
	v_mfma_f32_16x16x32_bf16 v[96:99], v[160:163], v[208:211], v[96:99]
	v_mfma_f32_16x16x32_bf16 v[124:127], v[156:159], v[188:191], v[124:127]
	v_mfma_f32_16x16x32_bf16 v[120:123], v[164:167], v[188:191], v[120:123]
	v_mfma_f32_16x16x32_bf16 v[116:119], v[156:159], v[196:199], v[116:119]
	v_mfma_f32_16x16x32_bf16 v[112:115], v[164:167], v[196:199], v[112:115]
	v_mfma_f32_16x16x32_bf16 v[108:111], v[156:159], v[204:207], v[108:111]
	v_mfma_f32_16x16x32_bf16 v[104:107], v[164:167], v[204:207], v[104:107]
	v_mfma_f32_16x16x32_bf16 v[100:103], v[156:159], v[212:215], v[100:103]
	v_mfma_f32_16x16x32_bf16 v[96:99], v[164:167], v[212:215], v[96:99]
	v_mfma_f32_16x16x32_bf16 v[80:83], v[168:171], v[184:187], v[80:83]
	v_mfma_f32_16x16x32_bf16 v[72:75], v[176:179], v[184:187], v[72:75]
	v_mfma_f32_16x16x32_bf16 v[60:63], v[168:171], v[192:195], v[60:63]
	v_mfma_f32_16x16x32_bf16 v[56:59], v[176:179], v[192:195], v[56:59]
	v_mfma_f32_16x16x32_bf16 v[44:47], v[168:171], v[200:203], v[44:47]
	v_mfma_f32_16x16x32_bf16 v[40:43], v[176:179], v[200:203], v[40:43]
	v_mfma_f32_16x16x32_bf16 v[36:39], v[168:171], v[208:211], v[36:39]
	v_mfma_f32_16x16x32_bf16 v[32:35], v[176:179], v[208:211], v[32:35]
	v_mfma_f32_16x16x32_bf16 v[80:83], v[172:175], v[188:191], v[80:83]
	v_mfma_f32_16x16x32_bf16 v[72:75], v[180:183], v[188:191], v[72:75]
	v_mfma_f32_16x16x32_bf16 v[60:63], v[172:175], v[196:199], v[60:63]
	v_mfma_f32_16x16x32_bf16 v[56:59], v[180:183], v[196:199], v[56:59]
	v_mfma_f32_16x16x32_bf16 v[44:47], v[172:175], v[204:207], v[44:47]
	v_mfma_f32_16x16x32_bf16 v[40:43], v[180:183], v[204:207], v[40:43]
	v_mfma_f32_16x16x32_bf16 v[36:39], v[172:175], v[212:215], v[36:39]
	v_mfma_f32_16x16x32_bf16 v[32:35], v[180:183], v[212:215], v[32:35]
	s_setprio 0
	s_barrier
	s_add_i32 s44, s54, s5
	v_lshl_add_u64 v[144:145], v[144:145], 0, s[16:17]
	s_mov_b32 m0, s44
	ds_read_b128 v[184:187], v151 offset:49152
	ds_read_b128 v[188:191], v151 offset:50176
	ds_read_b128 v[192:195], v151 offset:51200
	ds_read_b128 v[196:199], v151 offset:52224
	ds_read_b128 v[200:203], v151 offset:53248
	ds_read_b128 v[204:207], v151 offset:54272
	ds_read_b128 v[208:211], v151 offset:55296
	ds_read_b128 v[212:215], v151 offset:56320
	global_load_lds_dwordx4 v[144:145], off
	s_add_i32 m0, s44, 0x2000
	s_add_u32 s42, s42, 0x40080
	v_lshl_add_u64 v[144:145], v[216:217], 0, s[16:17]
	s_addc_u32 s43, s43, 0
	s_add_i32 s44, s55, s5
	global_load_lds_dwordx4 v[144:145], off
	v_lshl_add_u64 v[144:145], s[42:43], 0, v[132:133]
	s_mov_b32 m0, s44
	s_nop 0
	global_load_lds_dwordx4 v[144:145], off
	v_lshl_add_u64 v[144:145], s[42:43], 0, v[128:129]
	s_add_i32 m0, s44, 0x2000
	s_nop 0
	global_load_lds_dwordx4 v[144:145], off
	v_lshl_add_u64 v[144:145], v[218:219], 0, s[16:17]
	s_mov_b32 m0, s37
	s_nop 0
	global_load_lds_dwordx4 v[144:145], off
	v_lshl_add_u64 v[144:145], v[220:221], 0, s[16:17]
	s_mov_b32 m0, s38
	s_nop 0
	global_load_lds_dwordx4 v[144:145], off
	s_waitcnt vmcnt(8)
	s_waitcnt lgkmcnt(0)
	s_barrier
	s_setprio 1
	s_waitcnt lgkmcnt(0)
	v_mfma_f32_16x16x32_bf16 v[92:95], v[152:155], v[184:187], v[92:95]
	v_mfma_f32_16x16x32_bf16 v[88:91], v[160:163], v[184:187], v[88:91]
	v_mfma_f32_16x16x32_bf16 v[84:87], v[152:155], v[192:195], v[84:87]
	v_mfma_f32_16x16x32_bf16 v[76:79], v[160:163], v[192:195], v[76:79]
	v_mfma_f32_16x16x32_bf16 v[68:71], v[152:155], v[200:203], v[68:71]
	v_mfma_f32_16x16x32_bf16 v[64:67], v[160:163], v[200:203], v[64:67]
	v_mfma_f32_16x16x32_bf16 v[52:55], v[152:155], v[208:211], v[52:55]
	v_mfma_f32_16x16x32_bf16 v[48:51], v[160:163], v[208:211], v[48:51]
	v_mfma_f32_16x16x32_bf16 v[92:95], v[156:159], v[188:191], v[92:95]
	v_mfma_f32_16x16x32_bf16 v[88:91], v[164:167], v[188:191], v[88:91]
	v_mfma_f32_16x16x32_bf16 v[84:87], v[156:159], v[196:199], v[84:87]
	v_mfma_f32_16x16x32_bf16 v[76:79], v[164:167], v[196:199], v[76:79]
	v_mfma_f32_16x16x32_bf16 v[68:71], v[156:159], v[204:207], v[68:71]
	v_mfma_f32_16x16x32_bf16 v[64:67], v[164:167], v[204:207], v[64:67]
	v_mfma_f32_16x16x32_bf16 v[52:55], v[156:159], v[212:215], v[52:55]
	v_mfma_f32_16x16x32_bf16 v[48:51], v[164:167], v[212:215], v[48:51]
	v_mfma_f32_16x16x32_bf16 v[28:31], v[168:171], v[184:187], v[28:31]
	v_mfma_f32_16x16x32_bf16 v[24:27], v[176:179], v[184:187], v[24:27]
	v_mfma_f32_16x16x32_bf16 v[20:23], v[168:171], v[192:195], v[20:23]
	v_mfma_f32_16x16x32_bf16 v[16:19], v[176:179], v[192:195], v[16:19]
	v_mfma_f32_16x16x32_bf16 v[12:15], v[168:171], v[200:203], v[12:15]
	v_mfma_f32_16x16x32_bf16 v[8:11], v[176:179], v[200:203], v[8:11]
	v_mfma_f32_16x16x32_bf16 v[4:7], v[168:171], v[208:211], v[4:7]
	v_mfma_f32_16x16x32_bf16 v[0:3], v[176:179], v[208:211], v[0:3]
	v_mfma_f32_16x16x32_bf16 v[28:31], v[172:175], v[188:191], v[28:31]
	v_mfma_f32_16x16x32_bf16 v[24:27], v[180:183], v[188:191], v[24:27]
	v_mfma_f32_16x16x32_bf16 v[20:23], v[172:175], v[196:199], v[20:23]
	v_mfma_f32_16x16x32_bf16 v[16:19], v[180:183], v[196:199], v[16:19]
	v_mfma_f32_16x16x32_bf16 v[12:15], v[172:175], v[204:207], v[12:15]
	v_mfma_f32_16x16x32_bf16 v[8:11], v[180:183], v[204:207], v[8:11]
	v_mfma_f32_16x16x32_bf16 v[4:7], v[172:175], v[212:215], v[4:7]
	v_mfma_f32_16x16x32_bf16 v[0:3], v[180:183], v[212:215], v[0:3]
	s_setprio 0
	s_barrier
	s_add_i32 s53, s53, 2
	s_add_u32 s51, s51, 0x100
	s_addc_u32 s52, s52, 0
	s_add_u32 s30, s30, 0x100
	s_addc_u32 s31, s31, 0
	s_cmp_gt_u32 s53, 13
	s_cbranch_scc0 .LBB0_2337
	s_and_b64 vcc, exec, s[18:19]
	s_cbranch_vccz .LBB0_2340
	s_barrier

.LBB0_3217:
	ds_read_b128 v[144:147], v157
	ds_read_b128 v[148:151], v157 offset:1024
	ds_read_b128 v[160:163], v157 offset:2048
	ds_read_b128 v[164:167], v157 offset:3072
	ds_read_b128 v[168:171], v158
	ds_read_b128 v[172:175], v158 offset:1024
	ds_read_b128 v[176:179], v158 offset:2048
	ds_read_b128 v[180:183], v158 offset:3072
	s_add_u32 s40, s30, 0xfffc0080
	s_addc_u32 s41, s31, -1
	s_cmp_eq_u32 s54, 12
	s_cselect_b32 s43, s23, s41
	s_cselect_b32 s42, s50, s40
	s_cselect_b32 s41, s21, s53
	s_cselect_b32 s40, s51, s52
	v_lshl_add_u64 v[152:153], s[30:31], 0, v[138:139]
	s_add_i32 m0, s7, 0xc000
	ds_read_b128 v[184:187], v159
	ds_read_b128 v[188:191], v159 offset:1024
	ds_read_b128 v[192:195], v159 offset:2048
	ds_read_b128 v[196:199], v159 offset:3072
	ds_read_b128 v[200:203], v159 offset:4096
	ds_read_b128 v[204:207], v159 offset:5120
	ds_read_b128 v[208:211], v159 offset:6144
	ds_read_b128 v[212:215], v159 offset:7168
	global_load_lds_dwordx4 v[152:153], off
	v_lshl_add_u64 v[152:153], s[30:31], 0, v[136:137]
	s_add_i32 m0, s7, 0xe000
	s_nop 0
	global_load_lds_dwordx4 v[152:153], off
	s_waitcnt vmcnt(8)
	s_waitcnt lgkmcnt(0)
	s_barrier
	s_setprio 1
	s_waitcnt lgkmcnt(0)
	v_mfma_f32_16x16x32_bf16 v[124:127], v[144:147], v[184:187], v[124:127]
	v_mfma_f32_16x16x32_bf16 v[120:123], v[160:163], v[184:187], v[120:123]
	v_mfma_f32_16x16x32_bf16 v[116:119], v[144:147], v[192:195], v[116:119]
	v_mfma_f32_16x16x32_bf16 v[112:115], v[160:163], v[192:195], v[112:115]
	v_mfma_f32_16x16x32_bf16 v[108:111], v[144:147], v[200:203], v[108:111]
	v_mfma_f32_16x16x32_bf16 v[104:107], v[160:163], v[200:203], v[104:107]
	v_mfma_f32_16x16x32_bf16 v[100:103], v[144:147], v[208:211], v[100:103]
	v_mfma_f32_16x16x32_bf16 v[96:99], v[160:163], v[208:211], v[96:99]
	v_mfma_f32_16x16x32_bf16 v[124:127], v[148:151], v[188:191], v[124:127]
	v_mfma_f32_16x16x32_bf16 v[120:123], v[164:167], v[188:191], v[120:123]
	v_mfma_f32_16x16x32_bf16 v[116:119], v[148:151], v[196:199], v[116:119]
	v_mfma_f32_16x16x32_bf16 v[112:115], v[164:167], v[196:199], v[112:115]
	v_mfma_f32_16x16x32_bf16 v[108:111], v[148:151], v[204:207], v[108:111]
	v_mfma_f32_16x16x32_bf16 v[104:107], v[164:167], v[204:207], v[104:107]
	v_mfma_f32_16x16x32_bf16 v[100:103], v[148:151], v[212:215], v[100:103]
	v_mfma_f32_16x16x32_bf16 v[96:99], v[164:167], v[212:215], v[96:99]
	v_mfma_f32_16x16x32_bf16 v[76:79], v[168:171], v[184:187], v[76:79]
	v_mfma_f32_16x16x32_bf16 v[72:75], v[176:179], v[184:187], v[72:75]
	v_mfma_f32_16x16x32_bf16 v[60:63], v[168:171], v[192:195], v[60:63]
	v_mfma_f32_16x16x32_bf16 v[52:55], v[176:179], v[192:195], v[52:55]
	v_mfma_f32_16x16x32_bf16 v[44:47], v[168:171], v[200:203], v[44:47]
	v_mfma_f32_16x16x32_bf16 v[40:43], v[176:179], v[200:203], v[40:43]
	v_mfma_f32_16x16x32_bf16 v[36:39], v[168:171], v[208:211], v[36:39]
	v_mfma_f32_16x16x32_bf16 v[32:35], v[176:179], v[208:211], v[32:35]
	v_mfma_f32_16x16x32_bf16 v[76:79], v[172:175], v[188:191], v[76:79]
	v_mfma_f32_16x16x32_bf16 v[72:75], v[180:183], v[188:191], v[72:75]
	v_mfma_f32_16x16x32_bf16 v[60:63], v[172:175], v[196:199], v[60:63]
	v_mfma_f32_16x16x32_bf16 v[52:55], v[180:183], v[196:199], v[52:55]
	v_mfma_f32_16x16x32_bf16 v[44:47], v[172:175], v[204:207], v[44:47]
	v_mfma_f32_16x16x32_bf16 v[40:43], v[180:183], v[204:207], v[40:43]
	v_mfma_f32_16x16x32_bf16 v[36:39], v[172:175], v[212:215], v[36:39]
	v_mfma_f32_16x16x32_bf16 v[32:35], v[180:183], v[212:215], v[32:35]
	s_setprio 0
	s_barrier
	s_add_i32 s55, s45, s6
	v_lshl_add_u64 v[152:153], s[40:41], 0, v[130:131]
	s_mov_b32 m0, s55
	ds_read_b128 v[184:187], v159 offset:16384
	ds_read_b128 v[188:191], v159 offset:17408
	ds_read_b128 v[192:195], v159 offset:18432
	ds_read_b128 v[196:199], v159 offset:19456
	ds_read_b128 v[200:203], v159 offset:20480
	ds_read_b128 v[204:207], v159 offset:21504
	ds_read_b128 v[208:211], v159 offset:22528
	ds_read_b128 v[212:215], v159 offset:23552
	global_load_lds_dwordx4 v[152:153], off
	s_add_i32 m0, s55, 0x2000
	s_add_u32 s56, s40, 0x40000
	v_lshl_add_u64 v[216:217], s[40:41], 0, v[134:135]
	s_addc_u32 s57, s41, 0
	s_add_i32 s55, s46, s6
	global_load_lds_dwordx4 v[216:217], off
	v_lshl_add_u64 v[218:219], s[56:57], 0, v[130:131]
	s_mov_b32 m0, s55
	v_lshl_add_u64 v[220:221], s[42:43], 0, v[132:133]
	global_load_lds_dwordx4 v[218:219], off
	v_lshl_add_u64 v[218:219], s[56:57], 0, v[134:135]
	s_add_i32 m0, s55, 0x2000
	s_nop 0
	global_load_lds_dwordx4 v[218:219], off
	v_lshl_add_u64 v[218:219], s[42:43], 0, v[128:129]
	s_mov_b32 m0, s7
	s_nop 0
	global_load_lds_dwordx4 v[218:219], off
	s_mov_b32 m0, s8
	s_nop 0
	global_load_lds_dwordx4 v[220:221], off
	s_waitcnt vmcnt(8)
	s_waitcnt lgkmcnt(0)
	s_barrier
	s_setprio 1
	s_waitcnt lgkmcnt(0)
	v_mfma_f32_16x16x32_bf16 v[92:95], v[144:147], v[184:187], v[92:95]
	v_mfma_f32_16x16x32_bf16 v[88:91], v[160:163], v[184:187], v[88:91]
	v_mfma_f32_16x16x32_bf16 v[84:87], v[144:147], v[192:195], v[84:87]
	v_mfma_f32_16x16x32_bf16 v[80:83], v[160:163], v[192:195], v[80:83]
	v_mfma_f32_16x16x32_bf16 v[68:71], v[144:147], v[200:203], v[68:71]
	v_mfma_f32_16x16x32_bf16 v[64:67], v[160:163], v[200:203], v[64:67]
	v_mfma_f32_16x16x32_bf16 v[56:59], v[144:147], v[208:211], v[56:59]
	v_mfma_f32_16x16x32_bf16 v[48:51], v[160:163], v[208:211], v[48:51]
	v_mfma_f32_16x16x32_bf16 v[92:95], v[148:151], v[188:191], v[92:95]
	v_mfma_f32_16x16x32_bf16 v[88:91], v[164:167], v[188:191], v[88:91]
	v_mfma_f32_16x16x32_bf16 v[84:87], v[148:151], v[196:199], v[84:87]
	v_mfma_f32_16x16x32_bf16 v[80:83], v[164:167], v[196:199], v[80:83]
	v_mfma_f32_16x16x32_bf16 v[68:71], v[148:151], v[204:207], v[68:71]
	v_mfma_f32_16x16x32_bf16 v[64:67], v[164:167], v[204:207], v[64:67]
	v_mfma_f32_16x16x32_bf16 v[56:59], v[148:151], v[212:215], v[56:59]
	v_mfma_f32_16x16x32_bf16 v[48:51], v[164:167], v[212:215], v[48:51]
	v_mfma_f32_16x16x32_bf16 v[28:31], v[168:171], v[184:187], v[28:31]
	v_mfma_f32_16x16x32_bf16 v[24:27], v[176:179], v[184:187], v[24:27]
	v_mfma_f32_16x16x32_bf16 v[20:23], v[168:171], v[192:195], v[20:23]
	v_mfma_f32_16x16x32_bf16 v[16:19], v[176:179], v[192:195], v[16:19]
	v_mfma_f32_16x16x32_bf16 v[12:15], v[168:171], v[200:203], v[12:15]
	v_mfma_f32_16x16x32_bf16 v[8:11], v[176:179], v[200:203], v[8:11]
	v_mfma_f32_16x16x32_bf16 v[4:7], v[168:171], v[208:211], v[4:7]
	v_mfma_f32_16x16x32_bf16 v[0:3], v[176:179], v[208:211], v[0:3]
	v_mfma_f32_16x16x32_bf16 v[28:31], v[172:175], v[188:191], v[28:31]
	v_mfma_f32_16x16x32_bf16 v[24:27], v[180:183], v[188:191], v[24:27]
	v_mfma_f32_16x16x32_bf16 v[20:23], v[172:175], v[196:199], v[20:23]
	v_mfma_f32_16x16x32_bf16 v[16:19], v[180:183], v[196:199], v[16:19]
	v_mfma_f32_16x16x32_bf16 v[12:15], v[172:175], v[204:207], v[12:15]
	v_mfma_f32_16x16x32_bf16 v[8:11], v[180:183], v[204:207], v[8:11]
	v_mfma_f32_16x16x32_bf16 v[4:7], v[172:175], v[212:215], v[4:7]
	v_mfma_f32_16x16x32_bf16 v[0:3], v[180:183], v[212:215], v[0:3]
	s_setprio 0
	s_barrier
	s_add_i32 s55, 0, 0x18000
	s_add_i32 s56, 0, 0x1c000
	v_add_u32_e32 v164, s55, v155
	v_add_u32_e32 v180, s56, v155
	ds_read_b128 v[144:147], v164
	ds_read_b128 v[148:151], v164 offset:1024
	ds_read_b128 v[160:163], v164 offset:2048
	ds_read_b128 v[164:167], v164 offset:3072
	ds_read_b128 v[168:171], v180
	ds_read_b128 v[172:175], v180 offset:1024
	ds_read_b128 v[176:179], v180 offset:2048
	ds_read_b128 v[180:183], v180 offset:3072
	s_add_u32 s42, s42, 0x40000
	s_addc_u32 s43, s43, 0
	s_mov_b32 m0, s9
	v_lshl_add_u64 v[222:223], s[42:43], 0, v[128:129]
	ds_read_b128 v[184:187], v159 offset:32768
	ds_read_b128 v[188:191], v159 offset:33792
	ds_read_b128 v[192:195], v159 offset:34816
	ds_read_b128 v[196:199], v159 offset:35840
	ds_read_b128 v[200:203], v159 offset:36864
	ds_read_b128 v[204:207], v159 offset:37888
	ds_read_b128 v[208:211], v159 offset:38912
	ds_read_b128 v[212:215], v159 offset:39936
	global_load_lds_dwordx4 v[222:223], off
	v_lshl_add_u64 v[222:223], s[42:43], 0, v[132:133]
	s_mov_b32 m0, s33
	s_nop 0
	global_load_lds_dwordx4 v[222:223], off
	s_waitcnt vmcnt(8)
	s_waitcnt lgkmcnt(0)
	s_barrier
	s_setprio 1
	s_waitcnt lgkmcnt(0)
	v_mfma_f32_16x16x32_bf16 v[124:127], v[144:147], v[184:187], v[124:127]
	v_mfma_f32_16x16x32_bf16 v[120:123], v[160:163], v[184:187], v[120:123]
	v_mfma_f32_16x16x32_bf16 v[116:119], v[144:147], v[192:195], v[116:119]
	v_mfma_f32_16x16x32_bf16 v[112:115], v[160:163], v[192:195], v[112:115]
	v_mfma_f32_16x16x32_bf16 v[108:111], v[144:147], v[200:203], v[108:111]
	v_mfma_f32_16x16x32_bf16 v[104:107], v[160:163], v[200:203], v[104:107]
	v_mfma_f32_16x16x32_bf16 v[100:103], v[144:147], v[208:211], v[100:103]
	v_mfma_f32_16x16x32_bf16 v[96:99], v[160:163], v[208:211], v[96:99]
	v_mfma_f32_16x16x32_bf16 v[124:127], v[148:151], v[188:191], v[124:127]
	v_mfma_f32_16x16x32_bf16 v[120:123], v[164:167], v[188:191], v[120:123]
	v_mfma_f32_16x16x32_bf16 v[116:119], v[148:151], v[196:199], v[116:119]
	v_mfma_f32_16x16x32_bf16 v[112:115], v[164:167], v[196:199], v[112:115]
	v_mfma_f32_16x16x32_bf16 v[108:111], v[148:151], v[204:207], v[108:111]
	v_mfma_f32_16x16x32_bf16 v[104:107], v[164:167], v[204:207], v[104:107]
	v_mfma_f32_16x16x32_bf16 v[100:103], v[148:151], v[212:215], v[100:103]
	v_mfma_f32_16x16x32_bf16 v[96:99], v[164:167], v[212:215], v[96:99]
	v_mfma_f32_16x16x32_bf16 v[76:79], v[168:171], v[184:187], v[76:79]
	v_mfma_f32_16x16x32_bf16 v[72:75], v[176:179], v[184:187], v[72:75]
	v_mfma_f32_16x16x32_bf16 v[60:63], v[168:171], v[192:195], v[60:63]
	v_mfma_f32_16x16x32_bf16 v[52:55], v[176:179], v[192:195], v[52:55]
	v_mfma_f32_16x16x32_bf16 v[44:47], v[168:171], v[200:203], v[44:47]
	v_mfma_f32_16x16x32_bf16 v[40:43], v[176:179], v[200:203], v[40:43]
	v_mfma_f32_16x16x32_bf16 v[36:39], v[168:171], v[208:211], v[36:39]
	v_mfma_f32_16x16x32_bf16 v[32:35], v[176:179], v[208:211], v[32:35]
	v_mfma_f32_16x16x32_bf16 v[76:79], v[172:175], v[188:191], v[76:79]
	v_mfma_f32_16x16x32_bf16 v[72:75], v[180:183], v[188:191], v[72:75]
	v_mfma_f32_16x16x32_bf16 v[60:63], v[172:175], v[196:199], v[60:63]
	v_mfma_f32_16x16x32_bf16 v[52:55], v[180:183], v[196:199], v[52:55]
	v_mfma_f32_16x16x32_bf16 v[44:47], v[172:175], v[204:207], v[44:47]
	v_mfma_f32_16x16x32_bf16 v[40:43], v[180:183], v[204:207], v[40:43]
	v_mfma_f32_16x16x32_bf16 v[36:39], v[172:175], v[212:215], v[36:39]
	v_mfma_f32_16x16x32_bf16 v[32:35], v[180:183], v[212:215], v[32:35]
	s_setprio 0
	s_barrier
	s_add_i32 s42, s55, s6
	v_lshl_add_u64 v[152:153], v[152:153], 0, s[16:17]
	s_mov_b32 m0, s42
	ds_read_b128 v[184:187], v159 offset:49152
	ds_read_b128 v[188:191], v159 offset:50176
	ds_read_b128 v[192:195], v159 offset:51200
	ds_read_b128 v[196:199], v159 offset:52224
	ds_read_b128 v[200:203], v159 offset:53248
	ds_read_b128 v[204:207], v159 offset:54272
	ds_read_b128 v[208:211], v159 offset:55296
	ds_read_b128 v[212:215], v159 offset:56320
	global_load_lds_dwordx4 v[152:153], off
	s_add_i32 m0, s42, 0x2000
	s_add_u32 s40, s40, 0x40080
	v_lshl_add_u64 v[152:153], v[216:217], 0, s[16:17]
	s_addc_u32 s41, s41, 0
	s_add_i32 s42, s56, s6
	global_load_lds_dwordx4 v[152:153], off
	v_lshl_add_u64 v[152:153], s[40:41], 0, v[130:131]
	s_mov_b32 m0, s42
	s_nop 0
	global_load_lds_dwordx4 v[152:153], off
	v_lshl_add_u64 v[152:153], s[40:41], 0, v[134:135]
	s_add_i32 m0, s42, 0x2000
	s_nop 0
	global_load_lds_dwordx4 v[152:153], off
	v_lshl_add_u64 v[152:153], v[218:219], 0, s[16:17]
	s_mov_b32 m0, s37
	s_nop 0
	global_load_lds_dwordx4 v[152:153], off
	v_lshl_add_u64 v[152:153], v[220:221], 0, s[16:17]
	s_mov_b32 m0, s38
	s_nop 0
	global_load_lds_dwordx4 v[152:153], off
	s_waitcnt vmcnt(8)
	s_waitcnt lgkmcnt(0)
	s_barrier
	s_setprio 1
	s_waitcnt lgkmcnt(0)
	v_mfma_f32_16x16x32_bf16 v[92:95], v[144:147], v[184:187], v[92:95]
	v_mfma_f32_16x16x32_bf16 v[88:91], v[160:163], v[184:187], v[88:91]
	v_mfma_f32_16x16x32_bf16 v[84:87], v[144:147], v[192:195], v[84:87]
	v_mfma_f32_16x16x32_bf16 v[80:83], v[160:163], v[192:195], v[80:83]
	v_mfma_f32_16x16x32_bf16 v[68:71], v[144:147], v[200:203], v[68:71]
	v_mfma_f32_16x16x32_bf16 v[64:67], v[160:163], v[200:203], v[64:67]
	v_mfma_f32_16x16x32_bf16 v[56:59], v[144:147], v[208:211], v[56:59]
	v_mfma_f32_16x16x32_bf16 v[48:51], v[160:163], v[208:211], v[48:51]
	v_mfma_f32_16x16x32_bf16 v[92:95], v[148:151], v[188:191], v[92:95]
	v_mfma_f32_16x16x32_bf16 v[88:91], v[164:167], v[188:191], v[88:91]
	v_mfma_f32_16x16x32_bf16 v[84:87], v[148:151], v[196:199], v[84:87]
	v_mfma_f32_16x16x32_bf16 v[80:83], v[164:167], v[196:199], v[80:83]
	v_mfma_f32_16x16x32_bf16 v[68:71], v[148:151], v[204:207], v[68:71]
	v_mfma_f32_16x16x32_bf16 v[64:67], v[164:167], v[204:207], v[64:67]
	v_mfma_f32_16x16x32_bf16 v[56:59], v[148:151], v[212:215], v[56:59]
	v_mfma_f32_16x16x32_bf16 v[48:51], v[164:167], v[212:215], v[48:51]
	v_mfma_f32_16x16x32_bf16 v[28:31], v[168:171], v[184:187], v[28:31]
	v_mfma_f32_16x16x32_bf16 v[24:27], v[176:179], v[184:187], v[24:27]
	v_mfma_f32_16x16x32_bf16 v[20:23], v[168:171], v[192:195], v[20:23]
	v_mfma_f32_16x16x32_bf16 v[16:19], v[176:179], v[192:195], v[16:19]
	v_mfma_f32_16x16x32_bf16 v[12:15], v[168:171], v[200:203], v[12:15]
	v_mfma_f32_16x16x32_bf16 v[8:11], v[176:179], v[200:203], v[8:11]
	v_mfma_f32_16x16x32_bf16 v[4:7], v[168:171], v[208:211], v[4:7]
	v_mfma_f32_16x16x32_bf16 v[0:3], v[176:179], v[208:211], v[0:3]
	v_mfma_f32_16x16x32_bf16 v[28:31], v[172:175], v[188:191], v[28:31]
	v_mfma_f32_16x16x32_bf16 v[24:27], v[180:183], v[188:191], v[24:27]
	v_mfma_f32_16x16x32_bf16 v[20:23], v[172:175], v[196:199], v[20:23]
	v_mfma_f32_16x16x32_bf16 v[16:19], v[180:183], v[196:199], v[16:19]
	v_mfma_f32_16x16x32_bf16 v[12:15], v[172:175], v[204:207], v[12:15]
	v_mfma_f32_16x16x32_bf16 v[8:11], v[180:183], v[204:207], v[8:11]
	v_mfma_f32_16x16x32_bf16 v[4:7], v[172:175], v[212:215], v[4:7]
	v_mfma_f32_16x16x32_bf16 v[0:3], v[180:183], v[212:215], v[0:3]
	s_setprio 0
	s_barrier
	s_add_i32 s54, s54, 2
	s_add_u32 s52, s52, 0x100
	s_addc_u32 s53, s53, 0
	s_add_u32 s30, s30, 0x100
	s_addc_u32 s31, s31, 0
	s_cmp_gt_u32 s54, 13
	s_cbranch_scc0 .LBB0_3217
	s_and_b64 vcc, exec, s[18:19]
	s_cbranch_vccz .LBB0_3220
	s_barrier

.LBB0_3350:
	ds_read_b128 v[104:107], v233
	ds_read_b128 v[108:111], v233 offset:1024
	ds_read_b128 v[112:115], v233 offset:2048
	ds_read_b128 v[116:119], v233 offset:3072
	ds_read_b128 v[120:123], v234
	ds_read_b128 v[124:127], v234 offset:1024
	ds_read_b128 v[128:131], v234 offset:2048
	ds_read_b128 v[132:135], v234 offset:3072
	s_add_u32 s74, s28, 0xfffc0080
	s_addc_u32 s75, s29, -1
	s_cmp_eq_u32 s80, 12
	s_cselect_b32 s77, s69, s75
	s_cselect_b32 s76, s68, s74
	s_cselect_b32 s75, s67, s79
	s_cselect_b32 s74, s73, s78
	v_lshl_add_u64 v[208:209], s[28:29], 0, v[186:187]
	s_add_i32 m0, s96, 0xc000
	ds_read_b128 v[160:163], v235
	ds_read_b128 v[164:167], v235 offset:1024
	ds_read_b128 v[168:171], v235 offset:2048
	ds_read_b128 v[172:175], v235 offset:3072
	ds_read_b128 v[192:195], v235 offset:4096
	ds_read_b128 v[196:199], v235 offset:5120
	ds_read_b128 v[200:203], v235 offset:6144
	ds_read_b128 v[204:207], v235 offset:7168
	global_load_lds_dwordx4 v[208:209], off
	v_lshl_add_u64 v[208:209], s[28:29], 0, v[184:185]
	s_add_i32 m0, s96, 0xe000
	s_nop 0
	global_load_lds_dwordx4 v[208:209], off
	s_waitcnt vmcnt(8)
	s_waitcnt lgkmcnt(0)
	s_barrier
	s_setprio 1
	s_waitcnt lgkmcnt(0)
	v_mfma_f32_16x16x32_bf16 v[156:159], v[104:107], v[160:163], v[156:159]
	v_mfma_f32_16x16x32_bf16 v[60:63], v[112:115], v[160:163], v[60:63]
	v_mfma_f32_16x16x32_bf16 v[148:151], v[104:107], v[168:171], v[148:151]
	v_mfma_f32_16x16x32_bf16 v[52:55], v[112:115], v[168:171], v[52:55]
	v_mfma_f32_16x16x32_bf16 v[140:143], v[104:107], v[192:195], v[140:143]
	v_mfma_f32_16x16x32_bf16 v[44:47], v[112:115], v[192:195], v[44:47]
	v_mfma_f32_16x16x32_bf16 v[100:103], v[104:107], v[200:203], v[100:103]
	v_mfma_f32_16x16x32_bf16 v[36:39], v[112:115], v[200:203], v[36:39]
	v_mfma_f32_16x16x32_bf16 v[156:159], v[108:111], v[164:167], v[156:159]
	v_mfma_f32_16x16x32_bf16 v[60:63], v[116:119], v[164:167], v[60:63]
	v_mfma_f32_16x16x32_bf16 v[148:151], v[108:111], v[172:175], v[148:151]
	v_mfma_f32_16x16x32_bf16 v[52:55], v[116:119], v[172:175], v[52:55]
	v_mfma_f32_16x16x32_bf16 v[140:143], v[108:111], v[196:199], v[140:143]
	v_mfma_f32_16x16x32_bf16 v[44:47], v[116:119], v[196:199], v[44:47]
	v_mfma_f32_16x16x32_bf16 v[100:103], v[108:111], v[204:207], v[100:103]
	v_mfma_f32_16x16x32_bf16 v[36:39], v[116:119], v[204:207], v[36:39]
	v_mfma_f32_16x16x32_bf16 v[152:155], v[120:123], v[160:163], v[152:155]
	v_mfma_f32_16x16x32_bf16 v[56:59], v[128:131], v[160:163], v[56:59]
	v_mfma_f32_16x16x32_bf16 v[144:147], v[120:123], v[168:171], v[144:147]
	v_mfma_f32_16x16x32_bf16 v[48:51], v[128:131], v[168:171], v[48:51]
	v_mfma_f32_16x16x32_bf16 v[136:139], v[120:123], v[192:195], v[136:139]
	v_mfma_f32_16x16x32_bf16 v[40:43], v[128:131], v[192:195], v[40:43]
	v_mfma_f32_16x16x32_bf16 v[96:99], v[120:123], v[200:203], v[96:99]
	v_mfma_f32_16x16x32_bf16 v[32:35], v[128:131], v[200:203], v[32:35]
	v_mfma_f32_16x16x32_bf16 v[152:155], v[124:127], v[164:167], v[152:155]
	v_mfma_f32_16x16x32_bf16 v[56:59], v[132:135], v[164:167], v[56:59]
	v_mfma_f32_16x16x32_bf16 v[144:147], v[124:127], v[172:175], v[144:147]
	v_mfma_f32_16x16x32_bf16 v[48:51], v[132:135], v[172:175], v[48:51]
	v_mfma_f32_16x16x32_bf16 v[136:139], v[124:127], v[196:199], v[136:139]
	v_mfma_f32_16x16x32_bf16 v[40:43], v[132:135], v[196:199], v[40:43]
	v_mfma_f32_16x16x32_bf16 v[96:99], v[124:127], v[204:207], v[96:99]
	v_mfma_f32_16x16x32_bf16 v[32:35], v[132:135], v[204:207], v[32:35]
	s_setprio 0
	s_barrier
	s_add_i32 s81, s33, s95
	v_lshl_add_u64 v[208:209], s[74:75], 0, v[178:179]
	s_mov_b32 m0, s81
	ds_read_b128 v[160:163], v235 offset:16384
	ds_read_b128 v[164:167], v235 offset:17408
	ds_read_b128 v[168:171], v235 offset:18432
	ds_read_b128 v[172:175], v235 offset:19456
	ds_read_b128 v[192:195], v235 offset:20480
	ds_read_b128 v[196:199], v235 offset:21504
	ds_read_b128 v[200:203], v235 offset:22528
	ds_read_b128 v[204:207], v235 offset:23552
	global_load_lds_dwordx4 v[208:209], off
	s_add_i32 m0, s81, 0x2000
	s_add_u32 s82, s74, 0x40000
	v_lshl_add_u64 v[210:211], s[74:75], 0, v[182:183]
	s_addc_u32 s83, s75, 0
	s_add_i32 s81, s0, s95
	global_load_lds_dwordx4 v[210:211], off
	v_lshl_add_u64 v[212:213], s[82:83], 0, v[178:179]
	s_mov_b32 m0, s81
	v_lshl_add_u64 v[214:215], s[76:77], 0, v[180:181]
	global_load_lds_dwordx4 v[212:213], off
	v_lshl_add_u64 v[212:213], s[82:83], 0, v[182:183]
	s_add_i32 m0, s81, 0x2000
	s_nop 0
	global_load_lds_dwordx4 v[212:213], off
	v_lshl_add_u64 v[212:213], s[76:77], 0, v[176:177]
	s_mov_b32 m0, s96
	s_nop 0
	global_load_lds_dwordx4 v[212:213], off
	s_mov_b32 m0, s97
	s_nop 0
	global_load_lds_dwordx4 v[214:215], off
	s_waitcnt vmcnt(8)
	s_waitcnt lgkmcnt(0)
	s_barrier
	s_setprio 1
	s_waitcnt lgkmcnt(0)
	v_mfma_f32_16x16x32_bf16 v[92:95], v[104:107], v[160:163], v[92:95]
	v_mfma_f32_16x16x32_bf16 v[28:31], v[112:115], v[160:163], v[28:31]
	v_mfma_f32_16x16x32_bf16 v[84:87], v[104:107], v[168:171], v[84:87]
	v_mfma_f32_16x16x32_bf16 v[20:23], v[112:115], v[168:171], v[20:23]
	v_mfma_f32_16x16x32_bf16 v[76:79], v[104:107], v[192:195], v[76:79]
	v_mfma_f32_16x16x32_bf16 v[12:15], v[112:115], v[192:195], v[12:15]
	v_mfma_f32_16x16x32_bf16 v[68:71], v[104:107], v[200:203], v[68:71]
	v_mfma_f32_16x16x32_bf16 v[4:7], v[112:115], v[200:203], v[4:7]
	v_mfma_f32_16x16x32_bf16 v[92:95], v[108:111], v[164:167], v[92:95]
	v_mfma_f32_16x16x32_bf16 v[28:31], v[116:119], v[164:167], v[28:31]
	v_mfma_f32_16x16x32_bf16 v[84:87], v[108:111], v[172:175], v[84:87]
	v_mfma_f32_16x16x32_bf16 v[20:23], v[116:119], v[172:175], v[20:23]
	v_mfma_f32_16x16x32_bf16 v[76:79], v[108:111], v[196:199], v[76:79]
	v_mfma_f32_16x16x32_bf16 v[12:15], v[116:119], v[196:199], v[12:15]
	v_mfma_f32_16x16x32_bf16 v[68:71], v[108:111], v[204:207], v[68:71]
	v_mfma_f32_16x16x32_bf16 v[4:7], v[116:119], v[204:207], v[4:7]
	v_mfma_f32_16x16x32_bf16 v[88:91], v[120:123], v[160:163], v[88:91]
	v_mfma_f32_16x16x32_bf16 v[24:27], v[128:131], v[160:163], v[24:27]
	v_mfma_f32_16x16x32_bf16 v[80:83], v[120:123], v[168:171], v[80:83]
	v_mfma_f32_16x16x32_bf16 v[16:19], v[128:131], v[168:171], v[16:19]
	v_mfma_f32_16x16x32_bf16 v[72:75], v[120:123], v[192:195], v[72:75]
	v_mfma_f32_16x16x32_bf16 v[8:11], v[128:131], v[192:195], v[8:11]
	v_mfma_f32_16x16x32_bf16 v[64:67], v[120:123], v[200:203], v[64:67]
	v_mfma_f32_16x16x32_bf16 v[0:3], v[128:131], v[200:203], v[0:3]
	v_mfma_f32_16x16x32_bf16 v[88:91], v[124:127], v[164:167], v[88:91]
	v_mfma_f32_16x16x32_bf16 v[24:27], v[132:135], v[164:167], v[24:27]
	v_mfma_f32_16x16x32_bf16 v[80:83], v[124:127], v[172:175], v[80:83]
	v_mfma_f32_16x16x32_bf16 v[16:19], v[132:135], v[172:175], v[16:19]
	v_mfma_f32_16x16x32_bf16 v[72:75], v[124:127], v[196:199], v[72:75]
	v_mfma_f32_16x16x32_bf16 v[8:11], v[132:135], v[196:199], v[8:11]
	v_mfma_f32_16x16x32_bf16 v[64:67], v[124:127], v[204:207], v[64:67]
	v_mfma_f32_16x16x32_bf16 v[0:3], v[132:135], v[204:207], v[0:3]
	s_setprio 0
	s_barrier
	s_add_i32 s81, 0, 0x18000
	s_add_i32 s82, 0, 0x1c000
	v_add_u32_e32 v116, s81, v221
	v_add_u32_e32 v132, s82, v221
	ds_read_b128 v[104:107], v116
	ds_read_b128 v[108:111], v116 offset:1024
	ds_read_b128 v[112:115], v116 offset:2048
	ds_read_b128 v[116:119], v116 offset:3072
	ds_read_b128 v[120:123], v132
	ds_read_b128 v[124:127], v132 offset:1024
	ds_read_b128 v[128:131], v132 offset:2048
	ds_read_b128 v[132:135], v132 offset:3072
	s_add_u32 s76, s76, 0x40000
	s_addc_u32 s77, s77, 0
	s_mov_b32 m0, s8
	v_lshl_add_u64 v[216:217], s[76:77], 0, v[176:177]
	ds_read_b128 v[160:163], v235 offset:32768
	ds_read_b128 v[164:167], v235 offset:33792
	ds_read_b128 v[168:171], v235 offset:34816
	ds_read_b128 v[172:175], v235 offset:35840
	ds_read_b128 v[192:195], v235 offset:36864
	ds_read_b128 v[196:199], v235 offset:37888
	ds_read_b128 v[200:203], v235 offset:38912
	ds_read_b128 v[204:207], v235 offset:39936
	global_load_lds_dwordx4 v[216:217], off
	v_lshl_add_u64 v[216:217], s[76:77], 0, v[180:181]
	s_mov_b32 m0, s9
	s_nop 0
	global_load_lds_dwordx4 v[216:217], off
	s_waitcnt vmcnt(8)
	s_waitcnt lgkmcnt(0)
	s_barrier
	s_setprio 1
	s_waitcnt lgkmcnt(0)
	v_mfma_f32_16x16x32_bf16 v[156:159], v[104:107], v[160:163], v[156:159]
	v_mfma_f32_16x16x32_bf16 v[60:63], v[112:115], v[160:163], v[60:63]
	v_mfma_f32_16x16x32_bf16 v[148:151], v[104:107], v[168:171], v[148:151]
	v_mfma_f32_16x16x32_bf16 v[52:55], v[112:115], v[168:171], v[52:55]
	v_mfma_f32_16x16x32_bf16 v[140:143], v[104:107], v[192:195], v[140:143]
	v_mfma_f32_16x16x32_bf16 v[44:47], v[112:115], v[192:195], v[44:47]
	v_mfma_f32_16x16x32_bf16 v[100:103], v[104:107], v[200:203], v[100:103]
	v_mfma_f32_16x16x32_bf16 v[36:39], v[112:115], v[200:203], v[36:39]
	v_mfma_f32_16x16x32_bf16 v[156:159], v[108:111], v[164:167], v[156:159]
	v_mfma_f32_16x16x32_bf16 v[60:63], v[116:119], v[164:167], v[60:63]
	v_mfma_f32_16x16x32_bf16 v[148:151], v[108:111], v[172:175], v[148:151]
	v_mfma_f32_16x16x32_bf16 v[52:55], v[116:119], v[172:175], v[52:55]
	v_mfma_f32_16x16x32_bf16 v[140:143], v[108:111], v[196:199], v[140:143]
	v_mfma_f32_16x16x32_bf16 v[44:47], v[116:119], v[196:199], v[44:47]
	v_mfma_f32_16x16x32_bf16 v[100:103], v[108:111], v[204:207], v[100:103]
	v_mfma_f32_16x16x32_bf16 v[36:39], v[116:119], v[204:207], v[36:39]
	v_mfma_f32_16x16x32_bf16 v[152:155], v[120:123], v[160:163], v[152:155]
	v_mfma_f32_16x16x32_bf16 v[56:59], v[128:131], v[160:163], v[56:59]
	v_mfma_f32_16x16x32_bf16 v[144:147], v[120:123], v[168:171], v[144:147]
	v_mfma_f32_16x16x32_bf16 v[48:51], v[128:131], v[168:171], v[48:51]
	v_mfma_f32_16x16x32_bf16 v[136:139], v[120:123], v[192:195], v[136:139]
	v_mfma_f32_16x16x32_bf16 v[40:43], v[128:131], v[192:195], v[40:43]
	v_mfma_f32_16x16x32_bf16 v[96:99], v[120:123], v[200:203], v[96:99]
	v_mfma_f32_16x16x32_bf16 v[32:35], v[128:131], v[200:203], v[32:35]
	v_mfma_f32_16x16x32_bf16 v[152:155], v[124:127], v[164:167], v[152:155]
	v_mfma_f32_16x16x32_bf16 v[56:59], v[132:135], v[164:167], v[56:59]
	v_mfma_f32_16x16x32_bf16 v[144:147], v[124:127], v[172:175], v[144:147]
	v_mfma_f32_16x16x32_bf16 v[48:51], v[132:135], v[172:175], v[48:51]
	v_mfma_f32_16x16x32_bf16 v[136:139], v[124:127], v[196:199], v[136:139]
	v_mfma_f32_16x16x32_bf16 v[40:43], v[132:135], v[196:199], v[40:43]
	v_mfma_f32_16x16x32_bf16 v[96:99], v[124:127], v[204:207], v[96:99]
	v_mfma_f32_16x16x32_bf16 v[32:35], v[132:135], v[204:207], v[32:35]
	s_setprio 0
	s_barrier
	s_add_i32 s76, s81, s95
	v_lshl_add_u64 v[208:209], v[208:209], 0, s[48:49]
	s_mov_b32 m0, s76
	ds_read_b128 v[160:163], v235 offset:49152
	ds_read_b128 v[164:167], v235 offset:50176
	ds_read_b128 v[168:171], v235 offset:51200
	ds_read_b128 v[172:175], v235 offset:52224
	ds_read_b128 v[192:195], v235 offset:53248
	ds_read_b128 v[196:199], v235 offset:54272
	ds_read_b128 v[200:203], v235 offset:55296
	ds_read_b128 v[204:207], v235 offset:56320
	global_load_lds_dwordx4 v[208:209], off
	s_add_i32 m0, s76, 0x2000
	s_add_u32 s74, s74, 0x40080
	v_lshl_add_u64 v[208:209], v[210:211], 0, s[48:49]
	s_addc_u32 s75, s75, 0
	s_add_i32 s76, s82, s95
	global_load_lds_dwordx4 v[208:209], off
	v_lshl_add_u64 v[208:209], s[74:75], 0, v[178:179]
	s_mov_b32 m0, s76
	s_nop 0
	global_load_lds_dwordx4 v[208:209], off
	v_lshl_add_u64 v[208:209], s[74:75], 0, v[182:183]
	s_add_i32 m0, s76, 0x2000
	s_nop 0
	global_load_lds_dwordx4 v[208:209], off
	v_lshl_add_u64 v[208:209], v[212:213], 0, s[48:49]
	s_mov_b32 m0, s5
	s_nop 0
	global_load_lds_dwordx4 v[208:209], off
	v_lshl_add_u64 v[208:209], v[214:215], 0, s[48:49]
	s_mov_b32 m0, s6
	s_nop 0
	global_load_lds_dwordx4 v[208:209], off
	s_waitcnt vmcnt(8)
	s_waitcnt lgkmcnt(0)
	s_barrier
	s_setprio 1
	s_waitcnt lgkmcnt(0)
	v_mfma_f32_16x16x32_bf16 v[92:95], v[104:107], v[160:163], v[92:95]
	v_mfma_f32_16x16x32_bf16 v[28:31], v[112:115], v[160:163], v[28:31]
	v_mfma_f32_16x16x32_bf16 v[84:87], v[104:107], v[168:171], v[84:87]
	v_mfma_f32_16x16x32_bf16 v[20:23], v[112:115], v[168:171], v[20:23]
	v_mfma_f32_16x16x32_bf16 v[76:79], v[104:107], v[192:195], v[76:79]
	v_mfma_f32_16x16x32_bf16 v[12:15], v[112:115], v[192:195], v[12:15]
	v_mfma_f32_16x16x32_bf16 v[68:71], v[104:107], v[200:203], v[68:71]
	v_mfma_f32_16x16x32_bf16 v[4:7], v[112:115], v[200:203], v[4:7]
	v_mfma_f32_16x16x32_bf16 v[92:95], v[108:111], v[164:167], v[92:95]
	v_mfma_f32_16x16x32_bf16 v[28:31], v[116:119], v[164:167], v[28:31]
	v_mfma_f32_16x16x32_bf16 v[84:87], v[108:111], v[172:175], v[84:87]
	v_mfma_f32_16x16x32_bf16 v[20:23], v[116:119], v[172:175], v[20:23]
	v_mfma_f32_16x16x32_bf16 v[76:79], v[108:111], v[196:199], v[76:79]
	v_mfma_f32_16x16x32_bf16 v[12:15], v[116:119], v[196:199], v[12:15]
	v_mfma_f32_16x16x32_bf16 v[68:71], v[108:111], v[204:207], v[68:71]
	v_mfma_f32_16x16x32_bf16 v[4:7], v[116:119], v[204:207], v[4:7]
	v_mfma_f32_16x16x32_bf16 v[88:91], v[120:123], v[160:163], v[88:91]
	v_mfma_f32_16x16x32_bf16 v[24:27], v[128:131], v[160:163], v[24:27]
	v_mfma_f32_16x16x32_bf16 v[80:83], v[120:123], v[168:171], v[80:83]
	v_mfma_f32_16x16x32_bf16 v[16:19], v[128:131], v[168:171], v[16:19]
	v_mfma_f32_16x16x32_bf16 v[72:75], v[120:123], v[192:195], v[72:75]
	v_mfma_f32_16x16x32_bf16 v[8:11], v[128:131], v[192:195], v[8:11]
	v_mfma_f32_16x16x32_bf16 v[64:67], v[120:123], v[200:203], v[64:67]
	v_mfma_f32_16x16x32_bf16 v[0:3], v[128:131], v[200:203], v[0:3]
	v_mfma_f32_16x16x32_bf16 v[88:91], v[124:127], v[164:167], v[88:91]
	v_mfma_f32_16x16x32_bf16 v[24:27], v[132:135], v[164:167], v[24:27]
	v_mfma_f32_16x16x32_bf16 v[80:83], v[124:127], v[172:175], v[80:83]
	v_mfma_f32_16x16x32_bf16 v[16:19], v[132:135], v[172:175], v[16:19]
	v_mfma_f32_16x16x32_bf16 v[72:75], v[124:127], v[196:199], v[72:75]
	v_mfma_f32_16x16x32_bf16 v[8:11], v[132:135], v[196:199], v[8:11]
	v_mfma_f32_16x16x32_bf16 v[64:67], v[124:127], v[204:207], v[64:67]
	v_mfma_f32_16x16x32_bf16 v[0:3], v[132:135], v[204:207], v[0:3]
	s_setprio 0
	s_barrier
	s_add_i32 s80, s80, 2
	s_add_u32 s78, s78, 0x100
	s_addc_u32 s79, s79, 0
	s_add_u32 s28, s28, 0x100
	s_addc_u32 s29, s29, 0
	s_cmp_gt_u32 s80, 13
	s_cbranch_scc0 .LBB0_3350
	s_and_b64 vcc, exec, s[50:51]
	s_cbranch_vccz .LBB0_3353
	s_barrier

.LBB0_3685:
	ds_read_b128 v[146:149], v153
	ds_read_b128 v[156:159], v153 offset:1024
	ds_read_b128 v[160:163], v153 offset:2048
	ds_read_b128 v[164:167], v153 offset:3072
	ds_read_b128 v[168:171], v154
	ds_read_b128 v[172:175], v154 offset:1024
	ds_read_b128 v[176:179], v154 offset:2048
	ds_read_b128 v[180:183], v154 offset:3072
	s_add_u32 s42, s40, 0xfffc0080
	s_addc_u32 s43, s41, -1
	s_cmp_eq_u32 s56, 12
	s_cselect_b32 s45, s23, s43
	s_cselect_b32 s44, s29, s42
	s_cselect_b32 s43, s21, s55
	s_cselect_b32 s42, s31, s54
	v_lshl_add_u64 v[216:217], s[40:41], 0, v[140:141]
	s_add_i32 m0, s6, 0xc000
	ds_read_b128 v[184:187], v155
	ds_read_b128 v[188:191], v155 offset:1024
	ds_read_b128 v[192:195], v155 offset:2048
	ds_read_b128 v[196:199], v155 offset:3072
	ds_read_b128 v[200:203], v155 offset:4096
	ds_read_b128 v[204:207], v155 offset:5120
	ds_read_b128 v[208:211], v155 offset:6144
	ds_read_b128 v[212:215], v155 offset:7168
	global_load_lds_dwordx4 v[216:217], off
	v_lshl_add_u64 v[216:217], s[40:41], 0, v[138:139]
	s_add_i32 m0, s6, 0xe000
	s_nop 0
	global_load_lds_dwordx4 v[216:217], off
	s_waitcnt vmcnt(8)
	s_waitcnt lgkmcnt(0)
	s_barrier
	s_setprio 1
	s_waitcnt lgkmcnt(0)
	v_mfma_f32_16x16x32_bf16 v[124:127], v[146:149], v[184:187], v[124:127]
	v_mfma_f32_16x16x32_bf16 v[120:123], v[160:163], v[184:187], v[120:123]
	v_mfma_f32_16x16x32_bf16 v[116:119], v[146:149], v[192:195], v[116:119]
	v_mfma_f32_16x16x32_bf16 v[112:115], v[160:163], v[192:195], v[112:115]
	v_mfma_f32_16x16x32_bf16 v[108:111], v[146:149], v[200:203], v[108:111]
	v_mfma_f32_16x16x32_bf16 v[104:107], v[160:163], v[200:203], v[104:107]
	v_mfma_f32_16x16x32_bf16 v[100:103], v[146:149], v[208:211], v[100:103]
	v_mfma_f32_16x16x32_bf16 v[96:99], v[160:163], v[208:211], v[96:99]
	v_mfma_f32_16x16x32_bf16 v[124:127], v[156:159], v[188:191], v[124:127]
	v_mfma_f32_16x16x32_bf16 v[120:123], v[164:167], v[188:191], v[120:123]
	v_mfma_f32_16x16x32_bf16 v[116:119], v[156:159], v[196:199], v[116:119]
	v_mfma_f32_16x16x32_bf16 v[112:115], v[164:167], v[196:199], v[112:115]
	v_mfma_f32_16x16x32_bf16 v[108:111], v[156:159], v[204:207], v[108:111]
	v_mfma_f32_16x16x32_bf16 v[104:107], v[164:167], v[204:207], v[104:107]
	v_mfma_f32_16x16x32_bf16 v[100:103], v[156:159], v[212:215], v[100:103]
	v_mfma_f32_16x16x32_bf16 v[96:99], v[164:167], v[212:215], v[96:99]
	v_mfma_f32_16x16x32_bf16 v[60:63], v[168:171], v[184:187], v[60:63]
	v_mfma_f32_16x16x32_bf16 v[56:59], v[176:179], v[184:187], v[56:59]
	v_mfma_f32_16x16x32_bf16 v[52:55], v[168:171], v[192:195], v[52:55]
	v_mfma_f32_16x16x32_bf16 v[48:51], v[176:179], v[192:195], v[48:51]
	v_mfma_f32_16x16x32_bf16 v[44:47], v[168:171], v[200:203], v[44:47]
	v_mfma_f32_16x16x32_bf16 v[40:43], v[176:179], v[200:203], v[40:43]
	v_mfma_f32_16x16x32_bf16 v[36:39], v[168:171], v[208:211], v[36:39]
	v_mfma_f32_16x16x32_bf16 v[32:35], v[176:179], v[208:211], v[32:35]
	v_mfma_f32_16x16x32_bf16 v[60:63], v[172:175], v[188:191], v[60:63]
	v_mfma_f32_16x16x32_bf16 v[56:59], v[180:183], v[188:191], v[56:59]
	v_mfma_f32_16x16x32_bf16 v[52:55], v[172:175], v[196:199], v[52:55]
	v_mfma_f32_16x16x32_bf16 v[48:51], v[180:183], v[196:199], v[48:51]
	v_mfma_f32_16x16x32_bf16 v[44:47], v[172:175], v[204:207], v[44:47]
	v_mfma_f32_16x16x32_bf16 v[40:43], v[180:183], v[204:207], v[40:43]
	v_mfma_f32_16x16x32_bf16 v[36:39], v[172:175], v[212:215], v[36:39]
	v_mfma_f32_16x16x32_bf16 v[32:35], v[180:183], v[212:215], v[32:35]
	s_setprio 0
	s_barrier
	s_add_i32 s57, s49, s5
	v_lshl_add_u64 v[216:217], s[42:43], 0, v[130:131]
	s_mov_b32 m0, s57
	ds_read_b128 v[184:187], v155 offset:16384
	ds_read_b128 v[188:191], v155 offset:17408
	ds_read_b128 v[192:195], v155 offset:18432
	ds_read_b128 v[196:199], v155 offset:19456
	ds_read_b128 v[200:203], v155 offset:20480
	ds_read_b128 v[204:207], v155 offset:21504
	ds_read_b128 v[208:211], v155 offset:22528
	ds_read_b128 v[212:215], v155 offset:23552
	global_load_lds_dwordx4 v[216:217], off
	s_add_i32 m0, s57, 0x2000
	s_add_u32 s58, s42, 0x40000
	v_lshl_add_u64 v[218:219], s[42:43], 0, v[134:135]
	s_addc_u32 s59, s43, 0
	s_add_i32 s57, s50, s5
	global_load_lds_dwordx4 v[218:219], off
	v_lshl_add_u64 v[220:221], s[58:59], 0, v[130:131]
	s_mov_b32 m0, s57
	v_lshl_add_u64 v[222:223], s[44:45], 0, v[132:133]
	global_load_lds_dwordx4 v[220:221], off
	v_lshl_add_u64 v[220:221], s[58:59], 0, v[134:135]
	s_add_i32 m0, s57, 0x2000
	s_nop 0
	global_load_lds_dwordx4 v[220:221], off
	v_lshl_add_u64 v[220:221], s[44:45], 0, v[128:129]
	s_mov_b32 m0, s6
	s_nop 0
	global_load_lds_dwordx4 v[220:221], off
	s_mov_b32 m0, s7
	s_nop 0
	global_load_lds_dwordx4 v[222:223], off
	s_waitcnt vmcnt(8)
	s_waitcnt lgkmcnt(0)
	s_barrier
	s_setprio 1
	s_waitcnt lgkmcnt(0)
	v_mfma_f32_16x16x32_bf16 v[92:95], v[146:149], v[184:187], v[92:95]
	v_mfma_f32_16x16x32_bf16 v[88:91], v[160:163], v[184:187], v[88:91]
	v_mfma_f32_16x16x32_bf16 v[84:87], v[146:149], v[192:195], v[84:87]
	v_mfma_f32_16x16x32_bf16 v[80:83], v[160:163], v[192:195], v[80:83]
	v_mfma_f32_16x16x32_bf16 v[76:79], v[146:149], v[200:203], v[76:79]
	v_mfma_f32_16x16x32_bf16 v[72:75], v[160:163], v[200:203], v[72:75]
	v_mfma_f32_16x16x32_bf16 v[68:71], v[146:149], v[208:211], v[68:71]
	v_mfma_f32_16x16x32_bf16 v[64:67], v[160:163], v[208:211], v[64:67]
	v_mfma_f32_16x16x32_bf16 v[92:95], v[156:159], v[188:191], v[92:95]
	v_mfma_f32_16x16x32_bf16 v[88:91], v[164:167], v[188:191], v[88:91]
	v_mfma_f32_16x16x32_bf16 v[84:87], v[156:159], v[196:199], v[84:87]
	v_mfma_f32_16x16x32_bf16 v[80:83], v[164:167], v[196:199], v[80:83]
	v_mfma_f32_16x16x32_bf16 v[76:79], v[156:159], v[204:207], v[76:79]
	v_mfma_f32_16x16x32_bf16 v[72:75], v[164:167], v[204:207], v[72:75]
	v_mfma_f32_16x16x32_bf16 v[68:71], v[156:159], v[212:215], v[68:71]
	v_mfma_f32_16x16x32_bf16 v[64:67], v[164:167], v[212:215], v[64:67]
	v_mfma_f32_16x16x32_bf16 v[28:31], v[168:171], v[184:187], v[28:31]
	v_mfma_f32_16x16x32_bf16 v[24:27], v[176:179], v[184:187], v[24:27]
	v_mfma_f32_16x16x32_bf16 v[20:23], v[168:171], v[192:195], v[20:23]
	v_mfma_f32_16x16x32_bf16 v[16:19], v[176:179], v[192:195], v[16:19]
	v_mfma_f32_16x16x32_bf16 v[12:15], v[168:171], v[200:203], v[12:15]
	v_mfma_f32_16x16x32_bf16 v[8:11], v[176:179], v[200:203], v[8:11]
	v_mfma_f32_16x16x32_bf16 v[4:7], v[168:171], v[208:211], v[4:7]
	v_mfma_f32_16x16x32_bf16 v[0:3], v[176:179], v[208:211], v[0:3]
	v_mfma_f32_16x16x32_bf16 v[28:31], v[172:175], v[188:191], v[28:31]
	v_mfma_f32_16x16x32_bf16 v[24:27], v[180:183], v[188:191], v[24:27]
	v_mfma_f32_16x16x32_bf16 v[20:23], v[172:175], v[196:199], v[20:23]
	v_mfma_f32_16x16x32_bf16 v[16:19], v[180:183], v[196:199], v[16:19]
	v_mfma_f32_16x16x32_bf16 v[12:15], v[172:175], v[204:207], v[12:15]
	v_mfma_f32_16x16x32_bf16 v[8:11], v[180:183], v[204:207], v[8:11]
	v_mfma_f32_16x16x32_bf16 v[4:7], v[172:175], v[212:215], v[4:7]
	v_mfma_f32_16x16x32_bf16 v[0:3], v[180:183], v[212:215], v[0:3]
	s_setprio 0
	s_barrier
	s_add_i32 s57, 0, 0x18000
	s_add_i32 s58, 0, 0x1c000
	v_add_u32_e32 v164, s57, v151
	v_add_u32_e32 v180, s58, v151
	ds_read_b128 v[146:149], v164
	ds_read_b128 v[156:159], v164 offset:1024
	ds_read_b128 v[160:163], v164 offset:2048
	ds_read_b128 v[164:167], v164 offset:3072
	ds_read_b128 v[168:171], v180
	ds_read_b128 v[172:175], v180 offset:1024
	ds_read_b128 v[176:179], v180 offset:2048
	ds_read_b128 v[180:183], v180 offset:3072
	s_add_u32 s44, s44, 0x40000
	s_addc_u32 s45, s45, 0
	s_mov_b32 m0, s33
	v_lshl_add_u64 v[224:225], s[44:45], 0, v[128:129]
	ds_read_b128 v[184:187], v155 offset:32768
	ds_read_b128 v[188:191], v155 offset:33792
	ds_read_b128 v[192:195], v155 offset:34816
	ds_read_b128 v[196:199], v155 offset:35840
	ds_read_b128 v[200:203], v155 offset:36864
	ds_read_b128 v[204:207], v155 offset:37888
	ds_read_b128 v[208:211], v155 offset:38912
	ds_read_b128 v[212:215], v155 offset:39936
	global_load_lds_dwordx4 v[224:225], off
	v_lshl_add_u64 v[224:225], s[44:45], 0, v[132:133]
	s_mov_b32 m0, s35
	s_nop 0
	global_load_lds_dwordx4 v[224:225], off
	s_waitcnt vmcnt(8)
	s_waitcnt lgkmcnt(0)
	s_barrier
	s_setprio 1
	s_waitcnt lgkmcnt(0)
	v_mfma_f32_16x16x32_bf16 v[124:127], v[146:149], v[184:187], v[124:127]
	v_mfma_f32_16x16x32_bf16 v[120:123], v[160:163], v[184:187], v[120:123]
	v_mfma_f32_16x16x32_bf16 v[116:119], v[146:149], v[192:195], v[116:119]
	v_mfma_f32_16x16x32_bf16 v[112:115], v[160:163], v[192:195], v[112:115]
	v_mfma_f32_16x16x32_bf16 v[108:111], v[146:149], v[200:203], v[108:111]
	v_mfma_f32_16x16x32_bf16 v[104:107], v[160:163], v[200:203], v[104:107]
	v_mfma_f32_16x16x32_bf16 v[100:103], v[146:149], v[208:211], v[100:103]
	v_mfma_f32_16x16x32_bf16 v[96:99], v[160:163], v[208:211], v[96:99]
	v_mfma_f32_16x16x32_bf16 v[124:127], v[156:159], v[188:191], v[124:127]
	v_mfma_f32_16x16x32_bf16 v[120:123], v[164:167], v[188:191], v[120:123]
	v_mfma_f32_16x16x32_bf16 v[116:119], v[156:159], v[196:199], v[116:119]
	v_mfma_f32_16x16x32_bf16 v[112:115], v[164:167], v[196:199], v[112:115]
	v_mfma_f32_16x16x32_bf16 v[108:111], v[156:159], v[204:207], v[108:111]
	v_mfma_f32_16x16x32_bf16 v[104:107], v[164:167], v[204:207], v[104:107]
	v_mfma_f32_16x16x32_bf16 v[100:103], v[156:159], v[212:215], v[100:103]
	v_mfma_f32_16x16x32_bf16 v[96:99], v[164:167], v[212:215], v[96:99]
	v_mfma_f32_16x16x32_bf16 v[60:63], v[168:171], v[184:187], v[60:63]
	v_mfma_f32_16x16x32_bf16 v[56:59], v[176:179], v[184:187], v[56:59]
	v_mfma_f32_16x16x32_bf16 v[52:55], v[168:171], v[192:195], v[52:55]
	v_mfma_f32_16x16x32_bf16 v[48:51], v[176:179], v[192:195], v[48:51]
	v_mfma_f32_16x16x32_bf16 v[44:47], v[168:171], v[200:203], v[44:47]
	v_mfma_f32_16x16x32_bf16 v[40:43], v[176:179], v[200:203], v[40:43]
	v_mfma_f32_16x16x32_bf16 v[36:39], v[168:171], v[208:211], v[36:39]
	v_mfma_f32_16x16x32_bf16 v[32:35], v[176:179], v[208:211], v[32:35]
	v_mfma_f32_16x16x32_bf16 v[60:63], v[172:175], v[188:191], v[60:63]
	v_mfma_f32_16x16x32_bf16 v[56:59], v[180:183], v[188:191], v[56:59]
	v_mfma_f32_16x16x32_bf16 v[52:55], v[172:175], v[196:199], v[52:55]
	v_mfma_f32_16x16x32_bf16 v[48:51], v[180:183], v[196:199], v[48:51]
	v_mfma_f32_16x16x32_bf16 v[44:47], v[172:175], v[204:207], v[44:47]
	v_mfma_f32_16x16x32_bf16 v[40:43], v[180:183], v[204:207], v[40:43]
	v_mfma_f32_16x16x32_bf16 v[36:39], v[172:175], v[212:215], v[36:39]
	v_mfma_f32_16x16x32_bf16 v[32:35], v[180:183], v[212:215], v[32:35]
	s_setprio 0
	s_barrier
	s_add_i32 s44, s57, s5
	v_lshl_add_u64 v[216:217], v[216:217], 0, s[16:17]
	s_mov_b32 m0, s44
	ds_read_b128 v[184:187], v155 offset:49152
	ds_read_b128 v[188:191], v155 offset:50176
	ds_read_b128 v[192:195], v155 offset:51200
	ds_read_b128 v[196:199], v155 offset:52224
	ds_read_b128 v[200:203], v155 offset:53248
	ds_read_b128 v[204:207], v155 offset:54272
	ds_read_b128 v[208:211], v155 offset:55296
	ds_read_b128 v[212:215], v155 offset:56320
	global_load_lds_dwordx4 v[216:217], off
	s_add_i32 m0, s44, 0x2000
	s_add_u32 s42, s42, 0x40080
	v_lshl_add_u64 v[216:217], v[218:219], 0, s[16:17]
	s_addc_u32 s43, s43, 0
	s_add_i32 s44, s58, s5
	global_load_lds_dwordx4 v[216:217], off
	v_lshl_add_u64 v[216:217], s[42:43], 0, v[130:131]
	s_mov_b32 m0, s44
	s_nop 0
	global_load_lds_dwordx4 v[216:217], off
	v_lshl_add_u64 v[216:217], s[42:43], 0, v[134:135]
	s_add_i32 m0, s44, 0x2000
	s_nop 0
	global_load_lds_dwordx4 v[216:217], off
	v_lshl_add_u64 v[216:217], v[220:221], 0, s[16:17]
	s_mov_b32 m0, s37
	s_nop 0
	global_load_lds_dwordx4 v[216:217], off
	v_lshl_add_u64 v[216:217], v[222:223], 0, s[16:17]
	s_mov_b32 m0, s38
	s_nop 0
	global_load_lds_dwordx4 v[216:217], off
	s_waitcnt vmcnt(8)
	s_waitcnt lgkmcnt(0)
	s_barrier
	s_setprio 1
	s_waitcnt lgkmcnt(0)
	v_mfma_f32_16x16x32_bf16 v[92:95], v[146:149], v[184:187], v[92:95]
	v_mfma_f32_16x16x32_bf16 v[88:91], v[160:163], v[184:187], v[88:91]
	v_mfma_f32_16x16x32_bf16 v[84:87], v[146:149], v[192:195], v[84:87]
	v_mfma_f32_16x16x32_bf16 v[80:83], v[160:163], v[192:195], v[80:83]
	v_mfma_f32_16x16x32_bf16 v[76:79], v[146:149], v[200:203], v[76:79]
	v_mfma_f32_16x16x32_bf16 v[72:75], v[160:163], v[200:203], v[72:75]
	v_mfma_f32_16x16x32_bf16 v[68:71], v[146:149], v[208:211], v[68:71]
	v_mfma_f32_16x16x32_bf16 v[64:67], v[160:163], v[208:211], v[64:67]
	v_mfma_f32_16x16x32_bf16 v[92:95], v[156:159], v[188:191], v[92:95]
	v_mfma_f32_16x16x32_bf16 v[88:91], v[164:167], v[188:191], v[88:91]
	v_mfma_f32_16x16x32_bf16 v[84:87], v[156:159], v[196:199], v[84:87]
	v_mfma_f32_16x16x32_bf16 v[80:83], v[164:167], v[196:199], v[80:83]
	v_mfma_f32_16x16x32_bf16 v[76:79], v[156:159], v[204:207], v[76:79]
	v_mfma_f32_16x16x32_bf16 v[72:75], v[164:167], v[204:207], v[72:75]
	v_mfma_f32_16x16x32_bf16 v[68:71], v[156:159], v[212:215], v[68:71]
	v_mfma_f32_16x16x32_bf16 v[64:67], v[164:167], v[212:215], v[64:67]
	v_mfma_f32_16x16x32_bf16 v[28:31], v[168:171], v[184:187], v[28:31]
	v_mfma_f32_16x16x32_bf16 v[24:27], v[176:179], v[184:187], v[24:27]
	v_mfma_f32_16x16x32_bf16 v[20:23], v[168:171], v[192:195], v[20:23]
	v_mfma_f32_16x16x32_bf16 v[16:19], v[176:179], v[192:195], v[16:19]
	v_mfma_f32_16x16x32_bf16 v[12:15], v[168:171], v[200:203], v[12:15]
	v_mfma_f32_16x16x32_bf16 v[8:11], v[176:179], v[200:203], v[8:11]
	v_mfma_f32_16x16x32_bf16 v[4:7], v[168:171], v[208:211], v[4:7]
	v_mfma_f32_16x16x32_bf16 v[0:3], v[176:179], v[208:211], v[0:3]
	v_mfma_f32_16x16x32_bf16 v[28:31], v[172:175], v[188:191], v[28:31]
	v_mfma_f32_16x16x32_bf16 v[24:27], v[180:183], v[188:191], v[24:27]
	v_mfma_f32_16x16x32_bf16 v[20:23], v[172:175], v[196:199], v[20:23]
	v_mfma_f32_16x16x32_bf16 v[16:19], v[180:183], v[196:199], v[16:19]
	v_mfma_f32_16x16x32_bf16 v[12:15], v[172:175], v[204:207], v[12:15]
	v_mfma_f32_16x16x32_bf16 v[8:11], v[180:183], v[204:207], v[8:11]
	v_mfma_f32_16x16x32_bf16 v[4:7], v[172:175], v[212:215], v[4:7]
	v_mfma_f32_16x16x32_bf16 v[0:3], v[180:183], v[212:215], v[0:3]
	s_setprio 0
	s_barrier
	s_add_i32 s56, s56, 2
	s_add_u32 s54, s54, 0x100
	s_addc_u32 s55, s55, 0
	s_add_u32 s40, s40, 0x100
	s_addc_u32 s41, s41, 0
	s_cmp_gt_u32 s56, 13
	s_cbranch_scc0 .LBB0_3685
	s_and_b64 vcc, exec, s[18:19]
	s_cbranch_vccz .LBB0_3688
	s_barrier

.LBB0_3906:
	ds_read_b128 v[144:147], v157
	ds_read_b128 v[148:151], v157 offset:1024
	ds_read_b128 v[160:163], v157 offset:2048
	ds_read_b128 v[164:167], v157 offset:3072
	ds_read_b128 v[168:171], v158
	ds_read_b128 v[172:175], v158 offset:1024
	ds_read_b128 v[176:179], v158 offset:2048
	ds_read_b128 v[180:183], v158 offset:3072
	s_add_u32 s30, s28, 0xfffc0080
	s_addc_u32 s31, s29, -1
	s_cmp_eq_u32 s54, 12
	s_cselect_b32 s39, s21, s31
	s_cselect_b32 s38, s50, s30
	s_cselect_b32 s31, s19, s53
	s_cselect_b32 s30, s51, s52
	v_lshl_add_u64 v[152:153], s[28:29], 0, v[138:139]
	s_add_i32 m0, s7, 0xc000
	ds_read_b128 v[184:187], v159
	ds_read_b128 v[188:191], v159 offset:1024
	ds_read_b128 v[192:195], v159 offset:2048
	ds_read_b128 v[196:199], v159 offset:3072
	ds_read_b128 v[200:203], v159 offset:4096
	ds_read_b128 v[204:207], v159 offset:5120
	ds_read_b128 v[208:211], v159 offset:6144
	ds_read_b128 v[212:215], v159 offset:7168
	global_load_lds_dwordx4 v[152:153], off
	v_lshl_add_u64 v[152:153], s[28:29], 0, v[136:137]
	s_add_i32 m0, s7, 0xe000
	s_nop 0
	global_load_lds_dwordx4 v[152:153], off
	s_waitcnt vmcnt(8)
	s_waitcnt lgkmcnt(0)
	s_barrier
	s_setprio 1
	s_waitcnt lgkmcnt(0)
	v_mfma_f32_16x16x32_bf16 v[124:127], v[144:147], v[184:187], v[124:127]
	v_mfma_f32_16x16x32_bf16 v[120:123], v[160:163], v[184:187], v[120:123]
	v_mfma_f32_16x16x32_bf16 v[116:119], v[144:147], v[192:195], v[116:119]
	v_mfma_f32_16x16x32_bf16 v[112:115], v[160:163], v[192:195], v[112:115]
	v_mfma_f32_16x16x32_bf16 v[108:111], v[144:147], v[200:203], v[108:111]
	v_mfma_f32_16x16x32_bf16 v[104:107], v[160:163], v[200:203], v[104:107]
	v_mfma_f32_16x16x32_bf16 v[100:103], v[144:147], v[208:211], v[100:103]
	v_mfma_f32_16x16x32_bf16 v[96:99], v[160:163], v[208:211], v[96:99]
	v_mfma_f32_16x16x32_bf16 v[124:127], v[148:151], v[188:191], v[124:127]
	v_mfma_f32_16x16x32_bf16 v[120:123], v[164:167], v[188:191], v[120:123]
	v_mfma_f32_16x16x32_bf16 v[116:119], v[148:151], v[196:199], v[116:119]
	v_mfma_f32_16x16x32_bf16 v[112:115], v[164:167], v[196:199], v[112:115]
	v_mfma_f32_16x16x32_bf16 v[108:111], v[148:151], v[204:207], v[108:111]
	v_mfma_f32_16x16x32_bf16 v[104:107], v[164:167], v[204:207], v[104:107]
	v_mfma_f32_16x16x32_bf16 v[100:103], v[148:151], v[212:215], v[100:103]
	v_mfma_f32_16x16x32_bf16 v[96:99], v[164:167], v[212:215], v[96:99]
	v_mfma_f32_16x16x32_bf16 v[76:79], v[168:171], v[184:187], v[76:79]
	v_mfma_f32_16x16x32_bf16 v[72:75], v[176:179], v[184:187], v[72:75]
	v_mfma_f32_16x16x32_bf16 v[60:63], v[168:171], v[192:195], v[60:63]
	v_mfma_f32_16x16x32_bf16 v[52:55], v[176:179], v[192:195], v[52:55]
	v_mfma_f32_16x16x32_bf16 v[44:47], v[168:171], v[200:203], v[44:47]
	v_mfma_f32_16x16x32_bf16 v[40:43], v[176:179], v[200:203], v[40:43]
	v_mfma_f32_16x16x32_bf16 v[36:39], v[168:171], v[208:211], v[36:39]
	v_mfma_f32_16x16x32_bf16 v[32:35], v[176:179], v[208:211], v[32:35]
	v_mfma_f32_16x16x32_bf16 v[76:79], v[172:175], v[188:191], v[76:79]
	v_mfma_f32_16x16x32_bf16 v[72:75], v[180:183], v[188:191], v[72:75]
	v_mfma_f32_16x16x32_bf16 v[60:63], v[172:175], v[196:199], v[60:63]
	v_mfma_f32_16x16x32_bf16 v[52:55], v[180:183], v[196:199], v[52:55]
	v_mfma_f32_16x16x32_bf16 v[44:47], v[172:175], v[204:207], v[44:47]
	v_mfma_f32_16x16x32_bf16 v[40:43], v[180:183], v[204:207], v[40:43]
	v_mfma_f32_16x16x32_bf16 v[36:39], v[172:175], v[212:215], v[36:39]
	v_mfma_f32_16x16x32_bf16 v[32:35], v[180:183], v[212:215], v[32:35]
	s_setprio 0
	s_barrier
	s_add_i32 s55, s45, s6
	v_lshl_add_u64 v[152:153], s[30:31], 0, v[130:131]
	s_mov_b32 m0, s55
	ds_read_b128 v[184:187], v159 offset:16384
	ds_read_b128 v[188:191], v159 offset:17408
	ds_read_b128 v[192:195], v159 offset:18432
	ds_read_b128 v[196:199], v159 offset:19456
	ds_read_b128 v[200:203], v159 offset:20480
	ds_read_b128 v[204:207], v159 offset:21504
	ds_read_b128 v[208:211], v159 offset:22528
	ds_read_b128 v[212:215], v159 offset:23552
	global_load_lds_dwordx4 v[152:153], off
	s_add_i32 m0, s55, 0x2000
	s_add_u32 s56, s30, 0x40000
	v_lshl_add_u64 v[216:217], s[30:31], 0, v[134:135]
	s_addc_u32 s57, s31, 0
	s_add_i32 s55, s46, s6
	global_load_lds_dwordx4 v[216:217], off
	v_lshl_add_u64 v[218:219], s[56:57], 0, v[130:131]
	s_mov_b32 m0, s55
	v_lshl_add_u64 v[220:221], s[38:39], 0, v[132:133]
	global_load_lds_dwordx4 v[218:219], off
	v_lshl_add_u64 v[218:219], s[56:57], 0, v[134:135]
	s_add_i32 m0, s55, 0x2000
	s_nop 0
	global_load_lds_dwordx4 v[218:219], off
	v_lshl_add_u64 v[218:219], s[38:39], 0, v[128:129]
	s_mov_b32 m0, s7
	s_nop 0
	global_load_lds_dwordx4 v[218:219], off
	s_mov_b32 m0, s33
	s_nop 0
	global_load_lds_dwordx4 v[220:221], off
	s_waitcnt vmcnt(8)
	s_waitcnt lgkmcnt(0)
	s_barrier
	s_setprio 1
	s_waitcnt lgkmcnt(0)
	v_mfma_f32_16x16x32_bf16 v[92:95], v[144:147], v[184:187], v[92:95]
	v_mfma_f32_16x16x32_bf16 v[88:91], v[160:163], v[184:187], v[88:91]
	v_mfma_f32_16x16x32_bf16 v[84:87], v[144:147], v[192:195], v[84:87]
	v_mfma_f32_16x16x32_bf16 v[80:83], v[160:163], v[192:195], v[80:83]
	v_mfma_f32_16x16x32_bf16 v[68:71], v[144:147], v[200:203], v[68:71]
	v_mfma_f32_16x16x32_bf16 v[64:67], v[160:163], v[200:203], v[64:67]
	v_mfma_f32_16x16x32_bf16 v[56:59], v[144:147], v[208:211], v[56:59]
	v_mfma_f32_16x16x32_bf16 v[48:51], v[160:163], v[208:211], v[48:51]
	v_mfma_f32_16x16x32_bf16 v[92:95], v[148:151], v[188:191], v[92:95]
	v_mfma_f32_16x16x32_bf16 v[88:91], v[164:167], v[188:191], v[88:91]
	v_mfma_f32_16x16x32_bf16 v[84:87], v[148:151], v[196:199], v[84:87]
	v_mfma_f32_16x16x32_bf16 v[80:83], v[164:167], v[196:199], v[80:83]
	v_mfma_f32_16x16x32_bf16 v[68:71], v[148:151], v[204:207], v[68:71]
	v_mfma_f32_16x16x32_bf16 v[64:67], v[164:167], v[204:207], v[64:67]
	v_mfma_f32_16x16x32_bf16 v[56:59], v[148:151], v[212:215], v[56:59]
	v_mfma_f32_16x16x32_bf16 v[48:51], v[164:167], v[212:215], v[48:51]
	v_mfma_f32_16x16x32_bf16 v[28:31], v[168:171], v[184:187], v[28:31]
	v_mfma_f32_16x16x32_bf16 v[24:27], v[176:179], v[184:187], v[24:27]
	v_mfma_f32_16x16x32_bf16 v[20:23], v[168:171], v[192:195], v[20:23]
	v_mfma_f32_16x16x32_bf16 v[16:19], v[176:179], v[192:195], v[16:19]
	v_mfma_f32_16x16x32_bf16 v[12:15], v[168:171], v[200:203], v[12:15]
	v_mfma_f32_16x16x32_bf16 v[8:11], v[176:179], v[200:203], v[8:11]
	v_mfma_f32_16x16x32_bf16 v[4:7], v[168:171], v[208:211], v[4:7]
	v_mfma_f32_16x16x32_bf16 v[0:3], v[176:179], v[208:211], v[0:3]
	v_mfma_f32_16x16x32_bf16 v[28:31], v[172:175], v[188:191], v[28:31]
	v_mfma_f32_16x16x32_bf16 v[24:27], v[180:183], v[188:191], v[24:27]
	v_mfma_f32_16x16x32_bf16 v[20:23], v[172:175], v[196:199], v[20:23]
	v_mfma_f32_16x16x32_bf16 v[16:19], v[180:183], v[196:199], v[16:19]
	v_mfma_f32_16x16x32_bf16 v[12:15], v[172:175], v[204:207], v[12:15]
	v_mfma_f32_16x16x32_bf16 v[8:11], v[180:183], v[204:207], v[8:11]
	v_mfma_f32_16x16x32_bf16 v[4:7], v[172:175], v[212:215], v[4:7]
	v_mfma_f32_16x16x32_bf16 v[0:3], v[180:183], v[212:215], v[0:3]
	s_setprio 0
	s_barrier
	s_add_i32 s55, 0, 0x18000
	s_add_i32 s56, 0, 0x1c000
	v_add_u32_e32 v164, s55, v155
	v_add_u32_e32 v180, s56, v155
	ds_read_b128 v[144:147], v164
	ds_read_b128 v[148:151], v164 offset:1024
	ds_read_b128 v[160:163], v164 offset:2048
	ds_read_b128 v[164:167], v164 offset:3072
	ds_read_b128 v[168:171], v180
	ds_read_b128 v[172:175], v180 offset:1024
	ds_read_b128 v[176:179], v180 offset:2048
	ds_read_b128 v[180:183], v180 offset:3072
	s_add_u32 s38, s38, 0x40000
	s_addc_u32 s39, s39, 0
	s_mov_b32 m0, s35
	v_lshl_add_u64 v[222:223], s[38:39], 0, v[128:129]
	ds_read_b128 v[184:187], v159 offset:32768
	ds_read_b128 v[188:191], v159 offset:33792
	ds_read_b128 v[192:195], v159 offset:34816
	ds_read_b128 v[196:199], v159 offset:35840
	ds_read_b128 v[200:203], v159 offset:36864
	ds_read_b128 v[204:207], v159 offset:37888
	ds_read_b128 v[208:211], v159 offset:38912
	ds_read_b128 v[212:215], v159 offset:39936
	global_load_lds_dwordx4 v[222:223], off
	v_lshl_add_u64 v[222:223], s[38:39], 0, v[132:133]
	s_mov_b32 m0, s36
	s_nop 0
	global_load_lds_dwordx4 v[222:223], off
	s_waitcnt vmcnt(8)
	s_waitcnt lgkmcnt(0)
	s_barrier
	s_setprio 1
	s_waitcnt lgkmcnt(0)
	v_mfma_f32_16x16x32_bf16 v[124:127], v[144:147], v[184:187], v[124:127]
	v_mfma_f32_16x16x32_bf16 v[120:123], v[160:163], v[184:187], v[120:123]
	v_mfma_f32_16x16x32_bf16 v[116:119], v[144:147], v[192:195], v[116:119]
	v_mfma_f32_16x16x32_bf16 v[112:115], v[160:163], v[192:195], v[112:115]
	v_mfma_f32_16x16x32_bf16 v[108:111], v[144:147], v[200:203], v[108:111]
	v_mfma_f32_16x16x32_bf16 v[104:107], v[160:163], v[200:203], v[104:107]
	v_mfma_f32_16x16x32_bf16 v[100:103], v[144:147], v[208:211], v[100:103]
	v_mfma_f32_16x16x32_bf16 v[96:99], v[160:163], v[208:211], v[96:99]
	v_mfma_f32_16x16x32_bf16 v[124:127], v[148:151], v[188:191], v[124:127]
	v_mfma_f32_16x16x32_bf16 v[120:123], v[164:167], v[188:191], v[120:123]
	v_mfma_f32_16x16x32_bf16 v[116:119], v[148:151], v[196:199], v[116:119]
	v_mfma_f32_16x16x32_bf16 v[112:115], v[164:167], v[196:199], v[112:115]
	v_mfma_f32_16x16x32_bf16 v[108:111], v[148:151], v[204:207], v[108:111]
	v_mfma_f32_16x16x32_bf16 v[104:107], v[164:167], v[204:207], v[104:107]
	v_mfma_f32_16x16x32_bf16 v[100:103], v[148:151], v[212:215], v[100:103]
	v_mfma_f32_16x16x32_bf16 v[96:99], v[164:167], v[212:215], v[96:99]
	v_mfma_f32_16x16x32_bf16 v[76:79], v[168:171], v[184:187], v[76:79]
	v_mfma_f32_16x16x32_bf16 v[72:75], v[176:179], v[184:187], v[72:75]
	v_mfma_f32_16x16x32_bf16 v[60:63], v[168:171], v[192:195], v[60:63]
	v_mfma_f32_16x16x32_bf16 v[52:55], v[176:179], v[192:195], v[52:55]
	v_mfma_f32_16x16x32_bf16 v[44:47], v[168:171], v[200:203], v[44:47]
	v_mfma_f32_16x16x32_bf16 v[40:43], v[176:179], v[200:203], v[40:43]
	v_mfma_f32_16x16x32_bf16 v[36:39], v[168:171], v[208:211], v[36:39]
	v_mfma_f32_16x16x32_bf16 v[32:35], v[176:179], v[208:211], v[32:35]
	v_mfma_f32_16x16x32_bf16 v[76:79], v[172:175], v[188:191], v[76:79]
	v_mfma_f32_16x16x32_bf16 v[72:75], v[180:183], v[188:191], v[72:75]
	v_mfma_f32_16x16x32_bf16 v[60:63], v[172:175], v[196:199], v[60:63]
	v_mfma_f32_16x16x32_bf16 v[52:55], v[180:183], v[196:199], v[52:55]
	v_mfma_f32_16x16x32_bf16 v[44:47], v[172:175], v[204:207], v[44:47]
	v_mfma_f32_16x16x32_bf16 v[40:43], v[180:183], v[204:207], v[40:43]
	v_mfma_f32_16x16x32_bf16 v[36:39], v[172:175], v[212:215], v[36:39]
	v_mfma_f32_16x16x32_bf16 v[32:35], v[180:183], v[212:215], v[32:35]
	s_setprio 0
	s_barrier
	s_add_i32 s38, s55, s6
	v_lshl_add_u64 v[152:153], v[152:153], 0, s[14:15]
	s_mov_b32 m0, s38
	ds_read_b128 v[184:187], v159 offset:49152
	ds_read_b128 v[188:191], v159 offset:50176
	ds_read_b128 v[192:195], v159 offset:51200
	ds_read_b128 v[196:199], v159 offset:52224
	ds_read_b128 v[200:203], v159 offset:53248
	ds_read_b128 v[204:207], v159 offset:54272
	ds_read_b128 v[208:211], v159 offset:55296
	ds_read_b128 v[212:215], v159 offset:56320
	global_load_lds_dwordx4 v[152:153], off
	s_add_i32 m0, s38, 0x2000
	s_add_u32 s30, s30, 0x40080
	v_lshl_add_u64 v[152:153], v[216:217], 0, s[14:15]
	s_addc_u32 s31, s31, 0
	s_add_i32 s38, s56, s6
	global_load_lds_dwordx4 v[152:153], off
	v_lshl_add_u64 v[152:153], s[30:31], 0, v[130:131]
	s_mov_b32 m0, s38
	s_nop 0
	global_load_lds_dwordx4 v[152:153], off
	v_lshl_add_u64 v[152:153], s[30:31], 0, v[134:135]
	s_add_i32 m0, s38, 0x2000
	s_nop 0
	global_load_lds_dwordx4 v[152:153], off
	v_lshl_add_u64 v[152:153], v[218:219], 0, s[14:15]
	s_mov_b32 m0, s41
	s_nop 0
	global_load_lds_dwordx4 v[152:153], off
	v_lshl_add_u64 v[152:153], v[220:221], 0, s[14:15]
	s_mov_b32 m0, s42
	s_nop 0
	global_load_lds_dwordx4 v[152:153], off
	s_waitcnt vmcnt(8)
	s_waitcnt lgkmcnt(0)
	s_barrier
	s_setprio 1
	s_waitcnt lgkmcnt(0)
	v_mfma_f32_16x16x32_bf16 v[92:95], v[144:147], v[184:187], v[92:95]
	v_mfma_f32_16x16x32_bf16 v[88:91], v[160:163], v[184:187], v[88:91]
	v_mfma_f32_16x16x32_bf16 v[84:87], v[144:147], v[192:195], v[84:87]
	v_mfma_f32_16x16x32_bf16 v[80:83], v[160:163], v[192:195], v[80:83]
	v_mfma_f32_16x16x32_bf16 v[68:71], v[144:147], v[200:203], v[68:71]
	v_mfma_f32_16x16x32_bf16 v[64:67], v[160:163], v[200:203], v[64:67]
	v_mfma_f32_16x16x32_bf16 v[56:59], v[144:147], v[208:211], v[56:59]
	v_mfma_f32_16x16x32_bf16 v[48:51], v[160:163], v[208:211], v[48:51]
	v_mfma_f32_16x16x32_bf16 v[92:95], v[148:151], v[188:191], v[92:95]
	v_mfma_f32_16x16x32_bf16 v[88:91], v[164:167], v[188:191], v[88:91]
	v_mfma_f32_16x16x32_bf16 v[84:87], v[148:151], v[196:199], v[84:87]
	v_mfma_f32_16x16x32_bf16 v[80:83], v[164:167], v[196:199], v[80:83]
	v_mfma_f32_16x16x32_bf16 v[68:71], v[148:151], v[204:207], v[68:71]
	v_mfma_f32_16x16x32_bf16 v[64:67], v[164:167], v[204:207], v[64:67]
	v_mfma_f32_16x16x32_bf16 v[56:59], v[148:151], v[212:215], v[56:59]
	v_mfma_f32_16x16x32_bf16 v[48:51], v[164:167], v[212:215], v[48:51]
	v_mfma_f32_16x16x32_bf16 v[28:31], v[168:171], v[184:187], v[28:31]
	v_mfma_f32_16x16x32_bf16 v[24:27], v[176:179], v[184:187], v[24:27]
	v_mfma_f32_16x16x32_bf16 v[20:23], v[168:171], v[192:195], v[20:23]
	v_mfma_f32_16x16x32_bf16 v[16:19], v[176:179], v[192:195], v[16:19]
	v_mfma_f32_16x16x32_bf16 v[12:15], v[168:171], v[200:203], v[12:15]
	v_mfma_f32_16x16x32_bf16 v[8:11], v[176:179], v[200:203], v[8:11]
	v_mfma_f32_16x16x32_bf16 v[4:7], v[168:171], v[208:211], v[4:7]
	v_mfma_f32_16x16x32_bf16 v[0:3], v[176:179], v[208:211], v[0:3]
	v_mfma_f32_16x16x32_bf16 v[28:31], v[172:175], v[188:191], v[28:31]
	v_mfma_f32_16x16x32_bf16 v[24:27], v[180:183], v[188:191], v[24:27]
	v_mfma_f32_16x16x32_bf16 v[20:23], v[172:175], v[196:199], v[20:23]
	v_mfma_f32_16x16x32_bf16 v[16:19], v[180:183], v[196:199], v[16:19]
	v_mfma_f32_16x16x32_bf16 v[12:15], v[172:175], v[204:207], v[12:15]
	v_mfma_f32_16x16x32_bf16 v[8:11], v[180:183], v[204:207], v[8:11]
	v_mfma_f32_16x16x32_bf16 v[4:7], v[172:175], v[212:215], v[4:7]
	v_mfma_f32_16x16x32_bf16 v[0:3], v[180:183], v[212:215], v[0:3]
	s_setprio 0
	s_barrier
	s_add_i32 s54, s54, 2
	s_add_u32 s52, s52, 0x100
	s_addc_u32 s53, s53, 0
	s_add_u32 s28, s28, 0x100
	s_addc_u32 s29, s29, 0
	s_cmp_gt_u32 s54, 13
	s_cbranch_scc0 .LBB0_3906
	s_and_b64 vcc, exec, s[16:17]
	s_cbranch_vccz .LBB0_3909
	s_barrier

.LBB0_4039:
	ds_read_b128 v[104:107], v233
	ds_read_b128 v[108:111], v233 offset:1024
	ds_read_b128 v[112:115], v233 offset:2048
	ds_read_b128 v[116:119], v233 offset:3072
	ds_read_b128 v[120:123], v234
	ds_read_b128 v[124:127], v234 offset:1024
	ds_read_b128 v[128:131], v234 offset:2048
	ds_read_b128 v[132:135], v234 offset:3072
	s_add_u32 s68, s24, 0xfffc0080
	s_addc_u32 s69, s25, -1
	s_cmp_eq_u32 s74, 12
	s_cselect_b32 s71, s63, s69
	s_cselect_b32 s70, s62, s68
	s_cselect_b32 s69, s61, s73
	s_cselect_b32 s68, s67, s72
	v_lshl_add_u64 v[208:209], s[24:25], 0, v[186:187]
	s_add_i32 m0, s92, 0xc000
	ds_read_b128 v[160:163], v235
	ds_read_b128 v[164:167], v235 offset:1024
	ds_read_b128 v[168:171], v235 offset:2048
	ds_read_b128 v[172:175], v235 offset:3072
	ds_read_b128 v[192:195], v235 offset:4096
	ds_read_b128 v[196:199], v235 offset:5120
	ds_read_b128 v[200:203], v235 offset:6144
	ds_read_b128 v[204:207], v235 offset:7168
	global_load_lds_dwordx4 v[208:209], off
	v_lshl_add_u64 v[208:209], s[24:25], 0, v[184:185]
	s_add_i32 m0, s92, 0xe000
	s_nop 0
	global_load_lds_dwordx4 v[208:209], off
	s_waitcnt vmcnt(8)
	s_waitcnt lgkmcnt(0)
	s_barrier
	s_setprio 1
	s_waitcnt lgkmcnt(0)
	v_mfma_f32_16x16x32_bf16 v[156:159], v[104:107], v[160:163], v[156:159]
	v_mfma_f32_16x16x32_bf16 v[60:63], v[112:115], v[160:163], v[60:63]
	v_mfma_f32_16x16x32_bf16 v[148:151], v[104:107], v[168:171], v[148:151]
	v_mfma_f32_16x16x32_bf16 v[52:55], v[112:115], v[168:171], v[52:55]
	v_mfma_f32_16x16x32_bf16 v[140:143], v[104:107], v[192:195], v[140:143]
	v_mfma_f32_16x16x32_bf16 v[44:47], v[112:115], v[192:195], v[44:47]
	v_mfma_f32_16x16x32_bf16 v[100:103], v[104:107], v[200:203], v[100:103]
	v_mfma_f32_16x16x32_bf16 v[36:39], v[112:115], v[200:203], v[36:39]
	v_mfma_f32_16x16x32_bf16 v[156:159], v[108:111], v[164:167], v[156:159]
	v_mfma_f32_16x16x32_bf16 v[60:63], v[116:119], v[164:167], v[60:63]
	v_mfma_f32_16x16x32_bf16 v[148:151], v[108:111], v[172:175], v[148:151]
	v_mfma_f32_16x16x32_bf16 v[52:55], v[116:119], v[172:175], v[52:55]
	v_mfma_f32_16x16x32_bf16 v[140:143], v[108:111], v[196:199], v[140:143]
	v_mfma_f32_16x16x32_bf16 v[44:47], v[116:119], v[196:199], v[44:47]
	v_mfma_f32_16x16x32_bf16 v[100:103], v[108:111], v[204:207], v[100:103]
	v_mfma_f32_16x16x32_bf16 v[36:39], v[116:119], v[204:207], v[36:39]
	v_mfma_f32_16x16x32_bf16 v[152:155], v[120:123], v[160:163], v[152:155]
	v_mfma_f32_16x16x32_bf16 v[56:59], v[128:131], v[160:163], v[56:59]
	v_mfma_f32_16x16x32_bf16 v[144:147], v[120:123], v[168:171], v[144:147]
	v_mfma_f32_16x16x32_bf16 v[48:51], v[128:131], v[168:171], v[48:51]
	v_mfma_f32_16x16x32_bf16 v[136:139], v[120:123], v[192:195], v[136:139]
	v_mfma_f32_16x16x32_bf16 v[40:43], v[128:131], v[192:195], v[40:43]
	v_mfma_f32_16x16x32_bf16 v[96:99], v[120:123], v[200:203], v[96:99]
	v_mfma_f32_16x16x32_bf16 v[32:35], v[128:131], v[200:203], v[32:35]
	v_mfma_f32_16x16x32_bf16 v[152:155], v[124:127], v[164:167], v[152:155]
	v_mfma_f32_16x16x32_bf16 v[56:59], v[132:135], v[164:167], v[56:59]
	v_mfma_f32_16x16x32_bf16 v[144:147], v[124:127], v[172:175], v[144:147]
	v_mfma_f32_16x16x32_bf16 v[48:51], v[132:135], v[172:175], v[48:51]
	v_mfma_f32_16x16x32_bf16 v[136:139], v[124:127], v[196:199], v[136:139]
	v_mfma_f32_16x16x32_bf16 v[40:43], v[132:135], v[196:199], v[40:43]
	v_mfma_f32_16x16x32_bf16 v[96:99], v[124:127], v[204:207], v[96:99]
	v_mfma_f32_16x16x32_bf16 v[32:35], v[132:135], v[204:207], v[32:35]
	s_setprio 0
	s_barrier
	s_add_i32 s75, s33, s91
	v_lshl_add_u64 v[208:209], s[68:69], 0, v[178:179]
	s_mov_b32 m0, s75
	ds_read_b128 v[160:163], v235 offset:16384
	ds_read_b128 v[164:167], v235 offset:17408
	ds_read_b128 v[168:171], v235 offset:18432
	ds_read_b128 v[172:175], v235 offset:19456
	ds_read_b128 v[192:195], v235 offset:20480
	ds_read_b128 v[196:199], v235 offset:21504
	ds_read_b128 v[200:203], v235 offset:22528
	ds_read_b128 v[204:207], v235 offset:23552
	global_load_lds_dwordx4 v[208:209], off
	s_add_i32 m0, s75, 0x2000
	s_add_u32 s76, s68, 0x40000
	v_lshl_add_u64 v[210:211], s[68:69], 0, v[182:183]
	s_addc_u32 s77, s69, 0
	s_add_i32 s75, s0, s91
	global_load_lds_dwordx4 v[210:211], off
	v_lshl_add_u64 v[212:213], s[76:77], 0, v[178:179]
	s_mov_b32 m0, s75
	v_lshl_add_u64 v[214:215], s[70:71], 0, v[180:181]
	global_load_lds_dwordx4 v[212:213], off
	v_lshl_add_u64 v[212:213], s[76:77], 0, v[182:183]
	s_add_i32 m0, s75, 0x2000
	s_nop 0
	global_load_lds_dwordx4 v[212:213], off
	v_lshl_add_u64 v[212:213], s[70:71], 0, v[176:177]
	s_mov_b32 m0, s92
	s_nop 0
	global_load_lds_dwordx4 v[212:213], off
	s_mov_b32 m0, s93
	s_nop 0
	global_load_lds_dwordx4 v[214:215], off
	s_waitcnt vmcnt(8)
	s_waitcnt lgkmcnt(0)
	s_barrier
	s_setprio 1
	s_waitcnt lgkmcnt(0)
	v_mfma_f32_16x16x32_bf16 v[92:95], v[104:107], v[160:163], v[92:95]
	v_mfma_f32_16x16x32_bf16 v[28:31], v[112:115], v[160:163], v[28:31]
	v_mfma_f32_16x16x32_bf16 v[84:87], v[104:107], v[168:171], v[84:87]
	v_mfma_f32_16x16x32_bf16 v[20:23], v[112:115], v[168:171], v[20:23]
	v_mfma_f32_16x16x32_bf16 v[76:79], v[104:107], v[192:195], v[76:79]
	v_mfma_f32_16x16x32_bf16 v[12:15], v[112:115], v[192:195], v[12:15]
	v_mfma_f32_16x16x32_bf16 v[68:71], v[104:107], v[200:203], v[68:71]
	v_mfma_f32_16x16x32_bf16 v[4:7], v[112:115], v[200:203], v[4:7]
	v_mfma_f32_16x16x32_bf16 v[92:95], v[108:111], v[164:167], v[92:95]
	v_mfma_f32_16x16x32_bf16 v[28:31], v[116:119], v[164:167], v[28:31]
	v_mfma_f32_16x16x32_bf16 v[84:87], v[108:111], v[172:175], v[84:87]
	v_mfma_f32_16x16x32_bf16 v[20:23], v[116:119], v[172:175], v[20:23]
	v_mfma_f32_16x16x32_bf16 v[76:79], v[108:111], v[196:199], v[76:79]
	v_mfma_f32_16x16x32_bf16 v[12:15], v[116:119], v[196:199], v[12:15]
	v_mfma_f32_16x16x32_bf16 v[68:71], v[108:111], v[204:207], v[68:71]
	v_mfma_f32_16x16x32_bf16 v[4:7], v[116:119], v[204:207], v[4:7]
	v_mfma_f32_16x16x32_bf16 v[88:91], v[120:123], v[160:163], v[88:91]
	v_mfma_f32_16x16x32_bf16 v[24:27], v[128:131], v[160:163], v[24:27]
	v_mfma_f32_16x16x32_bf16 v[80:83], v[120:123], v[168:171], v[80:83]
	v_mfma_f32_16x16x32_bf16 v[16:19], v[128:131], v[168:171], v[16:19]
	v_mfma_f32_16x16x32_bf16 v[72:75], v[120:123], v[192:195], v[72:75]
	v_mfma_f32_16x16x32_bf16 v[8:11], v[128:131], v[192:195], v[8:11]
	v_mfma_f32_16x16x32_bf16 v[64:67], v[120:123], v[200:203], v[64:67]
	v_mfma_f32_16x16x32_bf16 v[0:3], v[128:131], v[200:203], v[0:3]
	v_mfma_f32_16x16x32_bf16 v[88:91], v[124:127], v[164:167], v[88:91]
	v_mfma_f32_16x16x32_bf16 v[24:27], v[132:135], v[164:167], v[24:27]
	v_mfma_f32_16x16x32_bf16 v[80:83], v[124:127], v[172:175], v[80:83]
	v_mfma_f32_16x16x32_bf16 v[16:19], v[132:135], v[172:175], v[16:19]
	v_mfma_f32_16x16x32_bf16 v[72:75], v[124:127], v[196:199], v[72:75]
	v_mfma_f32_16x16x32_bf16 v[8:11], v[132:135], v[196:199], v[8:11]
	v_mfma_f32_16x16x32_bf16 v[64:67], v[124:127], v[204:207], v[64:67]
	v_mfma_f32_16x16x32_bf16 v[0:3], v[132:135], v[204:207], v[0:3]
	s_setprio 0
	s_barrier
	s_add_i32 s75, 0, 0x18000
	s_add_i32 s76, 0, 0x1c000
	v_add_u32_e32 v116, s75, v221
	v_add_u32_e32 v132, s76, v221
	ds_read_b128 v[104:107], v116
	ds_read_b128 v[108:111], v116 offset:1024
	ds_read_b128 v[112:115], v116 offset:2048
	ds_read_b128 v[116:119], v116 offset:3072
	ds_read_b128 v[120:123], v132
	ds_read_b128 v[124:127], v132 offset:1024
	ds_read_b128 v[128:131], v132 offset:2048
	ds_read_b128 v[132:135], v132 offset:3072
	s_add_u32 s70, s70, 0x40000
	s_addc_u32 s71, s71, 0
	s_mov_b32 m0, s94
	v_lshl_add_u64 v[216:217], s[70:71], 0, v[176:177]
	ds_read_b128 v[160:163], v235 offset:32768
	ds_read_b128 v[164:167], v235 offset:33792
	ds_read_b128 v[168:171], v235 offset:34816
	ds_read_b128 v[172:175], v235 offset:35840
	ds_read_b128 v[192:195], v235 offset:36864
	ds_read_b128 v[196:199], v235 offset:37888
	ds_read_b128 v[200:203], v235 offset:38912
	ds_read_b128 v[204:207], v235 offset:39936
	global_load_lds_dwordx4 v[216:217], off
	v_lshl_add_u64 v[216:217], s[70:71], 0, v[180:181]
	s_mov_b32 m0, s95
	s_nop 0
	global_load_lds_dwordx4 v[216:217], off
	s_waitcnt vmcnt(8)
	s_waitcnt lgkmcnt(0)
	s_barrier
	s_setprio 1
	s_waitcnt lgkmcnt(0)
	v_mfma_f32_16x16x32_bf16 v[156:159], v[104:107], v[160:163], v[156:159]
	v_mfma_f32_16x16x32_bf16 v[60:63], v[112:115], v[160:163], v[60:63]
	v_mfma_f32_16x16x32_bf16 v[148:151], v[104:107], v[168:171], v[148:151]
	v_mfma_f32_16x16x32_bf16 v[52:55], v[112:115], v[168:171], v[52:55]
	v_mfma_f32_16x16x32_bf16 v[140:143], v[104:107], v[192:195], v[140:143]
	v_mfma_f32_16x16x32_bf16 v[44:47], v[112:115], v[192:195], v[44:47]
	v_mfma_f32_16x16x32_bf16 v[100:103], v[104:107], v[200:203], v[100:103]
	v_mfma_f32_16x16x32_bf16 v[36:39], v[112:115], v[200:203], v[36:39]
	v_mfma_f32_16x16x32_bf16 v[156:159], v[108:111], v[164:167], v[156:159]
	v_mfma_f32_16x16x32_bf16 v[60:63], v[116:119], v[164:167], v[60:63]
	v_mfma_f32_16x16x32_bf16 v[148:151], v[108:111], v[172:175], v[148:151]
	v_mfma_f32_16x16x32_bf16 v[52:55], v[116:119], v[172:175], v[52:55]
	v_mfma_f32_16x16x32_bf16 v[140:143], v[108:111], v[196:199], v[140:143]
	v_mfma_f32_16x16x32_bf16 v[44:47], v[116:119], v[196:199], v[44:47]
	v_mfma_f32_16x16x32_bf16 v[100:103], v[108:111], v[204:207], v[100:103]
	v_mfma_f32_16x16x32_bf16 v[36:39], v[116:119], v[204:207], v[36:39]
	v_mfma_f32_16x16x32_bf16 v[152:155], v[120:123], v[160:163], v[152:155]
	v_mfma_f32_16x16x32_bf16 v[56:59], v[128:131], v[160:163], v[56:59]
	v_mfma_f32_16x16x32_bf16 v[144:147], v[120:123], v[168:171], v[144:147]
	v_mfma_f32_16x16x32_bf16 v[48:51], v[128:131], v[168:171], v[48:51]
	v_mfma_f32_16x16x32_bf16 v[136:139], v[120:123], v[192:195], v[136:139]
	v_mfma_f32_16x16x32_bf16 v[40:43], v[128:131], v[192:195], v[40:43]
	v_mfma_f32_16x16x32_bf16 v[96:99], v[120:123], v[200:203], v[96:99]
	v_mfma_f32_16x16x32_bf16 v[32:35], v[128:131], v[200:203], v[32:35]
	v_mfma_f32_16x16x32_bf16 v[152:155], v[124:127], v[164:167], v[152:155]
	v_mfma_f32_16x16x32_bf16 v[56:59], v[132:135], v[164:167], v[56:59]
	v_mfma_f32_16x16x32_bf16 v[144:147], v[124:127], v[172:175], v[144:147]
	v_mfma_f32_16x16x32_bf16 v[48:51], v[132:135], v[172:175], v[48:51]
	v_mfma_f32_16x16x32_bf16 v[136:139], v[124:127], v[196:199], v[136:139]
	v_mfma_f32_16x16x32_bf16 v[40:43], v[132:135], v[196:199], v[40:43]
	v_mfma_f32_16x16x32_bf16 v[96:99], v[124:127], v[204:207], v[96:99]
	v_mfma_f32_16x16x32_bf16 v[32:35], v[132:135], v[204:207], v[32:35]
	s_setprio 0
	s_barrier
	s_add_i32 s70, s75, s91
	v_lshl_add_u64 v[208:209], v[208:209], 0, s[42:43]
	s_mov_b32 m0, s70
	ds_read_b128 v[160:163], v235 offset:49152
	ds_read_b128 v[164:167], v235 offset:50176
	ds_read_b128 v[168:171], v235 offset:51200
	ds_read_b128 v[172:175], v235 offset:52224
	ds_read_b128 v[192:195], v235 offset:53248
	ds_read_b128 v[196:199], v235 offset:54272
	ds_read_b128 v[200:203], v235 offset:55296
	ds_read_b128 v[204:207], v235 offset:56320
	global_load_lds_dwordx4 v[208:209], off
	s_add_i32 m0, s70, 0x2000
	s_add_u32 s68, s68, 0x40080
	v_lshl_add_u64 v[208:209], v[210:211], 0, s[42:43]
	s_addc_u32 s69, s69, 0
	s_add_i32 s70, s76, s91
	global_load_lds_dwordx4 v[208:209], off
	v_lshl_add_u64 v[208:209], s[68:69], 0, v[178:179]
	s_mov_b32 m0, s70
	s_nop 0
	global_load_lds_dwordx4 v[208:209], off
	v_lshl_add_u64 v[208:209], s[68:69], 0, v[182:183]
	s_add_i32 m0, s70, 0x2000
	s_nop 0
	global_load_lds_dwordx4 v[208:209], off
	v_lshl_add_u64 v[208:209], v[212:213], 0, s[42:43]
	s_mov_b32 m0, s5
	s_nop 0
	global_load_lds_dwordx4 v[208:209], off
	v_lshl_add_u64 v[208:209], v[214:215], 0, s[42:43]
	s_mov_b32 m0, s96
	s_nop 0
	global_load_lds_dwordx4 v[208:209], off
	s_waitcnt vmcnt(8)
	s_waitcnt lgkmcnt(0)
	s_barrier
	s_setprio 1
	s_waitcnt lgkmcnt(0)
	v_mfma_f32_16x16x32_bf16 v[92:95], v[104:107], v[160:163], v[92:95]
	v_mfma_f32_16x16x32_bf16 v[28:31], v[112:115], v[160:163], v[28:31]
	v_mfma_f32_16x16x32_bf16 v[84:87], v[104:107], v[168:171], v[84:87]
	v_mfma_f32_16x16x32_bf16 v[20:23], v[112:115], v[168:171], v[20:23]
	v_mfma_f32_16x16x32_bf16 v[76:79], v[104:107], v[192:195], v[76:79]
	v_mfma_f32_16x16x32_bf16 v[12:15], v[112:115], v[192:195], v[12:15]
	v_mfma_f32_16x16x32_bf16 v[68:71], v[104:107], v[200:203], v[68:71]
	v_mfma_f32_16x16x32_bf16 v[4:7], v[112:115], v[200:203], v[4:7]
	v_mfma_f32_16x16x32_bf16 v[92:95], v[108:111], v[164:167], v[92:95]
	v_mfma_f32_16x16x32_bf16 v[28:31], v[116:119], v[164:167], v[28:31]
	v_mfma_f32_16x16x32_bf16 v[84:87], v[108:111], v[172:175], v[84:87]
	v_mfma_f32_16x16x32_bf16 v[20:23], v[116:119], v[172:175], v[20:23]
	v_mfma_f32_16x16x32_bf16 v[76:79], v[108:111], v[196:199], v[76:79]
	v_mfma_f32_16x16x32_bf16 v[12:15], v[116:119], v[196:199], v[12:15]
	v_mfma_f32_16x16x32_bf16 v[68:71], v[108:111], v[204:207], v[68:71]
	v_mfma_f32_16x16x32_bf16 v[4:7], v[116:119], v[204:207], v[4:7]
	v_mfma_f32_16x16x32_bf16 v[88:91], v[120:123], v[160:163], v[88:91]
	v_mfma_f32_16x16x32_bf16 v[24:27], v[128:131], v[160:163], v[24:27]
	v_mfma_f32_16x16x32_bf16 v[80:83], v[120:123], v[168:171], v[80:83]
	v_mfma_f32_16x16x32_bf16 v[16:19], v[128:131], v[168:171], v[16:19]
	v_mfma_f32_16x16x32_bf16 v[72:75], v[120:123], v[192:195], v[72:75]
	v_mfma_f32_16x16x32_bf16 v[8:11], v[128:131], v[192:195], v[8:11]
	v_mfma_f32_16x16x32_bf16 v[64:67], v[120:123], v[200:203], v[64:67]
	v_mfma_f32_16x16x32_bf16 v[0:3], v[128:131], v[200:203], v[0:3]
	v_mfma_f32_16x16x32_bf16 v[88:91], v[124:127], v[164:167], v[88:91]
	v_mfma_f32_16x16x32_bf16 v[24:27], v[132:135], v[164:167], v[24:27]
	v_mfma_f32_16x16x32_bf16 v[80:83], v[124:127], v[172:175], v[80:83]
	v_mfma_f32_16x16x32_bf16 v[16:19], v[132:135], v[172:175], v[16:19]
	v_mfma_f32_16x16x32_bf16 v[72:75], v[124:127], v[196:199], v[72:75]
	v_mfma_f32_16x16x32_bf16 v[8:11], v[132:135], v[196:199], v[8:11]
	v_mfma_f32_16x16x32_bf16 v[64:67], v[124:127], v[204:207], v[64:67]
	v_mfma_f32_16x16x32_bf16 v[0:3], v[132:135], v[204:207], v[0:3]
	s_setprio 0
	s_barrier
	s_add_i32 s74, s74, 2
	s_add_u32 s72, s72, 0x100
	s_addc_u32 s73, s73, 0
	s_add_u32 s24, s24, 0x100
	s_addc_u32 s25, s25, 0
	s_cmp_gt_u32 s74, 13
	s_cbranch_scc0 .LBB0_4039
	s_and_b64 vcc, exec, s[44:45]
	s_cbranch_vccz .LBB0_4042
	s_barrier

.LBB0_4157:
	ds_read_b128 v[144:147], v157
	ds_read_b128 v[148:151], v157 offset:1024
	ds_read_b128 v[160:163], v157 offset:2048
	ds_read_b128 v[164:167], v157 offset:3072
	ds_read_b128 v[168:171], v158
	ds_read_b128 v[172:175], v158 offset:1024
	ds_read_b128 v[176:179], v158 offset:2048
	ds_read_b128 v[180:183], v158 offset:3072
	s_add_u32 s20, s18, 0x100
	s_addc_u32 s21, s19, 0
	s_cmp_eq_u32 s52, 40
	s_cselect_b32 s25, s7, s21
	s_cselect_b32 s24, s6, s20
	s_cselect_b32 s23, s17, s51
	s_cselect_b32 s22, s16, s50
	v_lshl_add_u64 v[152:153], s[18:19], 0, v[138:139]
	s_add_i32 m0, s29, 0xc000
	ds_read_b128 v[184:187], v159
	ds_read_b128 v[188:191], v159 offset:1024
	ds_read_b128 v[192:195], v159 offset:2048
	ds_read_b128 v[196:199], v159 offset:3072
	ds_read_b128 v[200:203], v159 offset:4096
	ds_read_b128 v[204:207], v159 offset:5120
	ds_read_b128 v[208:211], v159 offset:6144
	ds_read_b128 v[212:215], v159 offset:7168
	global_load_lds_dwordx4 v[152:153], off
	v_lshl_add_u64 v[152:153], s[18:19], 0, v[136:137]
	s_add_i32 m0, s29, 0xe000
	s_nop 0
	global_load_lds_dwordx4 v[152:153], off
	s_waitcnt vmcnt(8)
	s_waitcnt lgkmcnt(0)
	s_barrier
	s_setprio 1
	s_waitcnt lgkmcnt(0)
	v_mfma_f32_16x16x32_bf16 v[124:127], v[144:147], v[184:187], v[124:127]
	v_mfma_f32_16x16x32_bf16 v[120:123], v[160:163], v[184:187], v[120:123]
	v_mfma_f32_16x16x32_bf16 v[116:119], v[144:147], v[192:195], v[116:119]
	v_mfma_f32_16x16x32_bf16 v[112:115], v[160:163], v[192:195], v[112:115]
	v_mfma_f32_16x16x32_bf16 v[108:111], v[144:147], v[200:203], v[108:111]
	v_mfma_f32_16x16x32_bf16 v[104:107], v[160:163], v[200:203], v[104:107]
	v_mfma_f32_16x16x32_bf16 v[100:103], v[144:147], v[208:211], v[100:103]
	v_mfma_f32_16x16x32_bf16 v[96:99], v[160:163], v[208:211], v[96:99]
	v_mfma_f32_16x16x32_bf16 v[124:127], v[148:151], v[188:191], v[124:127]
	v_mfma_f32_16x16x32_bf16 v[120:123], v[164:167], v[188:191], v[120:123]
	v_mfma_f32_16x16x32_bf16 v[116:119], v[148:151], v[196:199], v[116:119]
	v_mfma_f32_16x16x32_bf16 v[112:115], v[164:167], v[196:199], v[112:115]
	v_mfma_f32_16x16x32_bf16 v[108:111], v[148:151], v[204:207], v[108:111]
	v_mfma_f32_16x16x32_bf16 v[104:107], v[164:167], v[204:207], v[104:107]
	v_mfma_f32_16x16x32_bf16 v[100:103], v[148:151], v[212:215], v[100:103]
	v_mfma_f32_16x16x32_bf16 v[96:99], v[164:167], v[212:215], v[96:99]
	v_mfma_f32_16x16x32_bf16 v[76:79], v[168:171], v[184:187], v[76:79]
	v_mfma_f32_16x16x32_bf16 v[72:75], v[176:179], v[184:187], v[72:75]
	v_mfma_f32_16x16x32_bf16 v[60:63], v[168:171], v[192:195], v[60:63]
	v_mfma_f32_16x16x32_bf16 v[52:55], v[176:179], v[192:195], v[52:55]
	v_mfma_f32_16x16x32_bf16 v[44:47], v[168:171], v[200:203], v[44:47]
	v_mfma_f32_16x16x32_bf16 v[40:43], v[176:179], v[200:203], v[40:43]
	v_mfma_f32_16x16x32_bf16 v[36:39], v[168:171], v[208:211], v[36:39]
	v_mfma_f32_16x16x32_bf16 v[32:35], v[176:179], v[208:211], v[32:35]
	v_mfma_f32_16x16x32_bf16 v[76:79], v[172:175], v[188:191], v[76:79]
	v_mfma_f32_16x16x32_bf16 v[72:75], v[180:183], v[188:191], v[72:75]
	v_mfma_f32_16x16x32_bf16 v[60:63], v[172:175], v[196:199], v[60:63]
	v_mfma_f32_16x16x32_bf16 v[52:55], v[180:183], v[196:199], v[52:55]
	v_mfma_f32_16x16x32_bf16 v[44:47], v[172:175], v[204:207], v[44:47]
	v_mfma_f32_16x16x32_bf16 v[40:43], v[180:183], v[204:207], v[40:43]
	v_mfma_f32_16x16x32_bf16 v[36:39], v[172:175], v[212:215], v[36:39]
	v_mfma_f32_16x16x32_bf16 v[32:35], v[180:183], v[212:215], v[32:35]
	s_setprio 0
	s_barrier
	s_add_i32 s18, s41, s28
	v_lshl_add_u64 v[152:153], s[22:23], 0, v[130:131]
	s_mov_b32 m0, s18
	ds_read_b128 v[184:187], v159 offset:16384
	ds_read_b128 v[188:191], v159 offset:17408
	ds_read_b128 v[192:195], v159 offset:18432
	ds_read_b128 v[196:199], v159 offset:19456
	ds_read_b128 v[200:203], v159 offset:20480
	ds_read_b128 v[204:207], v159 offset:21504
	ds_read_b128 v[208:211], v159 offset:22528
	ds_read_b128 v[212:215], v159 offset:23552
	global_load_lds_dwordx4 v[152:153], off
	s_add_i32 m0, s18, 0x2000
	s_add_u32 s18, s22, 0xb0000
	v_lshl_add_u64 v[216:217], s[22:23], 0, v[134:135]
	s_addc_u32 s19, s23, 0
	s_add_i32 s53, s42, s28
	global_load_lds_dwordx4 v[216:217], off
	v_lshl_add_u64 v[218:219], s[18:19], 0, v[130:131]
	s_mov_b32 m0, s53
	v_lshl_add_u64 v[220:221], s[24:25], 0, v[132:133]
	global_load_lds_dwordx4 v[218:219], off
	v_lshl_add_u64 v[218:219], s[18:19], 0, v[134:135]
	s_add_i32 m0, s53, 0x2000
	s_nop 0
	global_load_lds_dwordx4 v[218:219], off
	v_lshl_add_u64 v[218:219], s[24:25], 0, v[128:129]
	s_mov_b32 m0, s29
	s_nop 0
	global_load_lds_dwordx4 v[218:219], off
	s_mov_b32 m0, s30
	s_nop 0
	global_load_lds_dwordx4 v[220:221], off
	s_waitcnt vmcnt(8)
	s_waitcnt lgkmcnt(0)
	s_barrier
	s_setprio 1
	s_waitcnt lgkmcnt(0)
	v_mfma_f32_16x16x32_bf16 v[92:95], v[144:147], v[184:187], v[92:95]
	v_mfma_f32_16x16x32_bf16 v[88:91], v[160:163], v[184:187], v[88:91]
	v_mfma_f32_16x16x32_bf16 v[84:87], v[144:147], v[192:195], v[84:87]
	v_mfma_f32_16x16x32_bf16 v[80:83], v[160:163], v[192:195], v[80:83]
	v_mfma_f32_16x16x32_bf16 v[68:71], v[144:147], v[200:203], v[68:71]
	v_mfma_f32_16x16x32_bf16 v[64:67], v[160:163], v[200:203], v[64:67]
	v_mfma_f32_16x16x32_bf16 v[56:59], v[144:147], v[208:211], v[56:59]
	v_mfma_f32_16x16x32_bf16 v[48:51], v[160:163], v[208:211], v[48:51]
	v_mfma_f32_16x16x32_bf16 v[92:95], v[148:151], v[188:191], v[92:95]
	v_mfma_f32_16x16x32_bf16 v[88:91], v[164:167], v[188:191], v[88:91]
	v_mfma_f32_16x16x32_bf16 v[84:87], v[148:151], v[196:199], v[84:87]
	v_mfma_f32_16x16x32_bf16 v[80:83], v[164:167], v[196:199], v[80:83]
	v_mfma_f32_16x16x32_bf16 v[68:71], v[148:151], v[204:207], v[68:71]
	v_mfma_f32_16x16x32_bf16 v[64:67], v[164:167], v[204:207], v[64:67]
	v_mfma_f32_16x16x32_bf16 v[56:59], v[148:151], v[212:215], v[56:59]
	v_mfma_f32_16x16x32_bf16 v[48:51], v[164:167], v[212:215], v[48:51]
	v_mfma_f32_16x16x32_bf16 v[28:31], v[168:171], v[184:187], v[28:31]
	v_mfma_f32_16x16x32_bf16 v[24:27], v[176:179], v[184:187], v[24:27]
	v_mfma_f32_16x16x32_bf16 v[20:23], v[168:171], v[192:195], v[20:23]
	v_mfma_f32_16x16x32_bf16 v[16:19], v[176:179], v[192:195], v[16:19]
	v_mfma_f32_16x16x32_bf16 v[12:15], v[168:171], v[200:203], v[12:15]
	v_mfma_f32_16x16x32_bf16 v[8:11], v[176:179], v[200:203], v[8:11]
	v_mfma_f32_16x16x32_bf16 v[4:7], v[168:171], v[208:211], v[4:7]
	v_mfma_f32_16x16x32_bf16 v[0:3], v[176:179], v[208:211], v[0:3]
	v_mfma_f32_16x16x32_bf16 v[28:31], v[172:175], v[188:191], v[28:31]
	v_mfma_f32_16x16x32_bf16 v[24:27], v[180:183], v[188:191], v[24:27]
	v_mfma_f32_16x16x32_bf16 v[20:23], v[172:175], v[196:199], v[20:23]
	v_mfma_f32_16x16x32_bf16 v[16:19], v[180:183], v[196:199], v[16:19]
	v_mfma_f32_16x16x32_bf16 v[12:15], v[172:175], v[204:207], v[12:15]
	v_mfma_f32_16x16x32_bf16 v[8:11], v[180:183], v[204:207], v[8:11]
	v_mfma_f32_16x16x32_bf16 v[4:7], v[172:175], v[212:215], v[4:7]
	v_mfma_f32_16x16x32_bf16 v[0:3], v[180:183], v[212:215], v[0:3]
	s_setprio 0
	s_barrier
	s_add_i32 s53, 0, 0x18000
	s_add_i32 s54, 0, 0x1c000
	v_add_u32_e32 v164, s53, v155
	v_add_u32_e32 v180, s54, v155
	ds_read_b128 v[144:147], v164
	ds_read_b128 v[148:151], v164 offset:1024
	ds_read_b128 v[160:163], v164 offset:2048
	ds_read_b128 v[164:167], v164 offset:3072
	ds_read_b128 v[168:171], v180
	ds_read_b128 v[172:175], v180 offset:1024
	ds_read_b128 v[176:179], v180 offset:2048
	ds_read_b128 v[180:183], v180 offset:3072
	s_add_u32 s18, s24, 0xb0000
	s_addc_u32 s19, s25, 0
	s_mov_b32 m0, s31
	v_lshl_add_u64 v[222:223], s[18:19], 0, v[128:129]
	ds_read_b128 v[184:187], v159 offset:32768
	ds_read_b128 v[188:191], v159 offset:33792
	ds_read_b128 v[192:195], v159 offset:34816
	ds_read_b128 v[196:199], v159 offset:35840
	ds_read_b128 v[200:203], v159 offset:36864
	ds_read_b128 v[204:207], v159 offset:37888
	ds_read_b128 v[208:211], v159 offset:38912
	ds_read_b128 v[212:215], v159 offset:39936
	global_load_lds_dwordx4 v[222:223], off
	v_lshl_add_u64 v[222:223], s[18:19], 0, v[132:133]
	s_mov_b32 m0, s33
	s_nop 0
	global_load_lds_dwordx4 v[222:223], off
	s_waitcnt vmcnt(8)
	s_waitcnt lgkmcnt(0)
	s_barrier
	s_setprio 1
	s_waitcnt lgkmcnt(0)
	v_mfma_f32_16x16x32_bf16 v[124:127], v[144:147], v[184:187], v[124:127]
	v_mfma_f32_16x16x32_bf16 v[120:123], v[160:163], v[184:187], v[120:123]
	v_mfma_f32_16x16x32_bf16 v[116:119], v[144:147], v[192:195], v[116:119]
	v_mfma_f32_16x16x32_bf16 v[112:115], v[160:163], v[192:195], v[112:115]
	v_mfma_f32_16x16x32_bf16 v[108:111], v[144:147], v[200:203], v[108:111]
	v_mfma_f32_16x16x32_bf16 v[104:107], v[160:163], v[200:203], v[104:107]
	v_mfma_f32_16x16x32_bf16 v[100:103], v[144:147], v[208:211], v[100:103]
	v_mfma_f32_16x16x32_bf16 v[96:99], v[160:163], v[208:211], v[96:99]
	v_mfma_f32_16x16x32_bf16 v[124:127], v[148:151], v[188:191], v[124:127]
	v_mfma_f32_16x16x32_bf16 v[120:123], v[164:167], v[188:191], v[120:123]
	v_mfma_f32_16x16x32_bf16 v[116:119], v[148:151], v[196:199], v[116:119]
	v_mfma_f32_16x16x32_bf16 v[112:115], v[164:167], v[196:199], v[112:115]
	v_mfma_f32_16x16x32_bf16 v[108:111], v[148:151], v[204:207], v[108:111]
	v_mfma_f32_16x16x32_bf16 v[104:107], v[164:167], v[204:207], v[104:107]
	v_mfma_f32_16x16x32_bf16 v[100:103], v[148:151], v[212:215], v[100:103]
	v_mfma_f32_16x16x32_bf16 v[96:99], v[164:167], v[212:215], v[96:99]
	v_mfma_f32_16x16x32_bf16 v[76:79], v[168:171], v[184:187], v[76:79]
	v_mfma_f32_16x16x32_bf16 v[72:75], v[176:179], v[184:187], v[72:75]
	v_mfma_f32_16x16x32_bf16 v[60:63], v[168:171], v[192:195], v[60:63]
	v_mfma_f32_16x16x32_bf16 v[52:55], v[176:179], v[192:195], v[52:55]
	v_mfma_f32_16x16x32_bf16 v[44:47], v[168:171], v[200:203], v[44:47]
	v_mfma_f32_16x16x32_bf16 v[40:43], v[176:179], v[200:203], v[40:43]
	v_mfma_f32_16x16x32_bf16 v[36:39], v[168:171], v[208:211], v[36:39]
	v_mfma_f32_16x16x32_bf16 v[32:35], v[176:179], v[208:211], v[32:35]
	v_mfma_f32_16x16x32_bf16 v[76:79], v[172:175], v[188:191], v[76:79]
	v_mfma_f32_16x16x32_bf16 v[72:75], v[180:183], v[188:191], v[72:75]
	v_mfma_f32_16x16x32_bf16 v[60:63], v[172:175], v[196:199], v[60:63]
	v_mfma_f32_16x16x32_bf16 v[52:55], v[180:183], v[196:199], v[52:55]
	v_mfma_f32_16x16x32_bf16 v[44:47], v[172:175], v[204:207], v[44:47]
	v_mfma_f32_16x16x32_bf16 v[40:43], v[180:183], v[204:207], v[40:43]
	v_mfma_f32_16x16x32_bf16 v[36:39], v[172:175], v[212:215], v[36:39]
	v_mfma_f32_16x16x32_bf16 v[32:35], v[180:183], v[212:215], v[32:35]
	s_setprio 0
	s_barrier
	s_add_i32 s18, s53, s28
	v_lshl_add_u64 v[152:153], v[152:153], 0, s[12:13]
	s_mov_b32 m0, s18
	ds_read_b128 v[184:187], v159 offset:49152
	ds_read_b128 v[188:191], v159 offset:50176
	ds_read_b128 v[192:195], v159 offset:51200
	ds_read_b128 v[196:199], v159 offset:52224
	ds_read_b128 v[200:203], v159 offset:53248
	ds_read_b128 v[204:207], v159 offset:54272
	ds_read_b128 v[208:211], v159 offset:55296
	ds_read_b128 v[212:215], v159 offset:56320
	global_load_lds_dwordx4 v[152:153], off
	s_add_i32 m0, s18, 0x2000
	s_add_u32 s18, s22, 0xb0080
	v_lshl_add_u64 v[152:153], v[216:217], 0, s[12:13]
	s_addc_u32 s19, s23, 0
	s_add_i32 s22, s54, s28
	global_load_lds_dwordx4 v[152:153], off
	v_lshl_add_u64 v[152:153], s[18:19], 0, v[130:131]
	s_mov_b32 m0, s22
	s_nop 0
	global_load_lds_dwordx4 v[152:153], off
	v_lshl_add_u64 v[152:153], s[18:19], 0, v[134:135]
	s_add_i32 m0, s22, 0x2000
	s_nop 0
	global_load_lds_dwordx4 v[152:153], off
	v_lshl_add_u64 v[152:153], v[218:219], 0, s[12:13]
	s_mov_b32 m0, s37
	s_nop 0
	global_load_lds_dwordx4 v[152:153], off
	v_lshl_add_u64 v[152:153], v[220:221], 0, s[12:13]
	s_mov_b32 m0, s38
	s_nop 0
	global_load_lds_dwordx4 v[152:153], off
	s_waitcnt vmcnt(8)
	s_waitcnt lgkmcnt(0)
	s_barrier
	s_setprio 1
	s_waitcnt lgkmcnt(0)
	v_mfma_f32_16x16x32_bf16 v[92:95], v[144:147], v[184:187], v[92:95]
	v_mfma_f32_16x16x32_bf16 v[88:91], v[160:163], v[184:187], v[88:91]
	v_mfma_f32_16x16x32_bf16 v[84:87], v[144:147], v[192:195], v[84:87]
	v_mfma_f32_16x16x32_bf16 v[80:83], v[160:163], v[192:195], v[80:83]
	v_mfma_f32_16x16x32_bf16 v[68:71], v[144:147], v[200:203], v[68:71]
	v_mfma_f32_16x16x32_bf16 v[64:67], v[160:163], v[200:203], v[64:67]
	v_mfma_f32_16x16x32_bf16 v[56:59], v[144:147], v[208:211], v[56:59]
	v_mfma_f32_16x16x32_bf16 v[48:51], v[160:163], v[208:211], v[48:51]
	v_mfma_f32_16x16x32_bf16 v[92:95], v[148:151], v[188:191], v[92:95]
	v_mfma_f32_16x16x32_bf16 v[88:91], v[164:167], v[188:191], v[88:91]
	v_mfma_f32_16x16x32_bf16 v[84:87], v[148:151], v[196:199], v[84:87]
	v_mfma_f32_16x16x32_bf16 v[80:83], v[164:167], v[196:199], v[80:83]
	v_mfma_f32_16x16x32_bf16 v[68:71], v[148:151], v[204:207], v[68:71]
	v_mfma_f32_16x16x32_bf16 v[64:67], v[164:167], v[204:207], v[64:67]
	v_mfma_f32_16x16x32_bf16 v[56:59], v[148:151], v[212:215], v[56:59]
	v_mfma_f32_16x16x32_bf16 v[48:51], v[164:167], v[212:215], v[48:51]
	v_mfma_f32_16x16x32_bf16 v[28:31], v[168:171], v[184:187], v[28:31]
	v_mfma_f32_16x16x32_bf16 v[24:27], v[176:179], v[184:187], v[24:27]
	v_mfma_f32_16x16x32_bf16 v[20:23], v[168:171], v[192:195], v[20:23]
	v_mfma_f32_16x16x32_bf16 v[16:19], v[176:179], v[192:195], v[16:19]
	v_mfma_f32_16x16x32_bf16 v[12:15], v[168:171], v[200:203], v[12:15]
	v_mfma_f32_16x16x32_bf16 v[8:11], v[176:179], v[200:203], v[8:11]
	v_mfma_f32_16x16x32_bf16 v[4:7], v[168:171], v[208:211], v[4:7]
	v_mfma_f32_16x16x32_bf16 v[0:3], v[176:179], v[208:211], v[0:3]
	v_mfma_f32_16x16x32_bf16 v[28:31], v[172:175], v[188:191], v[28:31]
	v_mfma_f32_16x16x32_bf16 v[24:27], v[180:183], v[188:191], v[24:27]
	v_mfma_f32_16x16x32_bf16 v[20:23], v[172:175], v[196:199], v[20:23]
	v_mfma_f32_16x16x32_bf16 v[16:19], v[180:183], v[196:199], v[16:19]
	v_mfma_f32_16x16x32_bf16 v[12:15], v[172:175], v[204:207], v[12:15]
	v_mfma_f32_16x16x32_bf16 v[8:11], v[180:183], v[204:207], v[8:11]
	v_mfma_f32_16x16x32_bf16 v[4:7], v[172:175], v[212:215], v[4:7]
	v_mfma_f32_16x16x32_bf16 v[0:3], v[180:183], v[212:215], v[0:3]
	s_setprio 0
	s_barrier
	s_add_i32 s52, s52, 2
	s_add_u32 s50, s50, 0x100
	s_addc_u32 s51, s51, 0
	s_cmp_gt_u32 s52, 41
	s_mov_b64 s[18:19], s[20:21]
	s_cbranch_scc0 .LBB0_4157
	s_and_b64 vcc, exec, s[14:15]
	s_cbranch_vccz .LBB0_4160
	s_barrier
